# re-measure: best (sample-rows/cmp2/P9-epilogue/P7 hoist/K-order/early decode units/nt decode loads)
# speedup vs baseline: 1.0123x; 1.0123x over previous
; #define LAS __attribute__((address_space(3)))
; __device__ __forceinline__ int fresh_lane() { int l; asm volatile("v_mbcnt_lo_u32_b32 %0, -1, 0\n\tv_mbcnt_hi_u32_b32 %0, -1, %0" : "=v"(l)); return l; }
; __device__ __forceinline__ void attn_decode_unit(const Params& P, const Ctx& C, int sg) {
;     ...
;     int lane_ = fresh_lane();
;     const int lane = lane_, wave = C.wave, r32 = lane & 31, hi = lane >> 5, r8 = r32 & 7;
;     const int seq = sg >> 2, g = sg & 3, qi = r8 & 3, hsel = r8 >> 2, hq = 2 * g + hsel;
;     const int t = PAST + qi;
;     const size_t row = (size_t)NPR + seq * 4 + qi;
;     bf16x8 qr[4];
;     { const bf16_t* qp = (const bf16_t*)(ws + WS_Q) + row * 512 + hq * 64 + hi * 8;
; #pragma unroll
;       for (int d0 = 0; d0 < 4; ++d0) qr[d0] = *(const bf16x8*)(qp + d0 * 16); }
;     LAS unsigned char* KB = C.lds + wave * 16384; LAS unsigned char* VB = KB + 8192;
;     LAS float* ML = (LAS float*)(C.lds + DC_ML); LAS float* DIMP = (LAS float*)(C.lds + DC_IMP); LAS unsigned* DSEL = (LAS unsigned*)(C.lds + DC_SEL);
;     LAS float* DOC = (LAS float*)(C.lds + DC_OC);
;     f32x16 s0, s1;
;     float m_w = -1e30f, l_w = 0.f; f32x16 ow0 = F16Z, ow1 = F16Z;
;     __syncthreads();
;     if (wave == 0) {
;         const bf16_t* kcb = (const bf16_t*)(ws + WS_KCC) + ((size_t)4096 + sg * 128) * 64; const bf16_t* vcb = (const bf16_t*)(ws + WS_VCC) + ((size_t)4096 + sg * 128) * 64;
;         const int cmax = (t - 31) >> 4;
;         f32x16 oc0 = F16Z, oc1 = F16Z; float carry = 0.f; float val0[8], val1[8];
;         u32x4 k0r[8], v0r[8], k1r[8], v1r[8];
;         wave_tile_issue(kcb, vcb, lane, k0r, v0r); wave_tile_issue(kcb + 4096, vcb + 4096, lane, k1r, v1r);
;         wave_tile_commit(k0r, v0r, KB, VB, lane); qk_tile(KB, qr, s0, s1, r32, hi); mask_tile(s0, s1, 0, 0, cmax, true, hi);
.Lmy_e8:
	s_andn2_b64 vcc, exec, s[48:49]
	s_cbranch_vccnz .LBB0_1394
	v_readlane_b32 s8, v254, 37
	v_readlane_b32 s10, v254, 39
	v_readlane_b32 s11, v254, 40
	v_readlane_b32 s14, v254, 43
	v_readlane_b32 s15, v254, 44
	v_readlane_b32 s2, v254, 13
	s_mov_b64 s[84:85], s[58:59]
	v_readlane_b32 s12, v254, 41
	v_readlane_b32 s13, v254, 42
	s_mov_b64 s[10:11], s[14:15]
	s_add_i32 s52, s4, s2
	s_load_dwordx2 s[2:3], s[90:91], 0x100
	s_and_b32 s53, s4, 3
	s_waitcnt lgkmcnt(0)
	v_mbcnt_lo_u32_b32 v165, -1, 0
	v_mbcnt_hi_u32_b32 v165, -1, v165
	s_lshl_b32 s4, s53, 1
	v_lshrrev_b32_e32 v0, 2, v165
	v_and_or_b32 v227, v0, 1, s4
	s_and_b32 s4, s52, -4
	s_ashr_i32 s5, s4, 31
	s_add_u32 s4, s4, 0x4000
	v_and_b32_e32 v167, 3, v165
	s_addc_u32 s5, s5, 0
	v_or_b32_e32 v162, s4, v167
	v_mov_b32_e32 v163, s5
	v_ashrrev_i32_e32 v166, 5, v165
	v_lshlrev_b64 v[2:3], 10, v[162:163]
	v_lshl_add_u64 v[2:3], s[84:85], 0, v[2:3]
	v_lshlrev_b32_e32 v0, 7, v227
	v_lshlrev_b32_e32 v4, 3, v166
	v_lshl_add_u64 v[2:3], v[2:3], 0, v[0:1]
	v_ashrrev_i32_e32 v5, 31, v4
	v_lshl_add_u64 v[2:3], v[4:5], 1, v[2:3]
	s_mov_b64 s[4:5], 0x6c00000
	v_lshl_add_u64 v[4:5], v[2:3], 0, s[4:5]
	v_add_co_u32_e32 v2, vcc, 0x6c00000, v2
	v_lshlrev_b32_e32 v229, 4, v165
	s_nop 0
	v_addc_co_u32_e32 v3, vcc, 0, v3, vcc
	global_load_dwordx4 v[66:69], v[4:5], off offset:32 nt
	global_load_dwordx4 v[70:73], v[4:5], off offset:64 nt
	global_load_dwordx4 v[74:77], v[2:3], off nt
	global_load_dwordx4 v[78:81], v[4:5], off offset:96 nt
	v_and_b32_e32 v228, 31, v165
	s_and_b64 vcc, exec, s[6:7]
	v_lshlrev_b32_e32 v168, 10, v166
	v_lshlrev_b32_e32 v164, 2, v166
	v_add_u32_e32 v230, s33, v229
	v_readlane_b32 s9, v254, 38
	s_barrier
	s_cbranch_vccnz .LBB0_1240
	s_lshl_b32 s4, s52, 7
	s_ashr_i32 s5, s4, 31
	s_lshl_b64 s[4:5], s[4:5], 7
	s_add_u32 s4, s84, s4
	v_lshlrev_b32_e32 v2, 7, v165
	v_lshlrev_b32_e32 v34, 5, v165
	s_addc_u32 s5, s85, s5
	v_ashrrev_i32_e32 v3, 31, v2
	v_and_b32_e32 v84, 0xffffff80, v34
	s_add_u32 s8, s4, 0x37780000
	v_lshl_add_u64 v[82:83], s[4:5], 0, v[2:3]
	s_mov_b64 s[14:15], 0x36e80000
	v_add_u32_e32 v88, 0x1000, v84
	v_add_u32_e32 v90, 0x1800, v84
	s_addc_u32 s9, s5, 0
	v_lshl_add_u64 v[30:31], v[82:83], 0, s[14:15]
	s_mov_b32 s14, 0x36e80000
	v_ashrrev_i32_e32 v85, 31, v84
	v_ashrrev_i32_e32 v89, 31, v88
	v_ashrrev_i32_e32 v91, 31, v90
	v_add_co_u32_e32 v2, vcc, s14, v82
	v_and_b32_e32 v0, 48, v229
	v_lshl_add_u64 v[34:35], s[8:9], 0, v[84:85]
	v_lshl_add_u64 v[42:43], s[8:9], 0, v[88:89]
	v_lshl_add_u64 v[46:47], s[8:9], 0, v[90:91]
	v_addc_co_u32_e32 v3, vcc, 0, v83, vcc
	v_lshl_add_u64 v[54:55], v[34:35], 0, v[0:1]
	v_lshl_add_u64 v[58:59], v[42:43], 0, v[0:1]
	v_lshl_add_u64 v[62:63], v[46:47], 0, v[0:1]
	global_load_dwordx4 v[6:9], v[2:3], off nt
	s_nop 0
	global_load_dwordx4 v[2:5], v[30:31], off offset:48 nt
	global_load_dwordx4 v[10:13], v[30:31], off offset:32 nt
	global_load_dwordx4 v[14:17], v[30:31], off offset:16 nt
	global_load_dwordx4 v[18:21], v[30:31], off offset:112 nt
	global_load_dwordx4 v[22:25], v[30:31], off offset:96 nt
	global_load_dwordx4 v[26:29], v[30:31], off offset:80 nt
	s_nop 0
	global_load_dwordx4 v[30:33], v[30:31], off offset:64 nt
	s_mov_b64 s[8:9], 0x36e82000
	global_load_dwordx4 v[34:37], v[54:55], off nt
	global_load_dwordx4 v[38:41], v[54:55], off offset:2048 nt
	global_load_dwordx4 v[42:45], v[58:59], off nt
	global_load_dwordx4 v[46:49], v[62:63], off nt
	global_load_dwordx4 v[50:53], v[54:55], off offset:64 nt
	s_nop 0
	global_load_dwordx4 v[54:57], v[54:55], off offset:2112 nt
	s_nop 0
	global_load_dwordx4 v[58:61], v[58:59], off offset:64 nt
	s_nop 0
	global_load_dwordx4 v[62:65], v[62:63], off offset:64 nt
	v_lshl_add_u64 v[92:93], v[82:83], 0, s[8:9]
	s_mov_b32 s8, 0x36e82000
	s_add_u32 s4, s4, 0x37782000
	v_add_co_u32_e32 v82, vcc, s8, v82
	v_add_u32_e32 v86, 0x800, v84
	s_addc_u32 s5, s5, 0
	v_addc_co_u32_e32 v83, vcc, 0, v83, vcc
	v_ashrrev_i32_e32 v87, 31, v86
	global_load_dwordx4 v[102:105], v[82:83], off nt
	global_load_dwordx4 v[98:101], v[92:93], off offset:48 nt
	global_load_dwordx4 v[106:109], v[92:93], off offset:32 nt
	global_load_dwordx4 v[110:113], v[92:93], off offset:16 nt
	global_load_dwordx4 v[114:117], v[92:93], off offset:112 nt
	global_load_dwordx4 v[118:121], v[92:93], off offset:96 nt
	global_load_dwordx4 v[122:125], v[92:93], off offset:80 nt
	global_load_dwordx4 v[126:129], v[92:93], off offset:64 nt
	v_lshl_add_u64 v[82:83], s[4:5], 0, v[84:85]
	v_lshl_add_u64 v[92:93], s[4:5], 0, v[0:1]
	v_lshl_add_u64 v[82:83], v[82:83], 0, v[0:1]
	v_lshl_add_u64 v[84:85], s[4:5], 0, v[86:87]
	v_lshl_add_u64 v[86:87], v[92:93], 0, v[86:87]
	global_load_dwordx4 v[130:133], v[82:83], off nt
	global_load_dwordx4 v[134:137], v[86:87], off nt
	v_lshl_add_u64 v[86:87], s[4:5], 0, v[88:89]
	v_lshl_add_u64 v[88:89], s[4:5], 0, v[90:91]
	v_lshl_add_u64 v[86:87], v[86:87], 0, v[0:1]
	v_lshl_add_u64 v[88:89], v[88:89], 0, v[0:1]
	global_load_dwordx4 v[138:141], v[86:87], off nt
	global_load_dwordx4 v[142:145], v[88:89], off nt
	global_load_dwordx4 v[146:149], v[82:83], off offset:64 nt
	v_lshl_add_u64 v[82:83], v[84:85], 0, v[0:1]
	global_load_dwordx4 v[150:153], v[82:83], off offset:64 nt
	global_load_dwordx4 v[154:157], v[86:87], off offset:64 nt
	global_load_dwordx4 v[158:161], v[88:89], off offset:64 nt
	s_waitcnt lgkmcnt(0)
	v_lshlrev_b32_e32 v0, 4, v228
	v_add3_u32 v237, s33, v168, v0
	v_cmp_gt_u32_e32 vcc, 32, v166
	s_movk_i32 s14, 0x7f
	v_cmp_lt_i32_e64 s[4:5], -1, v166
	s_waitcnt vmcnt(31)
	ds_write_b128 v230, v[6:9]
	s_waitcnt vmcnt(28)
	ds_write_b128 v230, v[14:17] offset:1024
	ds_write_b128 v230, v[10:13] offset:2048
	ds_write_b128 v230, v[2:5] offset:3072
	s_waitcnt vmcnt(24)
; #define LAS __attribute__((address_space(3)))
; __device__ __forceinline__ int crow(int r, int hi) { return (r & 3) + 8 * (r >> 2) + 4 * hi; }
; #define MFMA32(a, b, c) __builtin_amdgcn_mfma_f32_32x32x16_bf16(a, b, c, 0, 0, 0)
; __device__ __forceinline__ void qk_tile(const LAS unsigned char* kb, const bf16x8 (&qr)[4], f32x16& s0, f32x16& s1, int r32, int hi) {
;     const LAS unsigned char* kp = kb + hi * 1024 + r32 * 16;
;     f32x16 a = F16Z, b = F16Z;
; #pragma unroll
;     for (int d0 = 0; d0 < 4; ++d0) {
;         const bf16x8 k0 = *(const LAS bf16x8*)(kp + d0 * 2048), k1 = *(const LAS bf16x8*)(kp + d0 * 2048 + 512);
;         a = MFMA32(k0, qr[d0], a); b = MFMA32(k1, qr[d0], b);
;     }
;     s0 = a; s1 = b;
; }
; __device__ __forceinline__ void mask_tile(f32x16& s0, f32x16& s1, int key0, int klo, int khi, bool en, int hi) {
; #pragma unroll
;     for (int r = 0; r < 16; ++r) { const int k = key0 + crow(r, hi);
;         if (!(en && k >= klo && k <= khi)) s0[r] = NEG_INF;
;         if (!(en && k + 32 >= klo && k + 32 <= khi)) s1[r] = NEG_INF; }
; }
; __device__ __forceinline__ float half_swap_max(float m) { auto rr = __builtin_amdgcn_permlane32_swap(__float_as_uint(m), __float_as_uint(m), false, false); return fmaxf(__uint_as_float(rr[0]), __uint_as_float(rr[1])); }
; __device__ __forceinline__ float half_swap_sum(float m) { auto rr = __builtin_amdgcn_permlane32_swap(__float_as_uint(m), __float_as_uint(m), false, false); return __uint_as_float(rr[0]) + __uint_as_float(rr[1]); }
; __device__ __forceinline__ float tile_max(const f32x16& s0, const f32x16& s1) {
;     float m = fmaxf(s0[0], s1[0]);
; #pragma unroll
;     for (int r = 1; r < 16; ++r) m = fmaxf(m, fmaxf(s0[r], s1[r]));
;     return half_swap_max(m);
; }
	ds_write_b128 v230, v[30:33] offset:4096
	ds_write_b128 v230, v[26:29] offset:5120
	ds_write_b128 v230, v[22:25] offset:6144
	ds_write_b128 v230, v[18:21] offset:7168
	s_waitcnt vmcnt(23)
	ds_write_b128 v230, v[34:37] offset:8192
	s_waitcnt vmcnt(22)
	ds_write_b128 v230, v[38:41] offset:9216
	s_waitcnt vmcnt(21)
	ds_write_b128 v230, v[42:45] offset:10240
	s_waitcnt vmcnt(20)
	ds_write_b128 v230, v[46:49] offset:11264
	s_waitcnt vmcnt(19)
	ds_write_b128 v230, v[50:53] offset:12288
	s_waitcnt vmcnt(18)
	ds_write_b128 v230, v[54:57] offset:13312
	s_waitcnt vmcnt(17)
	ds_write_b128 v230, v[58:61] offset:14336
	s_waitcnt vmcnt(16)
	ds_write_b128 v230, v[62:65] offset:15360
	s_waitcnt lgkmcnt(0)
	ds_read_b128 v[2:5], v237
	ds_read_b128 v[6:9], v237 offset:512
	s_waitcnt lgkmcnt(1)
	v_mfma_f32_32x32x16_bf16 v[18:33], v[2:5], v[74:77], 0
	ds_read_b128 v[34:37], v237 offset:2048
	ds_read_b128 v[38:41], v237 offset:2560
	s_waitcnt lgkmcnt(2)
	v_mfma_f32_32x32x16_bf16 v[2:17], v[6:9], v[74:77], 0
	s_waitcnt lgkmcnt(1)
	v_mfma_f32_32x32x16_bf16 v[18:33], v[34:37], v[66:69], v[18:33]
	s_waitcnt lgkmcnt(0)
	v_mfma_f32_32x32x16_bf16 v[2:17], v[38:41], v[66:69], v[2:17]
	ds_read_b128 v[34:37], v237 offset:4096
	ds_read_b128 v[38:41], v237 offset:4608
	s_waitcnt lgkmcnt(1)
	v_mfma_f32_32x32x16_bf16 v[18:33], v[34:37], v[70:73], v[18:33]
	s_waitcnt lgkmcnt(0)
	v_mfma_f32_32x32x16_bf16 v[2:17], v[38:41], v[70:73], v[2:17]
	ds_read_b128 v[34:37], v237 offset:6144
	ds_read_b128 v[38:41], v237 offset:6656
	s_waitcnt lgkmcnt(1)
	v_mfma_f32_32x32x16_bf16 v[18:33], v[34:37], v[78:81], v[18:33]
	v_subrev_u32_e32 v34, 22, v166
	s_waitcnt lgkmcnt(0)
	v_mfma_f32_32x32x16_bf16 v[2:17], v[38:41], v[78:81], v[2:17]
	s_nop 8
	v_cndmask_b32_e32 v0, v219, v18, vcc
	v_subrev_u32_e32 v18, 24, v166
	v_cmp_gt_u32_e32 vcc, s46, v18
	v_or_b32_e32 v18, 1, v164
	v_cmp_gt_i32_e64 s[8:9], s14, v18
	s_and_b64 s[8:9], s[4:5], s[8:9]
	v_cndmask_b32_e32 v4, v4, v219, vcc
	v_cndmask_b32_e64 v18, v219, v19, s[8:9]
	v_or_b32_e32 v19, 2, v164
	v_cmp_gt_i32_e64 s[8:9], s14, v19
	s_and_b64 s[8:9], s[4:5], s[8:9]
	v_cndmask_b32_e32 v2, v2, v219, vcc
	v_cndmask_b32_e64 v19, v219, v20, s[8:9]
	v_or_b32_e32 v20, 3, v164
	v_cndmask_b32_e32 v3, v3, v219, vcc
	v_cmp_gt_i32_e32 vcc, s14, v20
	s_and_b64 vcc, s[4:5], vcc
	v_cmp_gt_u32_e64 s[4:5], s46, v34
	v_cndmask_b32_e32 v20, v219, v21, vcc
	v_subrev_u32_e32 v21, 23, v166
	v_cmp_lt_u32_e32 vcc, s46, v21
	v_add_u32_e32 v21, 2, v166
	v_cndmask_b32_e64 v8, v8, v219, s[4:5]
	v_cndmask_b32_e32 v5, v219, v5, vcc
	v_cmp_gt_u32_e32 vcc, 32, v21
	v_cndmask_b32_e64 v7, v7, v219, s[4:5]
	v_cndmask_b32_e64 v6, v6, v219, s[4:5]
	v_cmp_gt_u32_e64 s[4:5], 31, v21
	s_or_b64 vcc, s[4:5], vcc
	v_subrev_u32_e32 v34, 20, v166
	v_cndmask_b32_e64 v21, v219, v25, s[4:5]
	v_subrev_u32_e32 v25, 21, v166
	v_cndmask_b32_e32 v24, v219, v24, vcc
	v_cndmask_b32_e32 v23, v219, v23, vcc
	v_cndmask_b32_e32 v22, v219, v22, vcc
	v_cmp_lt_u32_e32 vcc, s46, v25
	v_add_u32_e32 v25, 4, v166
	v_cmp_gt_u32_e64 s[4:5], s46, v34
	v_cndmask_b32_e32 v9, v219, v9, vcc
	v_cmp_gt_u32_e32 vcc, 32, v25
	v_cndmask_b32_e64 v12, v12, v219, s[4:5]
	v_cndmask_b32_e64 v11, v11, v219, s[4:5]
	v_cndmask_b32_e64 v10, v10, v219, s[4:5]
	v_cmp_gt_u32_e64 s[4:5], 31, v25
	s_or_b64 vcc, s[4:5], vcc
	v_subrev_u32_e32 v34, 18, v166
	v_cndmask_b32_e64 v25, v219, v29, s[4:5]
	v_subrev_u32_e32 v29, 19, v166
	v_cndmask_b32_e32 v28, v219, v28, vcc
	v_cndmask_b32_e32 v27, v219, v27, vcc
	v_cndmask_b32_e32 v26, v219, v26, vcc
	v_cmp_lt_u32_e32 vcc, s46, v29
	v_add_u32_e32 v29, 6, v166
	v_cmp_gt_u32_e64 s[4:5], s46, v34
	v_cndmask_b32_e32 v13, v219, v13, vcc
	v_cmp_gt_u32_e32 vcc, 32, v29
	v_cndmask_b32_e64 v16, v16, v219, s[4:5]
	v_cndmask_b32_e64 v15, v15, v219, s[4:5]
	v_cndmask_b32_e64 v14, v14, v219, s[4:5]
	v_cmp_gt_u32_e64 s[4:5], 31, v29
	s_or_b64 vcc, s[4:5], vcc
	v_cndmask_b32_e32 v32, v219, v32, vcc
	v_cndmask_b32_e64 v29, v219, v33, s[4:5]
	v_subrev_u32_e32 v33, 17, v166
	v_cndmask_b32_e32 v31, v219, v31, vcc
	v_cndmask_b32_e32 v30, v219, v30, vcc
	v_cmp_lt_u32_e32 vcc, s46, v33
	v_max_f32_e32 v33, v3, v3
	v_max_f32_e32 v34, v18, v18
	v_max_f32_e32 v33, v34, v33
	v_max_f32_e32 v34, v4, v4
	v_max_f32_e32 v35, v19, v19
	v_max_f32_e32 v34, v35, v34
	v_max_f32_e32 v35, v5, v5
	v_max_f32_e32 v36, v20, v20
	v_max3_f32 v33, v0, v2, v33
	v_max_f32_e32 v35, v36, v35
	v_max3_f32 v33, v33, v34, v35
	v_max_f32_e32 v34, v6, v6
	v_max_f32_e32 v35, v22, v22
	v_max_f32_e32 v34, v35, v34
	v_max_f32_e32 v35, v7, v7
	v_max_f32_e32 v36, v23, v23
	v_max_f32_e32 v35, v36, v35
	v_max3_f32 v33, v33, v34, v35
	v_max_f32_e32 v34, v8, v8
	v_max_f32_e32 v35, v24, v24
	v_max_f32_e32 v34, v35, v34
	v_max_f32_e32 v35, v9, v9
	v_max_f32_e32 v36, v21, v21
	v_max_f32_e32 v35, v36, v35
	v_max3_f32 v33, v33, v34, v35
	v_max_f32_e32 v34, v10, v10
	v_max_f32_e32 v35, v26, v26
	v_max_f32_e32 v34, v35, v34
	v_max_f32_e32 v35, v11, v11
	v_max_f32_e32 v36, v27, v27
	v_max_f32_e32 v35, v36, v35
	v_max3_f32 v33, v33, v34, v35
	v_max_f32_e32 v34, v12, v12
	v_max_f32_e32 v35, v28, v28
	v_max_f32_e32 v34, v35, v34
	v_max_f32_e32 v35, v13, v13
	v_max_f32_e32 v36, v25, v25
	v_max_f32_e32 v35, v36, v35
	v_max3_f32 v33, v33, v34, v35
	v_max_f32_e32 v34, v14, v14
	v_max_f32_e32 v35, v30, v30
	v_max_f32_e32 v34, v35, v34
	v_max_f32_e32 v35, v15, v15
	v_max_f32_e32 v36, v31, v31
	v_max_f32_e32 v35, v36, v35
	v_cndmask_b32_e32 v17, v219, v17, vcc
	v_max3_f32 v33, v33, v34, v35
	v_max_f32_e32 v34, v16, v16
	v_max_f32_e32 v35, v32, v32
	v_max_f32_e32 v34, v35, v34
	v_max_f32_e32 v35, v17, v17
	v_max_f32_e32 v36, v29, v29
	v_max_f32_e32 v35, v36, v35
; __device__ __forceinline__ float fast_exp2(float x) { return __builtin_amdgcn_exp2f(x); }
; __device__ __forceinline__ void attn_decode_unit(const Params& P, const Ctx& C, int sg) {
;     ...
;         wave_tile_commit(k0r, v0r, KB, VB, lane); qk_tile(KB, qr, s0, s1, r32, hi); mask_tile(s0, s1, 0, 0, cmax, true, hi);
;         const float m0 = tile_max(s0, s1); float l0 = 0.f;
; #pragma unroll
;         for (int r = 0; r < 16; ++r) { s0[r] = fast_exp2(s0[r] - m0); s1[r] = fast_exp2(s1[r] - m0); l0 += s0[r] + s1[r]; }
;         imp_tile(s0, s1, hi, carry, val0);
;         pv_tile(VB, s0, s1, oc0, oc1, lane, hi);
;         wave_tile_commit(k1r, v1r, KB, VB, lane); qk_tile(KB, qr, s0, s1, r32, hi); mask_tile(s0, s1, 64, 0, cmax, true, hi);
	v_max3_f32 v33, v33, v34, v35
	v_mov_b32_e32 v34, v33
	s_nop 1
	v_permlane32_swap_b32_e32 v33, v34
	v_max_f32_e32 v34, v34, v34
	v_max_f32_e32 v33, v33, v33
	v_max_f32_e32 v238, v33, v34
	v_sub_f32_e32 v5, v5, v238
	v_exp_f32_e32 v175, v5
	v_sub_f32_e32 v5, v22, v238
	v_exp_f32_e32 v188, v5
	v_sub_f32_e32 v5, v6, v238
	v_exp_f32_e32 v171, v5
	v_sub_f32_e32 v5, v23, v238
	v_exp_f32_e32 v189, v5
	v_sub_f32_e32 v5, v7, v238
	v_exp_f32_e32 v173, v5
	v_sub_f32_e32 v5, v24, v238
	v_exp_f32_e32 v192, v5
	v_sub_f32_e32 v5, v8, v238
	v_exp_f32_e32 v176, v5
	v_sub_f32_e32 v5, v21, v238
	v_exp_f32_e32 v195, v5
	v_sub_f32_e32 v5, v9, v238
	v_exp_f32_e32 v179, v5
	v_sub_f32_e32 v5, v26, v238
	v_exp_f32_e32 v191, v5
	v_sub_f32_e32 v5, v10, v238
	v_exp_f32_e32 v174, v5
	v_sub_f32_e32 v5, v27, v238
	v_exp_f32_e32 v193, v5
	v_sub_f32_e32 v5, v11, v238
	v_exp_f32_e32 v177, v5
	v_sub_f32_e32 v5, v28, v238
	v_exp_f32_e32 v196, v5
	v_sub_f32_e32 v5, v12, v238
	v_exp_f32_e32 v180, v5
	v_sub_f32_e32 v5, v25, v238
	v_exp_f32_e32 v199, v5
	v_sub_f32_e32 v5, v13, v238
	v_exp_f32_e32 v182, v5
	v_sub_f32_e32 v5, v30, v238
	v_exp_f32_e32 v194, v5
	v_sub_f32_e32 v5, v14, v238
	v_exp_f32_e32 v178, v5
	v_sub_f32_e32 v5, v31, v238
	v_exp_f32_e32 v197, v5
	v_sub_f32_e32 v5, v15, v238
	v_sub_f32_e32 v4, v4, v238
	v_exp_f32_e32 v181, v5
	v_sub_f32_e32 v5, v32, v238
	v_exp_f32_e32 v172, v4
	v_sub_f32_e32 v4, v20, v238
	v_exp_f32_e32 v200, v5
	v_sub_f32_e32 v5, v16, v238
	v_exp_f32_e32 v4, v4
	v_exp_f32_e32 v183, v5
	v_sub_f32_e32 v5, v29, v238
	v_exp_f32_e32 v201, v5
	v_sub_f32_e32 v5, v17, v238
	v_cmp_lt_i32_e32 vcc, v221, v222
	v_sub_f32_e32 v0, v0, v238
	v_sub_f32_e32 v3, v3, v238
	v_exp_f32_e32 v184, v5
	v_cndmask_b32_e32 v5, v220, v221, vcc
	v_exp_f32_e32 v33, v0
	v_sub_f32_e32 v0, v2, v238
	v_sub_f32_e32 v2, v18, v238
	v_exp_f32_e32 v170, v3
	v_sub_f32_e32 v3, v19, v238
	v_lshlrev_b32_e32 v206, 2, v5
	v_exp_f32_e32 v2, v2
	v_exp_f32_e32 v3, v3
	ds_bpermute_b32 v204, v206, v4
	v_cmp_gt_u32_e64 s[4:5], 32, v165
	v_add_f32_e32 v5, v33, v2
	v_add_f32_e32 v6, v3, v4
	v_add_f32_e32 v5, v5, v6
	s_waitcnt lgkmcnt(0)
	v_cndmask_b32_e64 v6, v204, 0, s[4:5]
	v_add_f32_e32 v205, v6, v5
	v_lshlrev_b32_e32 v5, 1, v165
	v_lshlrev_b32_e32 v6, 3, v165
	v_and_b32_e32 v5, 32, v5
	v_and_b32_e32 v6, 24, v6
	v_add3_u32 v5, s33, v5, v6
	v_lshlrev_b32_e32 v6, 8, v166
	v_and_b32_e32 v7, 0xc0, v229
	v_add3_u32 v211, v5, v6, v7
	v_exp_f32_e32 v169, v0
	v_cvt_pk_bf16_f32 v34, v33, v2
	v_cvt_pk_bf16_f32 v35, v3, v4
	v_cvt_pk_bf16_f32 v36, v188, v189
	v_cvt_pk_bf16_f32 v37, v192, v195
	ds_read_b64_tr_b16 v[94:95], v211 offset:8192
	ds_read_b64_tr_b16 v[96:97], v211 offset:8704
	ds_read_b64_tr_b16 v[38:39], v211 offset:12288
	ds_read_b64_tr_b16 v[40:41], v211 offset:12800
	v_cvt_pk_bf16_f32 v42, v191, v193
	v_cvt_pk_bf16_f32 v43, v196, v199
	v_cvt_pk_bf16_f32 v44, v194, v197
	v_cvt_pk_bf16_f32 v45, v200, v201
	ds_read_b64_tr_b16 v[82:83], v211 offset:9216
	ds_read_b64_tr_b16 v[84:85], v211 offset:9728
	ds_read_b64_tr_b16 v[46:47], v211 offset:13312
	ds_read_b64_tr_b16 v[48:49], v211 offset:13824
	v_cvt_pk_bf16_f32 v50, v169, v170
	v_cvt_pk_bf16_f32 v51, v172, v175
	v_cvt_pk_bf16_f32 v52, v171, v173
	v_cvt_pk_bf16_f32 v53, v176, v179
	ds_read_b64_tr_b16 v[86:87], v211 offset:10240
	ds_read_b64_tr_b16 v[88:89], v211 offset:10752
	ds_read_b64_tr_b16 v[58:59], v211 offset:14336
	ds_read_b64_tr_b16 v[60:61], v211 offset:14848
	v_cvt_pk_bf16_f32 v54, v174, v177
	v_cvt_pk_bf16_f32 v55, v180, v182
	v_cvt_pk_bf16_f32 v56, v178, v181
	v_cvt_pk_bf16_f32 v57, v183, v184
	ds_read_b64_tr_b16 v[90:91], v211 offset:11264
	ds_read_b64_tr_b16 v[92:93], v211 offset:11776
	ds_read_b64_tr_b16 v[62:63], v211 offset:15360
	ds_read_b64_tr_b16 v[64:65], v211 offset:15872
	s_waitcnt lgkmcnt(0)
	s_waitcnt vmcnt(15)
	ds_write_b128 v230, v[102:105]
	s_waitcnt vmcnt(12)
	ds_write_b128 v230, v[110:113] offset:1024
	ds_write_b128 v230, v[106:109] offset:2048
	ds_write_b128 v230, v[98:101] offset:3072
	s_waitcnt vmcnt(8)
	ds_write_b128 v230, v[126:129] offset:4096
	ds_write_b128 v230, v[122:125] offset:5120
	ds_write_b128 v230, v[118:121] offset:6144
	ds_write_b128 v230, v[114:117] offset:7168
	s_waitcnt vmcnt(7)
	ds_write_b128 v230, v[130:133] offset:8192
	s_waitcnt vmcnt(6)
	ds_write_b128 v230, v[134:137] offset:9216
	s_waitcnt vmcnt(5)
	ds_write_b128 v230, v[138:141] offset:10240
	s_waitcnt vmcnt(4)
	ds_write_b128 v230, v[142:145] offset:11264
	s_waitcnt vmcnt(3)
	ds_write_b128 v230, v[146:149] offset:12288
	s_waitcnt vmcnt(2)
	ds_write_b128 v230, v[150:153] offset:13312
	s_waitcnt vmcnt(1)
	ds_write_b128 v230, v[154:157] offset:14336
	s_waitcnt vmcnt(0)
	ds_write_b128 v230, v[158:161] offset:15360
	s_waitcnt lgkmcnt(0)
	v_add_f32_e32 v207, v2, v170
	v_add_f32_e32 v208, v3, v172
	v_add_f32_e32 v210, v4, v175
	ds_read_b128 v[2:5], v237
	ds_read_b128 v[6:9], v237 offset:512
	v_add_f32_e32 v0, v33, v169
	s_waitcnt lgkmcnt(1)
	v_mfma_f32_32x32x16_bf16 v[18:33], v[2:5], v[74:77], 0
	ds_read_b128 v[98:101], v237 offset:2048
	ds_read_b128 v[102:105], v237 offset:2560
	v_add_f32_e32 v0, 0, v0
	v_add_f32_e32 v0, v207, v0
	v_add_f32_e32 v0, v208, v0
	v_add_f32_e32 v212, v188, v171
	v_add_f32_e32 v0, v210, v0
	v_add_f32_e32 v213, v189, v173
	s_waitcnt lgkmcnt(2)
	v_mfma_f32_32x32x16_bf16 v[2:17], v[6:9], v[74:77], 0
	v_add_f32_e32 v0, v212, v0
	v_add_f32_e32 v214, v192, v176
	v_add_f32_e32 v0, v213, v0
	v_add_f32_e32 v215, v195, v179
	v_add_f32_e32 v0, v214, v0
	v_add_f32_e32 v216, v191, v174
	v_add_f32_e32 v0, v215, v0
	s_waitcnt lgkmcnt(0)
; __device__ __forceinline__ float fast_exp2(float x) { return __builtin_amdgcn_exp2f(x); }
; __device__ __forceinline__ void attn_decode_unit(const Params& P, const Ctx& C, int sg) {
;     ...
;         wave_tile_commit(k1r, v1r, KB, VB, lane); qk_tile(KB, qr, s0, s1, r32, hi); mask_tile(s0, s1, 64, 0, cmax, true, hi);
;         const float m1 = fmaxf(m0, tile_max(s0, s1)); const float a = fast_exp2(m0 - m1); float l1 = 0.f;
; #pragma unroll
;         for (int r = 0; r < 16; ++r) { s0[r] = fast_exp2(s0[r] - m1); s1[r] = fast_exp2(s1[r] - m1); l1 += s0[r] + s1[r]; }
;         carry *= a; oc0 = oc0 * a; oc1 = oc1 * a;
;         imp_tile(s0, s1, hi, carry, val1);
	v_mfma_f32_32x32x16_bf16 v[2:17], v[102:105], v[66:69], v[2:17]
	v_add_f32_e32 v217, v193, v177
	v_add_f32_e32 v0, v216, v0
	v_add_f32_e32 v231, v196, v180
	v_add_f32_e32 v0, v217, v0
	v_add_f32_e32 v232, v199, v182
	v_add_f32_e32 v0, v231, v0
	v_add_f32_e32 v233, v194, v178
	v_mfma_f32_32x32x16_bf16 v[18:33], v[98:101], v[66:69], v[18:33]
	ds_read_b128 v[98:101], v237 offset:4096
	ds_read_b128 v[102:105], v237 offset:4608
	v_add_f32_e32 v0, v232, v0
	v_add_f32_e32 v234, v197, v181
	v_add_f32_e32 v0, v233, v0
	v_add_f32_e32 v235, v200, v183
	v_add_f32_e32 v0, v234, v0
	v_add_f32_e32 v236, v201, v184
	s_waitcnt lgkmcnt(0)
	v_mfma_f32_32x32x16_bf16 v[2:17], v[102:105], v[70:73], v[2:17]
	v_add_f32_e32 v0, v235, v0
	v_add_f32_e32 v148, v236, v0
	ds_bpermute_b32 v186, v206, v184
	ds_bpermute_b32 v203, v206, v195
	ds_bpermute_b32 v202, v206, v199
	ds_bpermute_b32 v198, v206, v201
	ds_bpermute_b32 v190, v206, v175
	v_mfma_f32_32x32x16_bf16 v[18:33], v[98:101], v[70:73], v[18:33]
	ds_read_b128 v[98:101], v237 offset:6144
	ds_read_b128 v[102:105], v237 offset:6656
	ds_bpermute_b32 v187, v206, v179
	ds_bpermute_b32 v185, v206, v182
	s_waitcnt lgkmcnt(2)
	v_mfma_f32_32x32x16_bf16 v[2:17], v[102:105], v[78:81], v[2:17]
	v_mfma_f32_32x32x16_bf16 v[18:33], v[98:101], v[78:81], v[18:33]
	v_add_u32_e32 v99, -8, v166
	v_add_u32_e32 v98, 16, v166
	v_cmp_gt_u32_e64 s[8:9], s46, v99
	v_cmp_gt_u32_e32 vcc, 32, v98
	v_add_u32_e32 v99, -6, v166
	s_nop 5
	v_cndmask_b32_e64 v4, v4, v219, s[8:9]
	v_cndmask_b32_e64 v2, v2, v219, s[8:9]
	v_cndmask_b32_e64 v3, v3, v219, s[8:9]
	v_cmp_gt_u32_e64 s[8:9], 31, v98
	s_or_b64 vcc, s[8:9], vcc
	v_add_u32_e32 v98, -7, v166
	v_cndmask_b32_e64 v21, v219, v21, s[8:9]
	v_cndmask_b32_e32 v20, v219, v20, vcc
	v_cndmask_b32_e32 v18, v219, v18, vcc
	v_cndmask_b32_e32 v19, v219, v19, vcc
	v_cmp_lt_u32_e32 vcc, s46, v98
	v_add_u32_e32 v98, 18, v166
	v_cmp_gt_u32_e64 s[8:9], s46, v99
	v_cndmask_b32_e32 v5, v219, v5, vcc
	v_cmp_gt_u32_e32 vcc, 32, v98
	v_cndmask_b32_e64 v8, v8, v219, s[8:9]
	v_cndmask_b32_e64 v7, v7, v219, s[8:9]
	v_cndmask_b32_e64 v6, v6, v219, s[8:9]
	v_cmp_gt_u32_e64 s[8:9], 31, v98
	s_or_b64 vcc, s[8:9], vcc
	v_cndmask_b32_e32 v98, v219, v22, vcc
	v_add_u32_e32 v22, -5, v166
	v_add_u32_e32 v99, -4, v166
	v_cndmask_b32_e64 v25, v219, v25, s[8:9]
	v_cndmask_b32_e32 v24, v219, v24, vcc
	v_cndmask_b32_e32 v23, v219, v23, vcc
	v_cmp_lt_u32_e32 vcc, s46, v22
	v_add_u32_e32 v22, 20, v166
	v_cmp_gt_u32_e64 s[8:9], s46, v99
	v_cndmask_b32_e32 v9, v219, v9, vcc
	v_cmp_gt_u32_e32 vcc, 32, v22
	v_cndmask_b32_e64 v12, v12, v219, s[8:9]
	v_cndmask_b32_e64 v11, v11, v219, s[8:9]
	v_cndmask_b32_e64 v10, v10, v219, s[8:9]
	v_cmp_gt_u32_e64 s[8:9], 31, v22
	s_or_b64 vcc, s[8:9], vcc
	v_cndmask_b32_e32 v99, v219, v26, vcc
	v_add_u32_e32 v22, -3, v166
	v_add_u32_e32 v26, -2, v166
	v_cndmask_b32_e64 v29, v219, v29, s[8:9]
	v_cndmask_b32_e32 v28, v219, v28, vcc
	v_cndmask_b32_e32 v27, v219, v27, vcc
	v_cmp_lt_u32_e32 vcc, s46, v22
	v_add_u32_e32 v22, 22, v166
	v_cmp_gt_u32_e64 s[8:9], s46, v26
	v_cndmask_b32_e32 v13, v219, v13, vcc
	v_cmp_gt_u32_e32 vcc, 32, v22
	v_cndmask_b32_e64 v16, v16, v219, s[8:9]
	v_cndmask_b32_e64 v15, v15, v219, s[8:9]
	v_cndmask_b32_e64 v14, v14, v219, s[8:9]
	v_cmp_gt_u32_e64 s[8:9], 31, v22
	s_or_b64 vcc, s[8:9], vcc
	v_add_u32_e32 v22, -1, v166
	v_cndmask_b32_e32 v101, v219, v32, vcc
	v_cndmask_b32_e32 v32, v219, v31, vcc
	v_cndmask_b32_e32 v102, v219, v30, vcc
	v_cmp_lt_u32_e32 vcc, s46, v22
	v_max_f32_e32 v22, v3, v3
	v_max_f32_e32 v26, v19, v19
	v_max_f32_e32 v22, v26, v22
	v_max_f32_e32 v26, v4, v4
	v_max_f32_e32 v30, v20, v20
	v_max_f32_e32 v26, v30, v26
	v_max_f32_e32 v30, v5, v5
	v_max_f32_e32 v31, v21, v21
	v_max3_f32 v22, v18, v2, v22
	v_max_f32_e32 v30, v31, v30
	v_max3_f32 v22, v22, v26, v30
	v_max_f32_e32 v26, v6, v6
	v_max_f32_e32 v30, v98, v98
	v_max_f32_e32 v26, v30, v26
	v_max_f32_e32 v30, v7, v7
	v_max_f32_e32 v31, v23, v23
	v_max_f32_e32 v30, v31, v30
	v_max3_f32 v22, v22, v26, v30
	v_max_f32_e32 v26, v8, v8
	v_max_f32_e32 v30, v24, v24
	v_max_f32_e32 v26, v30, v26
	v_max_f32_e32 v30, v9, v9
	v_max_f32_e32 v31, v25, v25
	v_max_f32_e32 v30, v31, v30
	v_max3_f32 v22, v22, v26, v30
	v_max_f32_e32 v26, v10, v10
	v_max_f32_e32 v30, v99, v99
	v_max_f32_e32 v26, v30, v26
	v_max_f32_e32 v30, v11, v11
	v_max_f32_e32 v31, v27, v27
	v_max_f32_e32 v30, v31, v30
	v_max3_f32 v22, v22, v26, v30
	v_max_f32_e32 v26, v12, v12
	v_max_f32_e32 v30, v28, v28
	v_max_f32_e32 v26, v30, v26
	v_max_f32_e32 v30, v13, v13
	v_max_f32_e32 v31, v29, v29
	v_max_f32_e32 v30, v31, v30
	v_max3_f32 v22, v22, v26, v30
	v_max_f32_e32 v26, v14, v14
	v_max_f32_e32 v30, v102, v102
	v_max_f32_e32 v26, v30, v26
	v_max_f32_e32 v30, v15, v15
	v_max_f32_e32 v31, v32, v32
	v_max_f32_e32 v30, v31, v30
	v_cndmask_b32_e64 v100, v219, v33, s[8:9]
	v_cndmask_b32_e32 v17, v219, v17, vcc
	v_max3_f32 v22, v22, v26, v30
	v_max_f32_e32 v26, v16, v16
	v_max_f32_e32 v30, v101, v101
	v_max_f32_e32 v26, v30, v26
	v_max_f32_e32 v30, v17, v17
	v_max_f32_e32 v31, v100, v100
	v_max_f32_e32 v30, v31, v30
	v_max3_f32 v22, v22, v26, v30
	v_mov_b32_e32 v26, v22
	s_nop 1
	v_permlane32_swap_b32_e32 v22, v26
	v_max3_f32 v103, v238, v22, v26
	v_sub_f32_e32 v18, v18, v103
	v_sub_f32_e32 v2, v2, v103
	v_exp_f32_e32 v105, v18
	v_exp_f32_e32 v18, v2
	v_sub_f32_e32 v19, v19, v103
	v_sub_f32_e32 v3, v3, v103
	v_exp_f32_e32 v106, v19
	v_exp_f32_e32 v19, v3
	v_add_f32_e32 v2, v105, v18
	v_add_f32_e32 v2, 0, v2
	v_sub_f32_e32 v104, v238, v103
	v_add_f32_e32 v3, v106, v19
	v_add_f32_e32 v2, v3, v2
; __device__ __forceinline__ float half_swap_sum(float m) { auto rr = __builtin_amdgcn_permlane32_swap(__float_as_uint(m), __float_as_uint(m), false, false); return __uint_as_float(rr[0]) + __uint_as_float(rr[1]); }
; __device__ __forceinline__ void attn_decode_unit(const Params& P, const Ctx& C, int sg) {
;     ...
;         imp_tile(s0, s1, hi, carry, val1);
;         pv_tile(VB, s0, s1, oc0, oc1, lane, hi);
;         const float inv = 1.0f / fmaxf(half_swap_sum(l0 * a + l1), 1e-20f); const float inva = inv * a;
; #pragma unroll
;         for (int gi = 0; gi < 8; ++gi) { float w0 = val0[gi] * inva, w1 = val1[gi] * inv;
;             w0 += __shfl_xor(w0, 4); w1 += __shfl_xor(w1, 4);
;             if (r32 < 4) { DIMP[r32 * 64 + 2 * gi + hi] = w0; DIMP[r32 * 64 + 16 + 2 * gi + hi] = w1; } }
	v_sub_f32_e32 v3, v20, v103
	v_exp_f32_e32 v107, v3
	v_sub_f32_e32 v3, v4, v103
	v_exp_f32_e32 v20, v3
	v_exp_f32_e32 v0, v104
	v_add_f32_e32 v3, v107, v20
	v_add_f32_e32 v2, v3, v2
	v_sub_f32_e32 v3, v21, v103
	v_exp_f32_e32 v108, v3
	v_sub_f32_e32 v3, v5, v103
	v_exp_f32_e32 v22, v3
	ds_bpermute_b32 v153, v206, v108
	v_add_f32_e32 v3, v108, v22
	v_add_f32_e32 v2, v3, v2
	v_sub_f32_e32 v3, v98, v103
	v_exp_f32_e32 v31, v3
	v_sub_f32_e32 v3, v6, v103
	v_exp_f32_e32 v21, v3
	ds_bpermute_b32 v146, v206, v22
	v_add_f32_e32 v3, v31, v21
	v_add_f32_e32 v2, v3, v2
	v_sub_f32_e32 v3, v23, v103
	v_exp_f32_e32 v33, v3
	v_sub_f32_e32 v3, v7, v103
	v_exp_f32_e32 v23, v3
	s_nop 0
	v_add_f32_e32 v3, v33, v23
	v_add_f32_e32 v2, v3, v2
	v_sub_f32_e32 v3, v24, v103
	v_exp_f32_e32 v132, v3
	v_sub_f32_e32 v3, v8, v103
	v_exp_f32_e32 v24, v3
	s_nop 0
	v_add_f32_e32 v3, v132, v24
	v_add_f32_e32 v2, v3, v2
	v_sub_f32_e32 v3, v25, v103
	v_exp_f32_e32 v135, v3
	v_sub_f32_e32 v3, v9, v103
	v_exp_f32_e32 v26, v3
	ds_bpermute_b32 v152, v206, v135
	v_add_f32_e32 v3, v135, v26
	v_add_f32_e32 v2, v3, v2
	v_sub_f32_e32 v3, v99, v103
	v_exp_f32_e32 v134, v3
	v_sub_f32_e32 v3, v10, v103
	v_exp_f32_e32 v25, v3
	ds_bpermute_b32 v145, v206, v26
	v_add_f32_e32 v3, v134, v25
	v_add_f32_e32 v2, v3, v2
	v_sub_f32_e32 v3, v27, v103
	v_exp_f32_e32 v136, v3
	v_sub_f32_e32 v3, v11, v103
	v_exp_f32_e32 v27, v3
	s_nop 0
	v_add_f32_e32 v3, v136, v27
	v_add_f32_e32 v2, v3, v2
	v_sub_f32_e32 v3, v28, v103
	v_exp_f32_e32 v137, v3
	v_sub_f32_e32 v3, v12, v103
	v_exp_f32_e32 v28, v3
	s_nop 0
	v_add_f32_e32 v3, v137, v28
	v_add_f32_e32 v2, v3, v2
	v_sub_f32_e32 v3, v29, v103
	v_exp_f32_e32 v139, v3
	v_sub_f32_e32 v3, v13, v103
	v_exp_f32_e32 v30, v3
	ds_bpermute_b32 v150, v206, v139
	v_add_f32_e32 v3, v139, v30
	v_add_f32_e32 v2, v3, v2
	v_sub_f32_e32 v3, v102, v103
	v_exp_f32_e32 v138, v3
	v_sub_f32_e32 v3, v14, v103
	v_exp_f32_e32 v29, v3
	ds_bpermute_b32 v143, v206, v30
	v_add_f32_e32 v3, v138, v29
	v_add_f32_e32 v2, v3, v2
	v_sub_f32_e32 v3, v32, v103
	v_exp_f32_e32 v140, v3
	v_sub_f32_e32 v3, v15, v103
	v_exp_f32_e32 v32, v3
	s_nop 0
	v_add_f32_e32 v3, v140, v32
	v_add_f32_e32 v2, v3, v2
	v_sub_f32_e32 v3, v101, v103
	v_exp_f32_e32 v141, v3
	v_sub_f32_e32 v3, v16, v103
	v_exp_f32_e32 v131, v3
	s_nop 0
	v_add_f32_e32 v3, v141, v131
	v_add_f32_e32 v2, v3, v2
	v_sub_f32_e32 v3, v100, v103
	v_exp_f32_e32 v142, v3
	v_sub_f32_e32 v3, v17, v103
	v_exp_f32_e32 v133, v3
	ds_bpermute_b32 v147, v206, v142
	v_add_f32_e32 v3, v142, v133
	v_add_f32_e32 v130, v3, v2
	v_mfma_f32_32x32x16_bf16 v[2:17], v[94:97], v[34:37], 0
	v_fmac_f32_e32 v130, v148, v0
	v_mov_b32_e32 v148, v130
	s_nop 1
	v_permlane32_swap_b32_e32 v130, v148
	v_add_f32_e32 v130, v130, v148
	v_max_f32_e32 v130, 0x1e3ce508, v130
	v_div_scale_f32 v148, s[8:9], v130, v130, 1.0
	v_mfma_f32_32x32x16_bf16 v[2:17], v[82:85], v[42:45], v[2:17]
	v_rcp_f32_e32 v149, v148
	v_mul_f32_e32 v82, v0, v186
	v_add_f32_e32 v83, v105, v106
	v_add_f32_e32 v84, v107, v108
	v_fma_f32 v154, -v148, v149, 1.0
	v_fmac_f32_e32 v149, v154, v149
	v_div_scale_f32 v154, vcc, 1.0, v130, 1.0
	v_mfma_f32_32x32x16_bf16 v[2:17], v[86:89], v[50:53], v[2:17]
	v_mul_f32_e32 v155, v154, v149
	v_fma_f32 v156, -v148, v155, v154
	v_fmac_f32_e32 v155, v156, v149
	v_fma_f32 v148, -v148, v155, v154
	v_div_fmas_f32 v148, v148, v149, v155
	v_add_f32_e32 v83, v83, v84
	s_waitcnt lgkmcnt(6)
	v_cndmask_b32_e64 v82, v153, v82, s[4:5]
	v_mfma_f32_32x32x16_bf16 v[2:17], v[90:93], v[54:57], v[2:17]
	v_div_fixup_f32 v130, v148, v130, 1.0
	v_cmp_lt_i32_e32 vcc, v223, v222
	v_add_f32_e32 v151, v82, v83
	v_cvt_pk_bf16_f32 v94, v105, v106
	v_cvt_pk_bf16_f32 v95, v107, v108
	v_cvt_pk_bf16_f32 v96, v31, v33
	v_cvt_pk_bf16_f32 v97, v132, v135
	ds_read_b64_tr_b16 v[126:127], v211 offset:8192
	ds_read_b64_tr_b16 v[128:129], v211 offset:8704
	ds_read_b64_tr_b16 v[122:123], v211 offset:12288
	ds_read_b64_tr_b16 v[124:125], v211 offset:12800
	v_cvt_pk_bf16_f32 v90, v134, v136
	v_cvt_pk_bf16_f32 v91, v137, v139
	v_cvt_pk_bf16_f32 v92, v138, v140
	v_cvt_pk_bf16_f32 v93, v141, v142
	ds_read_b64_tr_b16 v[110:111], v211 offset:9216
	ds_read_b64_tr_b16 v[112:113], v211 offset:9728
	ds_read_b64_tr_b16 v[118:119], v211 offset:13312
	ds_read_b64_tr_b16 v[120:121], v211 offset:13824
	v_cvt_pk_bf16_f32 v86, v18, v19
	v_cvt_pk_bf16_f32 v87, v20, v22
	v_cvt_pk_bf16_f32 v88, v21, v23
	v_cvt_pk_bf16_f32 v89, v24, v26
	ds_read_b64_tr_b16 v[106:107], v211 offset:10240
	ds_read_b64_tr_b16 v[108:109], v211 offset:10752
	ds_read_b64_tr_b16 v[114:115], v211 offset:14336
	ds_read_b64_tr_b16 v[116:117], v211 offset:14848
	v_cvt_pk_bf16_f32 v82, v25, v27
	v_cvt_pk_bf16_f32 v83, v28, v30
	v_cvt_pk_bf16_f32 v84, v29, v32
	v_cvt_pk_bf16_f32 v85, v131, v133
	ds_read_b64_tr_b16 v[102:103], v211 offset:11264
	ds_read_b64_tr_b16 v[104:105], v211 offset:11776
	ds_read_b64_tr_b16 v[98:99], v211 offset:15360
	ds_read_b64_tr_b16 v[100:101], v211 offset:15872
	v_mul_f32_e32 v148, v0, v130
	v_cndmask_b32_e32 v149, v220, v223, vcc
	v_lshlrev_b32_e32 v149, 2, v149
	v_mul_f32_e32 v154, v205, v148
	v_mul_f32_e32 v155, v151, v130
	ds_bpermute_b32 v144, v206, v133
	ds_bpermute_b32 v156, v149, v154
	ds_bpermute_b32 v157, v149, v155
	v_readlane_b32 s8, v254, 28
	v_cmp_gt_u32_e32 vcc, 4, v228
	s_nop 0
	v_lshl_add_u32 v158, v228, 8, s8
	v_lshl_add_u32 v151, v166, 2, v158
	s_and_saveexec_b64 s[8:9], vcc
	s_cbranch_execz .LBB0_1219
	s_waitcnt lgkmcnt(0)
	v_add_f32_e32 v155, v155, v157
	v_add_f32_e32 v154, v154, v156
	ds_write2_b32 v151, v154, v155 offset1:16

; #define LAS __attribute__((address_space(3)))
; __device__ __forceinline__ unsigned cvt_pk_bf16(float lo, float hi) { unsigned r; asm volatile("v_cvt_pk_bf16_f32 %0, %1, %2" : "=v"(r) : "v"(lo), "v"(hi)); return r; }
; #define LDS_WAIT() asm volatile("s_waitcnt lgkmcnt(0)" ::: "memory")
; __device__ __forceinline__ void f32_k_issue(F32Tile& T, const float* kp, int lane) {
;     const float* kl = kp + (size_t)(lane >> 4) * 256 + (lane & 15) * 4;
; #pragma unroll
;     for (int i = 0; i < 16; ++i) T.x[i] = *(const f32x4*)(kl + (size_t)(4 * i) * 256);
; }
; template <int H> __device__ __forceinline__ void f32_k_commit(const F32Tile& T, LAS unsigned char* kb, int lane, float* kcopy, int skip) {
;     const int pc = lane & 15, rl = lane >> 4, c = pc >> 1;
;     float* kc = kcopy + (size_t)rl * 256 + pc * 4;
;     const unsigned keo = (unsigned)(c * 1024 + (pc & 1) * 8 + ((rl + c) & 7) * 16);
;     if (H == 0) LDS_WAIT();
; #pragma unroll
;     for (int i = 8 * H; i < 8 * H + 8; ++i) { u32x2 w; w.x = cvt_pk_bf16(T.x[i][0], T.x[i][1]); w.y = cvt_pk_bf16(T.x[i][2], T.x[i][3]);
;         *(LAS u32x2*)(kb + ((i & 1) ? (keo ^ 64u) : keo) + 128 * (i >> 1)) = w;
;         if (kcopy && 4 * i + rl >= skip) *(f32x4*)(kc + (size_t)(4 * i) * 256) = T.x[i]; }
;     if (H == 1) LDS_WAIT();
; }
; __device__ __forceinline__ void f32_v_issue(F32Half& T, const float* vp, int lane, int h) {
;     const float* vl = vp + (size_t)(lane >> 4) * 256 + (lane & 15) * 4;
; #pragma unroll
;     for (int i = 0; i < 8; ++i) T.x[i] = *(const f32x4*)(vl + (size_t)(4 * (8 * h + i)) * 256);
; }
; __device__ __forceinline__ void attn_decode_unit(const Params& P, const Ctx& C, int sg) {
;     ...
;     const float* sk = in6 + (size_t)seq * (512 * 256) + g * 64; const float* sv = in7 + (size_t)seq * (512 * 256) + g * 64;
;     float* ck = outp + O_SKW + (size_t)seq * (512 * 256) + g * 64; float* cv = outp + O_SVW + (size_t)seq * (512 * 256) + g * 64;
;     if (wave != 0) { const int j = wave;
;         F32_TILE_STEP(sk + (size_t)j * 64 * 256, sv + (size_t)j * 64 * 256, ck + ((ptrdiff_t)j * 64 - 4) * 256, cv + ((ptrdiff_t)j * 64 - 4) * 256, 0, 64 * j, qi + 1, 512 + qi, true, m_w, l_w, ow0, ow1); }
.LBB0_1240:
	s_ashr_i32 s94, s52, 2
	s_ashr_i32 s95, s94, 31
	s_lshl_b64 s[4:5], s[94:95], 19
	s_add_u32 s8, s12, s4
	s_addc_u32 s9, s13, s5
	s_lshl_b32 s12, s53, 8
	s_add_u32 s56, s8, s12
	s_addc_u32 s57, s9, 0
	s_add_u32 s8, s10, s4
	s_addc_u32 s9, s11, s5
	s_add_u32 s54, s8, s12
	s_addc_u32 s55, s9, 0
	s_add_u32 s2, s2, s4
	s_addc_u32 s3, s3, s5
	s_add_u32 s4, s2, s12
	s_addc_u32 s5, s3, 0
	s_add_u32 s2, s4, 0x8680000
	v_readlane_b32 s8, v254, 49
	s_addc_u32 s3, s5, 0
	v_readlane_b32 s9, v254, 50
	s_add_u32 s96, s4, 0xc680000
	v_and_b32_e32 v158, 15, v165
	v_cndmask_b32_e64 v0, 0, 1, s[8:9]
	s_addc_u32 s97, s5, 0
	v_cmp_ne_u32_e64 s[4:5], 1, v0
	s_andn2_b64 vcc, exec, s[8:9]
	v_bfe_u32 v159, v165, 1, 3
	s_waitcnt vmcnt(13)
	v_and_b32_e32 v122, 0xf0, v229
	v_lshlrev_b32_e32 v150, 4, v158
	v_writelane_b32 v254, s64, 23
	s_cbranch_vccnz .LBB0_1306
	v_readlane_b32 s14, v255, 25
	v_ashrrev_i32_e32 v116, 4, v165
	v_readlane_b32 s15, v255, 26
	s_add_u32 s8, s56, s14
	v_ashrrev_i32_e32 v117, 31, v116
	s_addc_u32 s9, s57, s15
	v_lshlrev_b64 v[114:115], 10, v[116:117]
	v_lshl_add_u64 v[2:3], s[8:9], 0, v[114:115]
	v_mov_b32_e32 v123, v1
	v_lshl_add_u64 v[2:3], v[2:3], 0, v[122:123]
	s_movk_i32 s10, 0x2000
	v_add_co_u32_e32 v4, vcc, s10, v2
	s_movk_i32 s11, 0x4000
	s_nop 0
	v_addc_co_u32_e32 v5, vcc, 0, v3, vcc
	global_load_dwordx4 v[106:109], v[4:5], off offset:-4096 nt
	global_load_dwordx4 v[102:105], v[4:5], off nt
	v_add_co_u32_e32 v4, vcc, s11, v2
	s_movk_i32 s12, 0x6000
	s_nop 0
	v_addc_co_u32_e32 v5, vcc, 0, v3, vcc
	global_load_dwordx4 v[98:101], v[4:5], off offset:-4096 nt
	global_load_dwordx4 v[94:97], v[4:5], off nt
	v_add_co_u32_e32 v4, vcc, s12, v2
	s_mov_b32 s8, 0x8000
	s_nop 0
	v_addc_co_u32_e32 v5, vcc, 0, v3, vcc
	global_load_dwordx4 v[82:85], v[4:5], off offset:-4096 nt
	global_load_dwordx4 v[62:65], v[4:5], off nt
	v_add_co_u32_e32 v4, vcc, s8, v2
	s_mov_b32 s8, 0xa000
	s_nop 0
	v_addc_co_u32_e32 v5, vcc, 0, v3, vcc
	global_load_dwordx4 v[54:57], v[4:5], off offset:-4096 nt
	global_load_dwordx4 v[30:33], v[4:5], off nt
	v_add_co_u32_e32 v4, vcc, s8, v2
	s_add_u32 s8, s54, s14
	s_nop 0
	v_addc_co_u32_e32 v5, vcc, 0, v3, vcc
	global_load_dwordx4 v[26:29], v[4:5], off offset:-4096 nt
	global_load_dwordx4 v[22:25], v[4:5], off nt
	v_add_co_u32_e32 v4, vcc, s45, v2
	s_addc_u32 s9, s55, s15
	s_nop 0
	v_addc_co_u32_e32 v5, vcc, 0, v3, vcc
	global_load_dwordx4 v[18:21], v[4:5], off offset:-4096 nt
	global_load_dwordx4 v[14:17], v[4:5], off nt
	v_add_co_u32_e32 v4, vcc, s47, v2
	v_lshl_add_u64 v[34:35], s[8:9], 0, v[114:115]
	s_nop 0
	v_addc_co_u32_e32 v5, vcc, 0, v3, vcc
	global_load_dwordx4 v[10:13], v[4:5], off offset:-4096 nt
	global_load_dwordx4 v[6:9], v[4:5], off nt
	v_add_co_u32_e32 v4, vcc, s62, v2
	v_lshl_add_u64 v[120:121], v[34:35], 0, v[122:123]
	s_nop 0
	v_addc_co_u32_e32 v5, vcc, 0, v3, vcc
	v_add_co_u32_e32 v34, vcc, s10, v120
	global_load_dwordx4 v[110:113], v[2:3], off nt
	s_nop 0
	global_load_dwordx4 v[2:5], v[4:5], off nt
	v_addc_co_u32_e32 v35, vcc, 0, v121, vcc
	global_load_dwordx4 v[90:93], v[120:121], off nt
	global_load_dwordx4 v[86:89], v[34:35], off offset:-4096 nt
	global_load_dwordx4 v[58:61], v[34:35], off nt
	v_add_co_u32_e32 v34, vcc, s11, v120
	s_movk_i32 s8, 0x7000
	s_nop 0
	v_addc_co_u32_e32 v35, vcc, 0, v121, vcc
	global_load_dwordx4 v[50:53], v[34:35], off offset:-4096 nt
	global_load_dwordx4 v[46:49], v[34:35], off nt
	v_add_co_u32_e32 v34, vcc, s12, v120
	v_mov_b32_e32 v151, v1
	s_nop 0
	v_addc_co_u32_e32 v35, vcc, 0, v121, vcc
	global_load_dwordx4 v[42:45], v[34:35], off offset:-4096 nt
	global_load_dwordx4 v[38:41], v[34:35], off nt
	v_add_co_u32_e32 v34, vcc, s8, v120
	s_add_u32 s8, s2, s14
	s_nop 0
	v_addc_co_u32_e32 v35, vcc, 0, v121, vcc
	global_load_dwordx4 v[34:37], v[34:35], off nt
	s_addc_u32 s9, s3, s15
	v_lshl_add_u64 v[118:119], s[8:9], 0, v[114:115]
	s_movk_i32 s8, 0xf000
	v_lshlrev_b32_e32 v117, 3, v165
	v_lshl_add_u64 v[124:125], v[118:119], 0, v[150:151]
	s_mov_b32 s9, -1
	v_and_b32_e32 v0, 8, v117
	v_lshl_add_u64 v[118:119], v[124:125], 0, s[8:9]
	v_lshl_or_b32 v0, v159, 10, v0
	v_add_lshl_u32 v123, v159, v116, 4
	s_movk_i32 s8, 0x70
	s_waitcnt lgkmcnt(0)
	v_and_or_b32 v0, v123, s8, v0
	v_add_u32_e32 v123, s33, v0
	v_cmp_lt_i32_e64 s[8:9], -1, v116
	s_waitcnt vmcnt(9)
	v_cvt_pk_bf16_f32 v126, v110, v111
	v_cvt_pk_bf16_f32 v127, v112, v113
	ds_write_b64 v123, v[126:127]
	s_and_saveexec_b64 s[10:11], s[8:9]
	s_cbranch_execz .LBB0_1243
	global_store_dwordx4 v[118:119], v[110:113], off

; #define LAS __attribute__((address_space(3)))
; __device__ __forceinline__ unsigned cvt_pk_bf16(float lo, float hi) { unsigned r; asm volatile("v_cvt_pk_bf16_f32 %0, %1, %2" : "=v"(r) : "v"(lo), "v"(hi)); return r; }
; #define LDS_WAIT() asm volatile("s_waitcnt lgkmcnt(0)" ::: "memory")
; template <int H> __device__ __forceinline__ void f32_k_commit(const F32Tile& T, LAS unsigned char* kb, int lane, float* kcopy, int skip) {
;     ...
;     for (int i = 8 * H; i < 8 * H + 8; ++i) { u32x2 w; w.x = cvt_pk_bf16(T.x[i][0], T.x[i][1]); w.y = cvt_pk_bf16(T.x[i][2], T.x[i][3]);
;         *(LAS u32x2*)(kb + ((i & 1) ? (keo ^ 64u) : keo) + 128 * (i >> 1)) = w;
;         if (kcopy && 4 * i + rl >= skip) *(f32x4*)(kc + (size_t)(4 * i) * 256) = T.x[i]; }
;     if (H == 1) LDS_WAIT();
; }
; __device__ __forceinline__ void f32_v_issue(F32Half& T, const float* vp, int lane, int h) {
;     const float* vl = vp + (size_t)(lane >> 4) * 256 + (lane & 15) * 4;
; #pragma unroll
;     for (int i = 0; i < 8; ++i) T.x[i] = *(const f32x4*)(vl + (size_t)(4 * (8 * h + i)) * 256);
; }
; __device__ __forceinline__ void f32_v_commit(const F32Half& T, LAS unsigned char* vb, int lane, float* vcopy, int skip, int h) {
;     const int pc = lane & 15, rl = lane >> 4;
;     LAS unsigned char* vd = vb + (pc >> 3) * 4096 + rl * 64 + (pc & 7) * 8; float* vc = vcopy + (size_t)rl * 256 + pc * 4;
; #pragma unroll
;     for (int i = 0; i < 8; ++i) { const int ri = 4 * (8 * h + i); u32x2 w; w.x = cvt_pk_bf16(T.x[i][0], T.x[i][1]); w.y = cvt_pk_bf16(T.x[i][2], T.x[i][3]);
;         *(LAS u32x2*)(vd + ri * 64) = w;
;         if (vcopy && ri + rl >= skip) *(f32x4*)(vc + (size_t)ri * 256) = T.x[i]; }
; }
.LBB0_1257:
	s_or_b64 exec, exec, s[24:25]
	s_nop 0
	v_add_co_u32_e32 v54, vcc, 0x8000, v120
	s_movk_i32 s24, 0xffdf
	s_nop 0
	v_addc_co_u32_e32 v55, vcc, 0, v121, vcc
	v_add_co_u32_e32 v56, vcc, 0x9000, v120
	v_cmp_lt_i32_e64 s[24:25], s24, v116
	s_nop 0
	v_addc_co_u32_e32 v57, vcc, 0, v121, vcc
	global_load_dwordx4 v[110:113], v[54:55], off nt
	global_load_dwordx4 v[106:109], v[56:57], off nt
	v_add_co_u32_e32 v54, vcc, 0xa000, v120
	s_nop 1
	v_addc_co_u32_e32 v55, vcc, 0, v121, vcc
	v_add_co_u32_e32 v56, vcc, 0xb000, v120
	s_nop 1
	v_addc_co_u32_e32 v57, vcc, 0, v121, vcc
	global_load_dwordx4 v[102:105], v[54:55], off nt
	global_load_dwordx4 v[98:101], v[56:57], off nt
	v_add_co_u32_e32 v54, vcc, 0xc000, v120
	s_nop 1
	v_addc_co_u32_e32 v55, vcc, 0, v121, vcc
	v_add_co_u32_e32 v56, vcc, 0xd000, v120
	s_nop 1
	v_addc_co_u32_e32 v57, vcc, 0, v121, vcc
	global_load_dwordx4 v[94:97], v[54:55], off nt
	global_load_dwordx4 v[82:85], v[56:57], off nt
	v_add_co_u32_e32 v54, vcc, 0xe000, v120
	s_nop 1
	v_addc_co_u32_e32 v55, vcc, 0, v121, vcc
	v_add_co_u32_e32 v56, vcc, 0xf000, v120
	s_nop 1
	v_addc_co_u32_e32 v57, vcc, 0, v121, vcc
	global_load_dwordx4 v[62:65], v[54:55], off nt
	s_nop 0
	global_load_dwordx4 v[54:57], v[56:57], off nt
	v_cvt_pk_bf16_f32 v120, v30, v31
	v_cvt_pk_bf16_f32 v121, v32, v33
	ds_write_b64 v123, v[120:121] offset:512
	s_and_saveexec_b64 s[26:27], s[24:25]
	s_cbranch_execz .LBB0_1259
	v_add_co_u32_e32 v120, vcc, 0x8000, v118
	s_nop 1
	v_addc_co_u32_e32 v121, vcc, 0, v119, vcc
	global_store_dwordx4 v[120:121], v[30:33], off

; #define LAS __attribute__((address_space(3)))
; __device__ __forceinline__ unsigned cvt_pk_bf16(float lo, float hi) { unsigned r; asm volatile("v_cvt_pk_bf16_f32 %0, %1, %2" : "=v"(r) : "v"(lo), "v"(hi)); return r; }
; #define LDS_WAIT() asm volatile("s_waitcnt lgkmcnt(0)" ::: "memory")
; __device__ __forceinline__ void f32_k_issue(F32Tile& T, const float* kp, int lane) {
;     const float* kl = kp + (size_t)(lane >> 4) * 256 + (lane & 15) * 4;
; #pragma unroll
;     for (int i = 0; i < 16; ++i) T.x[i] = *(const f32x4*)(kl + (size_t)(4 * i) * 256);
; }
; template <int H> __device__ __forceinline__ void f32_k_commit(const F32Tile& T, LAS unsigned char* kb, int lane, float* kcopy, int skip) {
;     const int pc = lane & 15, rl = lane >> 4, c = pc >> 1;
;     float* kc = kcopy + (size_t)rl * 256 + pc * 4;
;     const unsigned keo = (unsigned)(c * 1024 + (pc & 1) * 8 + ((rl + c) & 7) * 16);
;     if (H == 0) LDS_WAIT();
; #pragma unroll
;     for (int i = 8 * H; i < 8 * H + 8; ++i) { u32x2 w; w.x = cvt_pk_bf16(T.x[i][0], T.x[i][1]); w.y = cvt_pk_bf16(T.x[i][2], T.x[i][3]);
;         *(LAS u32x2*)(kb + ((i & 1) ? (keo ^ 64u) : keo) + 128 * (i >> 1)) = w;
;         if (kcopy && 4 * i + rl >= skip) *(f32x4*)(kc + (size_t)(4 * i) * 256) = T.x[i]; }
;     if (H == 1) LDS_WAIT();
; }
; __device__ __forceinline__ void f32_v_issue(F32Half& T, const float* vp, int lane, int h) {
;     const float* vl = vp + (size_t)(lane >> 4) * 256 + (lane & 15) * 4;
; #pragma unroll
;     for (int i = 0; i < 8; ++i) T.x[i] = *(const f32x4*)(vl + (size_t)(4 * (8 * h + i)) * 256);
; }
; __device__ __forceinline__ void attn_decode_unit(const Params& P, const Ctx& C, int sg) {
;     ...
;     float m_s = -1e30f, l_s = 0.f; f32x16 os0 = F16Z, os1 = F16Z;
;     if (wave == 0) {
;         F32_TILE_STEP(sk, sv, ck - 4 * 256, cv - 4 * 256, 4, 0, qi + 1, 512 + qi, true, m_w, l_w, ow0, ow1);
.LBB0_1307:
	v_lshlrev_b32_e32 v231, 6, v227
	s_lshl_b32 s64, s53, 6
	s_and_b64 vcc, exec, s[6:7]
	s_waitcnt lgkmcnt(0)
	s_barrier
	s_cbranch_vccnz .LBB0_1373
	v_ashrrev_i32_e32 v152, 4, v165
	v_ashrrev_i32_e32 v153, 31, v152
	v_lshlrev_b64 v[82:83], 10, v[152:153]
	v_lshl_add_u64 v[34:35], s[56:57], 0, v[82:83]
	v_mov_b32_e32 v123, v1
	v_lshl_add_u64 v[34:35], v[34:35], 0, v[122:123]
	v_add_co_u32_e32 v36, vcc, 0x1000, v34
	v_lshl_add_u64 v[86:87], s[54:55], 0, v[82:83]
	s_nop 0
	v_addc_co_u32_e32 v37, vcc, 0, v35, vcc
	global_load_dwordx4 v[146:149], v[34:35], off nt
	global_load_dwordx4 v[142:145], v[36:37], off nt
	v_add_co_u32_e32 v36, vcc, 0x2000, v34
	v_lshl_add_u64 v[154:155], v[86:87], 0, v[122:123]
	s_nop 0
	v_addc_co_u32_e32 v37, vcc, 0, v35, vcc
	v_add_co_u32_e32 v38, vcc, 0x3000, v34
	s_movk_i32 s6, 0x2000
	s_nop 0
	v_addc_co_u32_e32 v39, vcc, 0, v35, vcc
	global_load_dwordx4 v[138:141], v[36:37], off nt
	global_load_dwordx4 v[130:133], v[38:39], off nt
	v_add_co_u32_e32 v36, vcc, 0x4000, v34
	v_lshl_add_u64 v[156:157], s[2:3], 0, v[82:83]
	s_nop 0
	v_addc_co_u32_e32 v37, vcc, 0, v35, vcc
	v_add_co_u32_e32 v38, vcc, 0x5000, v34
	v_mov_b32_e32 v151, v1
	s_nop 0
	v_addc_co_u32_e32 v39, vcc, 0, v35, vcc
	global_load_dwordx4 v[126:129], v[36:37], off nt
	global_load_dwordx4 v[118:121], v[38:39], off nt
	v_add_co_u32_e32 v36, vcc, 0x6000, v34
	s_movk_i32 s2, 0xf000
	s_nop 0
	v_addc_co_u32_e32 v37, vcc, 0, v35, vcc
	v_add_co_u32_e32 v38, vcc, 0x7000, v34
	v_lshlrev_b32_e32 v160, 3, v165
	s_nop 0
	v_addc_co_u32_e32 v39, vcc, 0, v35, vcc
	global_load_dwordx4 v[114:117], v[36:37], off nt
	global_load_dwordx4 v[106:109], v[38:39], off nt
	v_add_co_u32_e32 v36, vcc, 0x8000, v34
	v_lshl_add_u64 v[156:157], v[156:157], 0, v[150:151]
	s_nop 0
	v_addc_co_u32_e32 v37, vcc, 0, v35, vcc
	v_add_co_u32_e32 v38, vcc, 0x9000, v34
	s_mov_b32 s3, -1
	s_nop 0
	v_addc_co_u32_e32 v39, vcc, 0, v35, vcc
	global_load_dwordx4 v[62:65], v[36:37], off nt
	global_load_dwordx4 v[58:61], v[38:39], off nt
	v_add_co_u32_e32 v36, vcc, 0xa000, v34
	v_and_b32_e32 v0, 8, v160
	s_nop 0
	v_addc_co_u32_e32 v37, vcc, 0, v35, vcc
	v_add_co_u32_e32 v38, vcc, 0xb000, v34
	v_lshl_add_u64 v[150:151], v[156:157], 0, s[2:3]
	s_nop 0
	v_addc_co_u32_e32 v39, vcc, 0, v35, vcc
	global_load_dwordx4 v[54:57], v[36:37], off nt
	global_load_dwordx4 v[50:53], v[38:39], off nt
	v_add_co_u32_e32 v36, vcc, 0xc000, v34
	v_lshl_or_b32 v0, v159, 10, v0
	s_nop 0
	v_addc_co_u32_e32 v37, vcc, 0, v35, vcc
	v_add_co_u32_e32 v38, vcc, 0xd000, v34
	v_add_lshl_u32 v153, v159, v152, 4
	s_nop 0
	v_addc_co_u32_e32 v39, vcc, 0, v35, vcc
	global_load_dwordx4 v[46:49], v[36:37], off nt
	global_load_dwordx4 v[42:45], v[38:39], off nt
	v_add_co_u32_e32 v36, vcc, 0xe000, v34
	s_movk_i32 s2, 0x70
	s_nop 0
	v_addc_co_u32_e32 v37, vcc, 0, v35, vcc
	v_add_co_u32_e32 v34, vcc, 0xf000, v34
	v_and_or_b32 v0, v153, s2, v0
	s_nop 0
	v_addc_co_u32_e32 v35, vcc, 0, v35, vcc
	v_add_co_u32_e32 v86, vcc, s6, v154
	s_movk_i32 s6, 0x4000
	s_nop 0
	v_addc_co_u32_e32 v87, vcc, 0, v155, vcc
	v_add_co_u32_e32 v88, vcc, s6, v154
	s_movk_i32 s6, 0x6000
	s_nop 0
	v_addc_co_u32_e32 v89, vcc, 0, v155, vcc
	v_add_co_u32_e32 v90, vcc, s6, v154
	s_movk_i32 s6, 0x7000
	s_nop 0
	v_addc_co_u32_e32 v91, vcc, 0, v155, vcc
	global_load_dwordx4 v[38:41], v[36:37], off nt
	s_nop 0
	global_load_dwordx4 v[34:37], v[34:35], off nt
	v_add_u32_e32 v153, s33, v0
	global_load_dwordx4 v[122:125], v[154:155], off nt
	global_load_dwordx4 v[110:113], v[86:87], off nt
	global_load_dwordx4 v[102:105], v[88:89], off offset:-4096 nt
	global_load_dwordx4 v[98:101], v[88:89], off nt
	global_load_dwordx4 v[94:97], v[90:91], off offset:-4096 nt
	s_nop 0
	global_load_dwordx4 v[90:93], v[90:91], off nt
	v_add_co_u32_e32 v88, vcc, s6, v154
	v_cmp_lt_i32_e64 s[6:7], 3, v152
	s_nop 0
	v_addc_co_u32_e32 v89, vcc, 0, v155, vcc
	global_load_dwordx4 v[134:137], v[86:87], off offset:-4096 nt
	s_nop 0
	global_load_dwordx4 v[86:89], v[88:89], off nt
	s_waitcnt lgkmcnt(0)
	s_waitcnt vmcnt(23)
	v_cvt_pk_bf16_f32 v168, v146, v147
	v_cvt_pk_bf16_f32 v169, v148, v149
	ds_write_b64 v153, v[168:169]
	s_and_saveexec_b64 s[2:3], s[6:7]
	s_cbranch_execz .LBB0_1310
	global_store_dwordx4 v[150:151], v[146:149], off

; #define LAS __attribute__((address_space(3)))
; __device__ __forceinline__ unsigned cvt_pk_bf16(float lo, float hi) { unsigned r; asm volatile("v_cvt_pk_bf16_f32 %0, %1, %2" : "=v"(r) : "v"(lo), "v"(hi)); return r; }
; __device__ __forceinline__ void f32_v_issue(F32Half& T, const float* vp, int lane, int h) {
;     const float* vl = vp + (size_t)(lane >> 4) * 256 + (lane & 15) * 4;
; #pragma unroll
;     for (int i = 0; i < 8; ++i) T.x[i] = *(const f32x4*)(vl + (size_t)(4 * (8 * h + i)) * 256);
; }
; __device__ __forceinline__ void f32_v_commit(const F32Half& T, LAS unsigned char* vb, int lane, float* vcopy, int skip, int h) {
;     const int pc = lane & 15, rl = lane >> 4;
;     LAS unsigned char* vd = vb + (pc >> 3) * 4096 + rl * 64 + (pc & 7) * 8; float* vc = vcopy + (size_t)rl * 256 + pc * 4;
; #pragma unroll
;     for (int i = 0; i < 8; ++i) { const int ri = 4 * (8 * h + i); u32x2 w; w.x = cvt_pk_bf16(T.x[i][0], T.x[i][1]); w.y = cvt_pk_bf16(T.x[i][2], T.x[i][3]);
;         *(LAS u32x2*)(vd + ri * 64) = w;
;         if (vcopy && ri + rl >= skip) *(f32x4*)(vc + (size_t)ri * 256) = T.x[i]; }
; }
.LBB0_1324:
	s_or_b64 exec, exec, s[2:3]
	s_nop 0
	v_add_co_u32_e32 v106, vcc, 0x8000, v154
	s_movk_i32 s2, 0xffe3
	s_nop 0
	v_addc_co_u32_e32 v107, vcc, 0, v155, vcc
	v_add_co_u32_e32 v108, vcc, 0x9000, v154
	v_cmp_lt_i32_e64 s[22:23], s2, v152
	s_nop 0
	v_addc_co_u32_e32 v109, vcc, 0, v155, vcc
	global_load_dwordx4 v[146:149], v[106:107], off nt
	global_load_dwordx4 v[142:145], v[108:109], off nt
	v_add_co_u32_e32 v106, vcc, 0xa000, v154
	s_nop 1
	v_addc_co_u32_e32 v107, vcc, 0, v155, vcc
	v_add_co_u32_e32 v108, vcc, 0xb000, v154
	s_nop 1
	v_addc_co_u32_e32 v109, vcc, 0, v155, vcc
	global_load_dwordx4 v[138:141], v[106:107], off nt
	global_load_dwordx4 v[130:133], v[108:109], off nt
	v_add_co_u32_e32 v106, vcc, 0xc000, v154
	s_nop 1
	v_addc_co_u32_e32 v107, vcc, 0, v155, vcc
	v_add_co_u32_e32 v108, vcc, 0xd000, v154
	s_nop 1
	v_addc_co_u32_e32 v109, vcc, 0, v155, vcc
	global_load_dwordx4 v[126:129], v[106:107], off nt
	global_load_dwordx4 v[118:121], v[108:109], off nt
	v_add_co_u32_e32 v106, vcc, 0xe000, v154
	s_nop 1
	v_addc_co_u32_e32 v107, vcc, 0, v155, vcc
	v_add_co_u32_e32 v108, vcc, 0xf000, v154
	s_nop 1
	v_addc_co_u32_e32 v109, vcc, 0, v155, vcc
	global_load_dwordx4 v[114:117], v[106:107], off nt
	s_nop 0
	global_load_dwordx4 v[106:109], v[108:109], off nt
	s_waitcnt vmcnt(23)
	v_cvt_pk_bf16_f32 v154, v62, v63
	v_cvt_pk_bf16_f32 v155, v64, v65
	ds_write_b64 v153, v[154:155] offset:512
	s_and_saveexec_b64 s[2:3], s[22:23]
	s_cbranch_execz .LBB0_1326
	v_add_co_u32_e32 v154, vcc, 0x8000, v150
	s_nop 1
	v_addc_co_u32_e32 v155, vcc, 0, v151, vcc
	global_store_dwordx4 v[154:155], v[62:65], off

; #define LAS __attribute__((address_space(3)))
; __device__ __forceinline__ unsigned cvt_pk_bf16(float lo, float hi) { unsigned r; asm volatile("v_cvt_pk_bf16_f32 %0, %1, %2" : "=v"(r) : "v"(lo), "v"(hi)); return r; }
; __device__ __forceinline__ float fast_exp2(float x) { return __builtin_amdgcn_exp2f(x); }
; #define MFMA32(a, b, c) __builtin_amdgcn_mfma_f32_32x32x16_bf16(a, b, c, 0, 0, 0)
; __device__ __forceinline__ s16x4 tr16(const LAS unsigned char* p) { return __builtin_bit_cast(s16x4, __builtin_amdgcn_ds_read_tr16_b64_v4i16((LAS v4i16_t*)p)); }
; __device__ __forceinline__ bf16x8 cat8(s16x4 lo, s16x4 hi) { return (bf16x8){lo[0], lo[1], lo[2], lo[3], hi[0], hi[1], hi[2], hi[3]}; }
; __device__ __forceinline__ void softmax_step(f32x16& s0, f32x16& s1, float& m_run, float& l_run, f32x16& o0, f32x16& o1) {
;     const float mn = fmaxf(m_run, tile_max(s0, s1)); const float alpha = fast_exp2(m_run - mn); m_run = mn;
;     float sum = 0.f;
; #pragma unroll
;     for (int r = 0; r < 16; ++r) { s0[r] = fast_exp2(s0[r] - mn); s1[r] = fast_exp2(s1[r] - mn); sum += s0[r] + s1[r]; }
;     l_run = l_run * alpha + sum;
;     o0 = o0 * alpha; o1 = o1 * alpha;
; }
; __device__ __forceinline__ bf16x8 pack8(const f32x16& p, int o) {
;     u32x4 w; w.x = cvt_pk_bf16(p[o], p[o + 1]); w.y = cvt_pk_bf16(p[o + 2], p[o + 3]); w.z = cvt_pk_bf16(p[o + 4], p[o + 5]); w.w = cvt_pk_bf16(p[o + 6], p[o + 7]);
;     return __builtin_bit_cast(bf16x8, w);
; }
; __device__ __forceinline__ void pv_tile(const LAS unsigned char* vb, const f32x16& p0, const f32x16& p1, f32x16& o0, f32x16& o1, int lane, int hi) {
;     const LAS unsigned char* vp = vb + ((lane >> 4) & 1) * 32 + (lane & 3) * 8 + (4 * hi + ((lane & 15) >> 2)) * 64;
; #pragma unroll
;     for (int kk = 0; kk < 4; ++kk) {
;         const bf16x8 pf = (kk < 2) ? pack8(p0, 8 * kk) : pack8(p1, 8 * (kk - 2));
;         const bf16x8 v0 = cat8(tr16(vp + kk * 1024), tr16(vp + kk * 1024 + 512));
;         const bf16x8 v1 = cat8(tr16(vp + 4096 + kk * 1024), tr16(vp + 4096 + kk * 1024 + 512));
;         o0 = MFMA32(v0, pf, o0); o1 = MFMA32(v1, pf, o1);
;     }
; }
.LBB0_1372:
	s_or_b64 exec, exec, s[2:3]
	v_max3_f32 v82, v84, v46, v47
	v_sub_f32_e32 v0, v173, v82
	v_exp_f32_e32 v34, v0
	v_sub_f32_e32 v0, v177, v82
	v_exp_f32_e32 v46, v0
	v_sub_f32_e32 v35, v175, v82
	v_sub_f32_e32 v36, v176, v82
	v_exp_f32_e32 v35, v35
	v_exp_f32_e32 v47, v36
	v_add_f32_e32 v0, v34, v46
	v_add_f32_e32 v0, 0, v0
	v_sub_f32_e32 v37, v174, v82
	v_add_f32_e32 v36, v35, v47
	v_add_f32_e32 v0, v36, v0
	v_sub_f32_e32 v36, v172, v82
	v_exp_f32_e32 v36, v36
	v_exp_f32_e32 v48, v37
	v_sub_f32_e32 v49, v171, v82
	v_exp_f32_e32 v49, v49
	v_sub_f32_e32 v59, v169, v82
	v_add_f32_e32 v37, v36, v48
	v_add_f32_e32 v0, v37, v0
	v_sub_f32_e32 v37, v170, v82
	v_exp_f32_e32 v37, v37
	v_exp_f32_e32 v59, v59
	v_sub_f32_e32 v61, v161, v82
	v_exp_f32_e32 v61, v61
	v_add_f32_e32 v58, v37, v49
	v_add_f32_e32 v0, v58, v0
	v_sub_f32_e32 v58, v168, v82
	v_exp_f32_e32 v58, v58
	v_sub_f32_e32 v63, v157, v82
	v_exp_f32_e32 v63, v63
	v_sub_f32_e32 v65, v155, v82
	v_add_f32_e32 v60, v58, v59
	v_add_f32_e32 v0, v60, v0
	v_sub_f32_e32 v60, v159, v82
	v_exp_f32_e32 v60, v60
	v_exp_f32_e32 v65, v65
	v_sub_f32_e32 v56, v56, v82
	v_sub_f32_e32 v57, v57, v82
	v_add_f32_e32 v62, v60, v61
	v_add_f32_e32 v0, v62, v0
	v_sub_f32_e32 v62, v156, v82
	v_exp_f32_e32 v62, v62
	v_exp_f32_e32 v56, v56
	v_exp_f32_e32 v57, v57
	v_sub_f32_e32 v54, v54, v82
	v_add_f32_e32 v64, v62, v63
	v_add_f32_e32 v0, v64, v0
	v_sub_f32_e32 v64, v154, v82
	v_exp_f32_e32 v64, v64
	v_sub_f32_e32 v55, v55, v82
	v_exp_f32_e32 v54, v54
	v_exp_f32_e32 v55, v55
	v_sub_f32_e32 v52, v52, v82
	v_sub_f32_e32 v53, v53, v82
	v_exp_f32_e32 v52, v52
	v_exp_f32_e32 v53, v53
	v_sub_f32_e32 v50, v50, v82
	v_sub_f32_e32 v51, v51, v82
	v_sub_f32_e32 v44, v44, v82
	v_add_f32_e32 v83, v64, v65
	v_exp_f32_e32 v50, v50
	v_exp_f32_e32 v51, v51
	v_exp_f32_e32 v87, v44
	v_sub_f32_e32 v44, v45, v82
	v_sub_f32_e32 v42, v42, v82
	v_add_f32_e32 v0, v83, v0
	v_add_f32_e32 v83, v56, v57
	v_exp_f32_e32 v88, v44
	v_exp_f32_e32 v89, v42
	v_sub_f32_e32 v42, v43, v82
	v_sub_f32_e32 v38, v38, v82
	v_add_f32_e32 v0, v83, v0
	v_add_f32_e32 v83, v54, v55
	v_exp_f32_e32 v90, v42
	v_exp_f32_e32 v91, v38
	v_sub_f32_e32 v38, v40, v82
	v_add_f32_e32 v0, v83, v0
	v_add_f32_e32 v83, v52, v53
	v_exp_f32_e32 v92, v38
	v_add_f32_e32 v0, v83, v0
	v_add_f32_e32 v83, v50, v51
	v_add_f32_e32 v0, v83, v0
	v_add_f32_e32 v44, v87, v88
	v_add_f32_e32 v0, v44, v0
	v_add_f32_e32 v42, v89, v90
	v_add_f32_e32 v0, v42, v0
	v_add_f32_e32 v38, v91, v92
	v_add_f32_e32 v0, v38, v0
	v_sub_f32_e32 v38, v39, v82
	v_exp_f32_e32 v93, v38
	v_sub_f32_e32 v38, v41, v82
	v_exp_f32_e32 v94, v38
	v_and_b32_e32 v39, 0xc0, v229
	s_waitcnt lgkmcnt(0)
	v_cvt_pk_bf16_f32 v34, v34, v35
	v_add_f32_e32 v38, v93, v94
	v_add_f32_e32 v86, v38, v0
	v_sub_f32_e32 v0, v84, v82
	v_exp_f32_e32 v0, v0
	v_and_b32_e32 v38, 24, v160
	v_cvt_pk_bf16_f32 v35, v36, v37
	v_cvt_pk_bf16_f32 v36, v58, v60
	v_fmac_f32_e32 v86, v85, v0
	v_pk_mul_f32 v[32:33], v[32:33], v[0:1] op_sel_hi:[1,0]
	v_pk_mul_f32 v[30:31], v[30:31], v[0:1] op_sel_hi:[1,0]
	v_pk_mul_f32 v[28:29], v[28:29], v[0:1] op_sel_hi:[1,0]
	v_pk_mul_f32 v[26:27], v[26:27], v[0:1] op_sel_hi:[1,0]
	v_pk_mul_f32 v[24:25], v[24:25], v[0:1] op_sel_hi:[1,0]
	v_pk_mul_f32 v[22:23], v[22:23], v[0:1] op_sel_hi:[1,0]
	v_pk_mul_f32 v[20:21], v[20:21], v[0:1] op_sel_hi:[1,0]
	v_pk_mul_f32 v[18:19], v[18:19], v[0:1] op_sel_hi:[1,0]
	v_pk_mul_f32 v[16:17], v[16:17], v[0:1] op_sel_hi:[1,0]
	v_pk_mul_f32 v[14:15], v[14:15], v[0:1] op_sel_hi:[1,0]
	v_pk_mul_f32 v[12:13], v[12:13], v[0:1] op_sel_hi:[1,0]
	v_pk_mul_f32 v[10:11], v[10:11], v[0:1] op_sel_hi:[1,0]
	v_pk_mul_f32 v[8:9], v[8:9], v[0:1] op_sel_hi:[1,0]
	v_pk_mul_f32 v[6:7], v[6:7], v[0:1] op_sel_hi:[1,0]
	v_pk_mul_f32 v[4:5], v[4:5], v[0:1] op_sel_hi:[1,0]
	v_pk_mul_f32 v[2:3], v[2:3], v[0:1] op_sel_hi:[1,0]
	v_lshlrev_b32_e32 v0, 1, v165
	v_and_b32_e32 v0, 32, v0
	v_add3_u32 v0, s33, v0, v38
	v_lshlrev_b32_e32 v38, 8, v166
	v_add3_u32 v83, v0, v38, v39
	v_cvt_pk_bf16_f32 v37, v62, v64
	ds_read_b64_tr_b16 v[38:39], v83 offset:8192
	ds_read_b64_tr_b16 v[40:41], v83 offset:8704
	ds_read_b64_tr_b16 v[42:43], v83 offset:12288
	ds_read_b64_tr_b16 v[44:45], v83 offset:12800
	s_waitcnt lgkmcnt(2)
	v_mfma_f32_32x32x16_bf16 v[18:33], v[38:41], v[34:37], v[18:33]
	s_ashr_i32 s53, s52, 31
	s_lshl_b64 s[2:3], s[52:53], 13
	s_add_u32 s6, s84, s2
	s_addc_u32 s7, s85, s3
	s_add_u32 s2, s6, 0x30300000
	s_addc_u32 s3, s7, 0
	s_waitcnt lgkmcnt(0)
	v_mfma_f32_32x32x16_bf16 v[2:17], v[42:45], v[34:37], v[2:17]
	v_cvt_pk_bf16_f32 v34, v56, v54
	v_cvt_pk_bf16_f32 v35, v52, v50
	v_cvt_pk_bf16_f32 v36, v87, v89
	v_cvt_pk_bf16_f32 v37, v91, v93
	ds_read_b64_tr_b16 v[38:39], v83 offset:9216
	ds_read_b64_tr_b16 v[40:41], v83 offset:9728
	ds_read_b64_tr_b16 v[42:43], v83 offset:13312
	ds_read_b64_tr_b16 v[44:45], v83 offset:13824
	s_waitcnt lgkmcnt(2)
	v_mfma_f32_32x32x16_bf16 v[18:33], v[38:41], v[34:37], v[18:33]
	s_waitcnt lgkmcnt(0)
	v_mfma_f32_32x32x16_bf16 v[2:17], v[42:45], v[34:37], v[2:17]
	v_cvt_pk_bf16_f32 v34, v46, v47
	v_cvt_pk_bf16_f32 v35, v48, v49
	v_cvt_pk_bf16_f32 v36, v59, v61
	v_cvt_pk_bf16_f32 v37, v63, v65
	ds_read_b64_tr_b16 v[38:39], v83 offset:10240
	ds_read_b64_tr_b16 v[40:41], v83 offset:10752
	ds_read_b64_tr_b16 v[42:43], v83 offset:14336
	ds_read_b64_tr_b16 v[44:45], v83 offset:14848
	s_waitcnt lgkmcnt(2)
	v_mfma_f32_32x32x16_bf16 v[18:33], v[38:41], v[34:37], v[18:33]
	s_waitcnt lgkmcnt(0)
; #define LAS __attribute__((address_space(3)))
; #define LDS_WAIT() asm volatile("s_waitcnt lgkmcnt(0)" ::: "memory")
; __device__ __forceinline__ void wave_tile_load(const bf16_t* kt, const bf16_t* vt, LAS unsigned char* kb, LAS unsigned char* vb, int lane) {
;     LDS_WAIT();
;     { u32x4 kr[8];
; #pragma unroll
;       for (int c = 0; c < 8; ++c) kr[c] = *(const u32x4*)((const unsigned char*)kt + lane * 128 + c * 16);
; #pragma unroll
;       for (int c = 0; c < 8; ++c) *(LAS u32x4*)(kb + c * 1024 + lane * 16) = kr[c]; }
;     __builtin_amdgcn_sched_barrier(0);
;     { u32x4 vr[8];
; #pragma unroll
;       for (int c = 0; c < 8; ++c) vr[c] = *(const u32x4*)((const unsigned char*)vt + (16 * (c & 3) + (lane >> 2)) * 128 + (c >> 2) * 64 + (lane & 3) * 16);
; #pragma unroll
;       for (int c = 0; c < 8; ++c) *(LAS u32x4*)(vb + c * 1024 + lane * 16) = vr[c]; }
;     LDS_WAIT();
; }
; __device__ __forceinline__ void attn_decode_unit(const Params& P, const Ctx& C, int sg) {
;     ...
;         wave_tile_load((const bf16_t*)(ws + WS_CWK) + (size_t)sg * 4096, (const bf16_t*)(ws + WS_CWV) + (size_t)sg * 4096, KB, VB, lane);
;         qk_tile(KB, qr, s0, s1, r32, hi); mask_tile(s0, s1, 512, qi + 1, 512 + qi, true, hi);
	v_mfma_f32_32x32x16_bf16 v[2:17], v[42:45], v[34:37], v[2:17]
	v_cvt_pk_bf16_f32 v34, v57, v55
	v_cvt_pk_bf16_f32 v35, v53, v51
	v_cvt_pk_bf16_f32 v36, v88, v90
	v_cvt_pk_bf16_f32 v37, v92, v94
	ds_read_b64_tr_b16 v[38:39], v83 offset:11264
	ds_read_b64_tr_b16 v[40:41], v83 offset:11776
	ds_read_b64_tr_b16 v[42:43], v83 offset:15360
	ds_read_b64_tr_b16 v[44:45], v83 offset:15872
	s_waitcnt lgkmcnt(0)
	s_waitcnt lgkmcnt(2)
	v_mfma_f32_32x32x16_bf16 v[18:33], v[38:41], v[34:37], v[18:33]
	s_waitcnt lgkmcnt(0)
	v_mfma_f32_32x32x16_bf16 v[2:17], v[42:45], v[34:37], v[2:17]
	v_lshlrev_b32_e32 v34, 7, v165
	v_ashrrev_i32_e32 v35, 31, v34
	v_lshl_add_u64 v[34:35], s[6:7], 0, v[34:35]
	s_mov_b64 s[6:7], 0x2de00000
	v_lshl_add_u64 v[62:63], v[34:35], 0, s[6:7]
	s_mov_b32 s6, 0x2de00000
	v_add_co_u32_e32 v34, vcc, s6, v34
	s_nop 1
	v_addc_co_u32_e32 v35, vcc, 0, v35, vcc
	global_load_dwordx4 v[34:37], v[34:35], off nt
	s_nop 0
	global_load_dwordx4 v[38:41], v[62:63], off offset:48 nt
	global_load_dwordx4 v[42:45], v[62:63], off offset:32 nt
	global_load_dwordx4 v[46:49], v[62:63], off offset:16 nt
	global_load_dwordx4 v[50:53], v[62:63], off offset:112 nt
	global_load_dwordx4 v[54:57], v[62:63], off offset:96 nt
	global_load_dwordx4 v[58:61], v[62:63], off offset:80 nt
	s_nop 0
	global_load_dwordx4 v[62:65], v[62:63], off offset:64 nt
	s_waitcnt vmcnt(7)
	ds_write_b128 v230, v[34:37]
	s_waitcnt vmcnt(4)
	ds_write_b128 v230, v[46:49] offset:1024
	ds_write_b128 v230, v[42:45] offset:2048
	ds_write_b128 v230, v[38:41] offset:3072
	s_waitcnt vmcnt(0)
	ds_write_b128 v230, v[62:65] offset:4096
	ds_write_b128 v230, v[58:61] offset:5120
	ds_write_b128 v230, v[54:57] offset:6144
	ds_write_b128 v230, v[50:53] offset:7168
	v_lshlrev_b32_e32 v34, 5, v165
	v_and_b32_e32 v46, 0xffffff80, v34
	v_ashrrev_i32_e32 v47, 31, v46
	v_lshl_add_u64 v[34:35], s[2:3], 0, v[46:47]
	v_add_u32_e32 v42, 0x1000, v46
	v_add_u32_e32 v46, 0x1800, v46
	v_ashrrev_i32_e32 v43, 31, v42
	v_ashrrev_i32_e32 v47, 31, v46
	v_and_b32_e32 v0, 48, v229
	v_lshl_add_u64 v[42:43], s[2:3], 0, v[42:43]
	v_lshl_add_u64 v[46:47], s[2:3], 0, v[46:47]
	v_lshl_add_u64 v[54:55], v[34:35], 0, v[0:1]
	v_lshl_add_u64 v[58:59], v[42:43], 0, v[0:1]
	v_lshl_add_u64 v[62:63], v[46:47], 0, v[0:1]
	global_load_dwordx4 v[34:37], v[54:55], off nt
	global_load_dwordx4 v[38:41], v[54:55], off offset:2048 nt
	global_load_dwordx4 v[42:45], v[58:59], off nt
	global_load_dwordx4 v[46:49], v[62:63], off nt
	global_load_dwordx4 v[50:53], v[54:55], off offset:64 nt
	s_nop 0
	global_load_dwordx4 v[54:57], v[54:55], off offset:2112 nt
	s_nop 0
	global_load_dwordx4 v[58:61], v[58:59], off offset:64 nt
	s_nop 0
	global_load_dwordx4 v[62:65], v[62:63], off offset:64 nt
	v_add_u32_e32 v0, v151, v153
	v_cmp_le_i32_e64 s[6:7], v164, v167
	s_waitcnt vmcnt(7)
	ds_write_b128 v230, v[34:37] offset:8192
	s_waitcnt vmcnt(6)
	ds_write_b128 v230, v[38:41] offset:9216
	s_waitcnt vmcnt(5)
	ds_write_b128 v230, v[42:45] offset:10240
	s_waitcnt vmcnt(4)
	ds_write_b128 v230, v[46:49] offset:11264
	s_waitcnt vmcnt(3)
	ds_write_b128 v230, v[50:53] offset:12288
	s_waitcnt vmcnt(2)
	ds_write_b128 v230, v[54:57] offset:13312
	s_waitcnt vmcnt(1)
	ds_write_b128 v230, v[58:61] offset:14336
	s_waitcnt vmcnt(0)
	ds_write_b128 v230, v[62:65] offset:15360
	s_waitcnt lgkmcnt(0)
	ds_read_b128 v[34:37], v0
	ds_read_b128 v[38:41], v0 offset:512
	s_waitcnt lgkmcnt(1)
	v_mfma_f32_32x32x16_bf16 v[50:65], v[34:37], v[74:77], 0
	ds_read_b128 v[88:91], v0 offset:2048
	ds_read_b128 v[92:95], v0 offset:2560
	s_waitcnt lgkmcnt(2)
	v_mfma_f32_32x32x16_bf16 v[34:49], v[38:41], v[74:77], 0
	s_waitcnt lgkmcnt(1)
	v_mfma_f32_32x32x16_bf16 v[50:65], v[88:91], v[66:69], v[50:65]
	s_waitcnt lgkmcnt(0)
	v_mfma_f32_32x32x16_bf16 v[34:49], v[92:95], v[66:69], v[34:49]
	ds_read_b128 v[88:91], v0 offset:4096
	ds_read_b128 v[92:95], v0 offset:4608
	s_waitcnt lgkmcnt(1)
	v_mfma_f32_32x32x16_bf16 v[50:65], v[88:91], v[70:73], v[50:65]
	s_waitcnt lgkmcnt(0)
	v_mfma_f32_32x32x16_bf16 v[34:49], v[92:95], v[70:73], v[34:49]
	ds_read_b128 v[88:91], v0 offset:6144
	ds_read_b128 v[92:95], v0 offset:6656
	v_add_u32_e32 v0, 0x200, v164
	v_cmp_gt_i32_e32 vcc, v0, v167
	s_and_b64 vcc, s[6:7], vcc
	s_waitcnt lgkmcnt(1)
	v_mfma_f32_32x32x16_bf16 v[50:65], v[88:91], v[78:81], v[50:65]
	s_waitcnt lgkmcnt(0)
; __device__ __forceinline__ int crow(int r, int hi) { return (r & 3) + 8 * (r >> 2) + 4 * hi; }
; __device__ __forceinline__ void mask_tile(f32x16& s0, f32x16& s1, int key0, int klo, int khi, bool en, int hi) {
; #pragma unroll
;     for (int r = 0; r < 16; ++r) { const int k = key0 + crow(r, hi);
;         if (!(en && k >= klo && k <= khi)) s0[r] = NEG_INF;
;         if (!(en && k + 32 >= klo && k + 32 <= khi)) s1[r] = NEG_INF; }
; }
; __device__ __forceinline__ float half_swap_max(float m) { auto rr = __builtin_amdgcn_permlane32_swap(__float_as_uint(m), __float_as_uint(m), false, false); return fmaxf(__uint_as_float(rr[0]), __uint_as_float(rr[1])); }
; __device__ __forceinline__ float half_swap_sum(float m) { auto rr = __builtin_amdgcn_permlane32_swap(__float_as_uint(m), __float_as_uint(m), false, false); return __uint_as_float(rr[0]) + __uint_as_float(rr[1]); }
; __device__ __forceinline__ float tile_max(const f32x16& s0, const f32x16& s1) {
;     float m = fmaxf(s0[0], s1[0]);
; #pragma unroll
;     for (int r = 1; r < 16; ++r) m = fmaxf(m, fmaxf(s0[r], s1[r]));
;     return half_swap_max(m);
; }
	v_mfma_f32_32x32x16_bf16 v[34:49], v[92:95], v[78:81], v[34:49]
	s_nop 9
	v_cndmask_b32_e32 v0, v219, v50, vcc
	v_add_u32_e32 v50, 0x220, v164
	v_cmp_le_i32_e32 vcc, v50, v167
	v_cmp_gt_i32_e64 s[6:7], v50, v150
	s_or_b64 vcc, vcc, s[6:7]
	v_add_u32_e32 v50, 0x201, v164
	v_cmp_le_i32_e64 s[6:7], v50, v150
	v_cndmask_b32_e32 v34, v34, v219, vcc
	v_cmp_gt_i32_e32 vcc, v50, v167
	s_and_b64 vcc, vcc, s[6:7]
	s_nop 0
	v_cndmask_b32_e32 v50, v219, v51, vcc
	v_add_u32_e32 v51, 0x221, v164
	v_cmp_le_i32_e32 vcc, v51, v167
	v_cmp_gt_i32_e64 s[6:7], v51, v150
	s_or_b64 vcc, vcc, s[6:7]
	v_add_u32_e32 v51, 0x202, v164
	v_cndmask_b32_e32 v35, v35, v219, vcc
	v_cmp_gt_i32_e32 vcc, v51, v167
	v_cmp_le_i32_e64 s[6:7], v51, v150
	s_and_b64 vcc, vcc, s[6:7]
	v_cndmask_b32_e32 v51, v219, v52, vcc
	v_add_u32_e32 v52, 0x222, v164
	v_cmp_le_i32_e32 vcc, v52, v167
	v_cmp_gt_i32_e64 s[6:7], v52, v150
	s_or_b64 vcc, vcc, s[6:7]
	v_cndmask_b32_e32 v52, v36, v219, vcc
	v_add_u32_e32 v36, 0x203, v164
	v_cmp_gt_i32_e32 vcc, v36, v167
	v_cmp_le_i32_e64 s[6:7], v36, v150
	s_and_b64 vcc, vcc, s[6:7]
	v_add_u32_e32 v36, 0x223, v164
	v_cndmask_b32_e32 v53, v219, v53, vcc
	v_cmp_le_i32_e32 vcc, v36, v167
	v_cmp_gt_i32_e64 s[6:7], v36, v150
	s_or_b64 vcc, vcc, s[6:7]
	v_add_u32_e32 v36, 0x208, v164
	v_cndmask_b32_e32 v85, v37, v219, vcc
	v_cmp_gt_i32_e32 vcc, v36, v167
	v_cmp_le_i32_e64 s[6:7], v36, v150
	s_and_b64 vcc, vcc, s[6:7]
	v_add_u32_e32 v36, 0x228, v164
	v_cndmask_b32_e32 v54, v219, v54, vcc
	v_cmp_le_i32_e32 vcc, v36, v167
	v_cmp_gt_i32_e64 s[6:7], v36, v150
	s_or_b64 vcc, vcc, s[6:7]
	v_add_u32_e32 v36, 0x209, v164
	v_cndmask_b32_e32 v38, v38, v219, vcc
	v_cmp_gt_i32_e32 vcc, v36, v167
	v_cmp_le_i32_e64 s[6:7], v36, v150
	s_and_b64 vcc, vcc, s[6:7]
	v_add_u32_e32 v36, 0x229, v164
	v_cndmask_b32_e32 v55, v219, v55, vcc
	v_cmp_le_i32_e32 vcc, v36, v167
	v_cmp_gt_i32_e64 s[6:7], v36, v150
	s_or_b64 vcc, vcc, s[6:7]
	v_add_u32_e32 v36, 0x20a, v164
	v_cndmask_b32_e32 v39, v39, v219, vcc
	v_cmp_gt_i32_e32 vcc, v36, v167
	v_cmp_le_i32_e64 s[6:7], v36, v150
	s_and_b64 vcc, vcc, s[6:7]
	v_add_u32_e32 v36, 0x22a, v164
	v_cndmask_b32_e32 v56, v219, v56, vcc
	v_cmp_le_i32_e32 vcc, v36, v167
	v_cmp_gt_i32_e64 s[6:7], v36, v150
	s_or_b64 vcc, vcc, s[6:7]
	v_add_u32_e32 v36, 0x20b, v164
	v_cndmask_b32_e32 v87, v40, v219, vcc
	v_cmp_gt_i32_e32 vcc, v36, v167
	v_cmp_le_i32_e64 s[6:7], v36, v150
	s_and_b64 vcc, vcc, s[6:7]
	v_add_u32_e32 v36, 0x22b, v164
	v_cndmask_b32_e32 v88, v219, v57, vcc
	v_cmp_le_i32_e32 vcc, v36, v167
	v_cmp_gt_i32_e64 s[6:7], v36, v150
	s_or_b64 vcc, vcc, s[6:7]
	v_add_u32_e32 v36, 0x210, v164
	v_cndmask_b32_e32 v89, v41, v219, vcc
	v_cmp_gt_i32_e32 vcc, v36, v167
	v_cmp_le_i32_e64 s[6:7], v36, v150
	s_and_b64 vcc, vcc, s[6:7]
	v_add_u32_e32 v36, 0x230, v164
	v_cndmask_b32_e32 v58, v219, v58, vcc
	v_cmp_le_i32_e32 vcc, v36, v167
	v_cmp_gt_i32_e64 s[6:7], v36, v150
	s_or_b64 vcc, vcc, s[6:7]
	v_add_u32_e32 v36, 0x211, v164
	v_cndmask_b32_e32 v90, v42, v219, vcc
	v_cmp_gt_i32_e32 vcc, v36, v167
	v_cmp_le_i32_e64 s[6:7], v36, v150
	s_and_b64 vcc, vcc, s[6:7]
	v_add_u32_e32 v36, 0x231, v164
	v_cndmask_b32_e32 v59, v219, v59, vcc
	v_cmp_le_i32_e32 vcc, v36, v167
	v_cmp_gt_i32_e64 s[6:7], v36, v150
	s_or_b64 vcc, vcc, s[6:7]
	v_add_u32_e32 v36, 0x212, v164
	v_cndmask_b32_e32 v91, v43, v219, vcc
	v_cmp_gt_i32_e32 vcc, v36, v167
	v_cmp_le_i32_e64 s[6:7], v36, v150
	s_and_b64 vcc, vcc, s[6:7]
	v_add_u32_e32 v36, 0x232, v164
	v_cndmask_b32_e32 v60, v219, v60, vcc
	v_cmp_le_i32_e32 vcc, v36, v167
	v_cmp_gt_i32_e64 s[6:7], v36, v150
	s_or_b64 vcc, vcc, s[6:7]
	v_add_u32_e32 v36, 0x213, v164
	v_cndmask_b32_e32 v44, v44, v219, vcc
	v_cmp_gt_i32_e32 vcc, v36, v167
	v_cmp_le_i32_e64 s[6:7], v36, v150
	s_and_b64 vcc, vcc, s[6:7]
	v_add_u32_e32 v36, 0x233, v164
	v_cndmask_b32_e32 v61, v219, v61, vcc
	v_cmp_le_i32_e32 vcc, v36, v167
	v_cmp_gt_i32_e64 s[6:7], v36, v150
	s_or_b64 vcc, vcc, s[6:7]
	v_add_u32_e32 v36, 0x218, v164
	v_cndmask_b32_e32 v45, v45, v219, vcc
	v_cmp_gt_i32_e32 vcc, v36, v167
	v_cmp_le_i32_e64 s[6:7], v36, v150
	s_and_b64 vcc, vcc, s[6:7]
	v_add_u32_e32 v36, 0x238, v164
	v_cndmask_b32_e32 v62, v219, v62, vcc
	v_cmp_le_i32_e32 vcc, v36, v167
	v_cmp_gt_i32_e64 s[6:7], v36, v150
	s_or_b64 vcc, vcc, s[6:7]
	v_add_u32_e32 v36, 0x219, v164
	v_cndmask_b32_e32 v46, v46, v219, vcc
	v_cmp_gt_i32_e32 vcc, v36, v167
	v_cmp_le_i32_e64 s[6:7], v36, v150
	s_and_b64 vcc, vcc, s[6:7]
	v_add_u32_e32 v36, 0x239, v164
	v_cndmask_b32_e32 v63, v219, v63, vcc
	v_cmp_le_i32_e32 vcc, v36, v167
	v_cmp_gt_i32_e64 s[6:7], v36, v150
	s_or_b64 vcc, vcc, s[6:7]
	v_add_u32_e32 v36, 0x21a, v164
	v_cndmask_b32_e32 v47, v47, v219, vcc
	v_cmp_gt_i32_e32 vcc, v36, v167
	v_cmp_le_i32_e64 s[6:7], v36, v150
	s_and_b64 vcc, vcc, s[6:7]
	v_add_u32_e32 v36, 0x23a, v164
	v_cndmask_b32_e32 v64, v219, v64, vcc
	v_cmp_le_i32_e32 vcc, v36, v167
	v_cmp_gt_i32_e64 s[6:7], v36, v150
	s_or_b64 vcc, vcc, s[6:7]
	v_add_u32_e32 v36, 0x21b, v164
	v_cndmask_b32_e32 v92, v48, v219, vcc
	v_cmp_gt_i32_e32 vcc, v36, v167
	v_cmp_le_i32_e64 s[6:7], v36, v150
	s_and_b64 vcc, vcc, s[6:7]
	v_add_u32_e32 v36, 0x23b, v164
	v_cndmask_b32_e32 v65, v219, v65, vcc
	v_cmp_le_i32_e32 vcc, v36, v167
	v_cmp_gt_i32_e64 s[6:7], v36, v150
	v_max_f32_e32 v36, v35, v35
	v_max_f32_e32 v37, v50, v50
	v_max_f32_e32 v36, v37, v36
	v_max_f32_e32 v37, v52, v52
	v_max_f32_e32 v40, v51, v51
	v_max_f32_e32 v37, v40, v37
	v_max_f32_e32 v40, v85, v85
	v_max_f32_e32 v41, v53, v53
	v_max3_f32 v36, v0, v34, v36
	v_max_f32_e32 v40, v41, v40
	v_max3_f32 v36, v36, v37, v40
	v_max_f32_e32 v37, v38, v38
	v_max_f32_e32 v40, v54, v54
; __device__ __forceinline__ float fast_exp2(float x) { return __builtin_amdgcn_exp2f(x); }
; __device__ __forceinline__ int crow(int r, int hi) { return (r & 3) + 8 * (r >> 2) + 4 * hi; }
; __device__ __forceinline__ void mask_tile(f32x16& s0, f32x16& s1, int key0, int klo, int khi, bool en, int hi) {
; #pragma unroll
;     for (int r = 0; r < 16; ++r) { const int k = key0 + crow(r, hi);
;         if (!(en && k >= klo && k <= khi)) s0[r] = NEG_INF;
;         if (!(en && k + 32 >= klo && k + 32 <= khi)) s1[r] = NEG_INF; }
; }
; __device__ __forceinline__ float half_swap_max(float m) { auto rr = __builtin_amdgcn_permlane32_swap(__float_as_uint(m), __float_as_uint(m), false, false); return fmaxf(__uint_as_float(rr[0]), __uint_as_float(rr[1])); }
; __device__ __forceinline__ float half_swap_sum(float m) { auto rr = __builtin_amdgcn_permlane32_swap(__float_as_uint(m), __float_as_uint(m), false, false); return __uint_as_float(rr[0]) + __uint_as_float(rr[1]); }
; __device__ __forceinline__ float tile_max(const f32x16& s0, const f32x16& s1) {
;     float m = fmaxf(s0[0], s1[0]);
; #pragma unroll
;     for (int r = 1; r < 16; ++r) m = fmaxf(m, fmaxf(s0[r], s1[r]));
;     return half_swap_max(m);
; }
; __device__ __forceinline__ void stats_step(const f32x16& s0, const f32x16& s1, float& m_run, float& l_run) {
;     const float mn = fmaxf(m_run, tile_max(s0, s1)); const float alpha = fast_exp2(m_run - mn); m_run = mn;
;     float sum = 0.f;
; #pragma unroll
;     for (int r = 0; r < 16; ++r) sum += fast_exp2(s0[r] - mn) + fast_exp2(s1[r] - mn);
;     l_run = l_run * alpha + sum;
; }
; __device__ __forceinline__ void softmax_step(f32x16& s0, f32x16& s1, float& m_run, float& l_run, f32x16& o0, f32x16& o1) {
;     const float mn = fmaxf(m_run, tile_max(s0, s1)); const float alpha = fast_exp2(m_run - mn); m_run = mn;
;     float sum = 0.f;
; #pragma unroll
;     for (int r = 0; r < 16; ++r) { s0[r] = fast_exp2(s0[r] - mn); s1[r] = fast_exp2(s1[r] - mn); sum += s0[r] + s1[r]; }
;     l_run = l_run * alpha + sum;
;     o0 = o0 * alpha; o1 = o1 * alpha;
; }
	v_max_f32_e32 v37, v40, v37
	v_max_f32_e32 v40, v39, v39
	v_max_f32_e32 v41, v55, v55
	v_max_f32_e32 v40, v41, v40
	v_max3_f32 v36, v36, v37, v40
	v_max_f32_e32 v37, v87, v87
	v_max_f32_e32 v40, v56, v56
	v_max_f32_e32 v37, v40, v37
	v_max_f32_e32 v40, v89, v89
	v_max_f32_e32 v41, v88, v88
	v_max_f32_e32 v40, v41, v40
	v_max3_f32 v36, v36, v37, v40
	v_max_f32_e32 v37, v90, v90
	v_max_f32_e32 v40, v58, v58
	v_max_f32_e32 v37, v40, v37
	v_max_f32_e32 v40, v91, v91
	v_max_f32_e32 v41, v59, v59
	v_max_f32_e32 v40, v41, v40
	v_max3_f32 v36, v36, v37, v40
	v_max_f32_e32 v37, v44, v44
	v_max_f32_e32 v40, v60, v60
	v_max_f32_e32 v37, v40, v37
	v_max_f32_e32 v40, v45, v45
	v_max_f32_e32 v41, v61, v61
	v_max_f32_e32 v40, v41, v40
	v_max3_f32 v36, v36, v37, v40
	v_max_f32_e32 v37, v46, v46
	v_max_f32_e32 v40, v62, v62
	v_max_f32_e32 v37, v40, v37
	v_max_f32_e32 v40, v47, v47
	v_max_f32_e32 v41, v63, v63
	s_or_b64 vcc, vcc, s[6:7]
	v_max_f32_e32 v40, v41, v40
	v_cndmask_b32_e32 v93, v49, v219, vcc
	v_max3_f32 v36, v36, v37, v40
	v_max_f32_e32 v37, v92, v92
	v_max_f32_e32 v40, v64, v64
	v_max_f32_e32 v37, v40, v37
	v_max_f32_e32 v40, v93, v93
	v_max_f32_e32 v41, v65, v65
	v_max_f32_e32 v40, v41, v40
	v_max3_f32 v36, v36, v37, v40
	v_mov_b32_e32 v37, v36
	s_nop 1
	v_permlane32_swap_b32_e32 v36, v37
	v_max3_f32 v84, v82, v36, v37
	v_sub_f32_e32 v0, v0, v84
	v_exp_f32_e32 v94, v0
	v_sub_f32_e32 v0, v34, v84
	v_exp_f32_e32 v95, v0
	v_sub_f32_e32 v0, v50, v84
	v_exp_f32_e32 v48, v0
	v_sub_f32_e32 v0, v35, v84
	v_exp_f32_e32 v0, v0
	v_add_f32_e32 v49, v94, v95
	v_pk_add_f32 v[34:35], v[48:49], v[0:1]
	s_nop 0
	v_pk_add_f32 v[36:37], v[34:35], v[34:35] op_sel_hi:[0,1]
	v_sub_f32_e32 v34, v51, v84
	v_exp_f32_e32 v49, v34
	v_sub_f32_e32 v34, v52, v84
	v_exp_f32_e32 v96, v34
	v_sub_f32_e32 v34, v53, v84
	v_exp_f32_e32 v50, v34
	v_sub_f32_e32 v34, v85, v84
	v_exp_f32_e32 v36, v34
	v_add_f32_e32 v51, v49, v96
	v_cvt_pk_bf16_f32 v48, v94, v48
	v_cvt_pk_bf16_f32 v49, v49, v50
	v_pk_add_f32 v[34:35], v[50:51], v[36:37]
	s_nop 0
	v_pk_add_f32 v[40:41], v[34:35], v[34:35] op_sel_hi:[0,1]
	v_sub_f32_e32 v34, v54, v84
	v_exp_f32_e32 v37, v34
	v_sub_f32_e32 v34, v38, v84
	v_exp_f32_e32 v97, v34
	v_sub_f32_e32 v34, v55, v84
	v_exp_f32_e32 v52, v34
	v_sub_f32_e32 v34, v39, v84
	v_exp_f32_e32 v40, v34
	v_add_f32_e32 v53, v37, v97
	v_cvt_pk_bf16_f32 v50, v37, v52
	v_pk_add_f32 v[34:35], v[52:53], v[40:41]
	s_nop 0
	v_pk_add_f32 v[42:43], v[34:35], v[34:35] op_sel_hi:[0,1]
	v_sub_f32_e32 v34, v56, v84
	v_exp_f32_e32 v41, v34
	v_sub_f32_e32 v34, v87, v84
	v_exp_f32_e32 v98, v34
	v_sub_f32_e32 v34, v88, v84
	v_exp_f32_e32 v56, v34
	v_sub_f32_e32 v34, v89, v84
	v_exp_f32_e32 v42, v34
	v_add_f32_e32 v57, v41, v98
	v_cvt_pk_bf16_f32 v51, v41, v56
	v_pk_add_f32 v[34:35], v[56:57], v[42:43]
	s_nop 0
	v_pk_add_f32 v[34:35], v[34:35], v[34:35] op_sel_hi:[0,1]
	v_sub_f32_e32 v34, v58, v84
	v_exp_f32_e32 v43, v34
	v_sub_f32_e32 v34, v90, v84
	v_exp_f32_e32 v99, v34
	v_sub_f32_e32 v34, v59, v84
	v_exp_f32_e32 v54, v34
	v_sub_f32_e32 v34, v91, v84
	v_exp_f32_e32 v34, v34
	v_add_f32_e32 v55, v43, v99
	v_pk_add_f32 v[38:39], v[54:55], v[34:35]
	s_nop 0
	v_pk_add_f32 v[38:39], v[38:39], v[38:39] op_sel_hi:[0,1]
	v_sub_f32_e32 v38, v44, v84
	v_sub_f32_e32 v35, v60, v84
	v_exp_f32_e32 v100, v38
	v_sub_f32_e32 v38, v61, v84
	v_exp_f32_e32 v35, v35
	v_exp_f32_e32 v58, v38
	v_sub_f32_e32 v38, v45, v84
	v_exp_f32_e32 v38, v38
	v_add_f32_e32 v59, v35, v100
	v_pk_add_f32 v[44:45], v[58:59], v[38:39]
	s_nop 0
	v_pk_add_f32 v[44:45], v[44:45], v[44:45] op_sel_hi:[0,1]
	v_sub_f32_e32 v44, v46, v84
	v_sub_f32_e32 v39, v62, v84
	v_exp_f32_e32 v101, v44
	v_sub_f32_e32 v44, v63, v84
	v_exp_f32_e32 v39, v39
	v_exp_f32_e32 v60, v44
	v_sub_f32_e32 v44, v47, v84
	v_exp_f32_e32 v44, v44
	v_add_f32_e32 v61, v39, v101
	v_pk_add_f32 v[46:47], v[60:61], v[44:45]
	s_nop 0
	v_pk_add_f32 v[46:47], v[46:47], v[46:47] op_sel_hi:[0,1]
	v_sub_f32_e32 v46, v92, v84
	v_sub_f32_e32 v45, v64, v84
	v_exp_f32_e32 v61, v46
	v_sub_f32_e32 v46, v65, v84
	v_exp_f32_e32 v45, v45
	v_exp_f32_e32 v90, v46
	v_sub_f32_e32 v46, v93, v84
	v_exp_f32_e32 v46, v46
	v_add_f32_e32 v91, v45, v61
	v_pk_add_f32 v[62:63], v[90:91], v[46:47]
	v_sub_f32_e32 v47, v82, v84
	v_add_f32_e32 v85, v62, v63
	v_exp_f32_e32 v62, v47
	s_nop 0
	v_fmac_f32_e32 v85, v86, v62
	v_pk_mul_f32 v[32:33], v[32:33], v[62:63] op_sel_hi:[1,0]
	v_pk_mul_f32 v[30:31], v[30:31], v[62:63] op_sel_hi:[1,0]
	v_pk_mul_f32 v[28:29], v[28:29], v[62:63] op_sel_hi:[1,0]
	v_pk_mul_f32 v[26:27], v[26:27], v[62:63] op_sel_hi:[1,0]
	v_pk_mul_f32 v[24:25], v[24:25], v[62:63] op_sel_hi:[1,0]
	v_pk_mul_f32 v[22:23], v[22:23], v[62:63] op_sel_hi:[1,0]
	v_pk_mul_f32 v[20:21], v[20:21], v[62:63] op_sel_hi:[1,0]
	v_pk_mul_f32 v[18:19], v[18:19], v[62:63] op_sel_hi:[1,0]
	v_pk_mul_f32 v[16:17], v[16:17], v[62:63] op_sel_hi:[1,0]
	v_pk_mul_f32 v[14:15], v[14:15], v[62:63] op_sel_hi:[1,0]
	v_pk_mul_f32 v[12:13], v[12:13], v[62:63] op_sel_hi:[1,0]
	v_pk_mul_f32 v[10:11], v[10:11], v[62:63] op_sel_hi:[1,0]
	v_pk_mul_f32 v[8:9], v[8:9], v[62:63] op_sel_hi:[1,0]
	v_pk_mul_f32 v[6:7], v[6:7], v[62:63] op_sel_hi:[1,0]
	v_pk_mul_f32 v[4:5], v[4:5], v[62:63] op_sel_hi:[1,0]
	v_pk_mul_f32 v[2:3], v[2:3], v[62:63] op_sel_hi:[1,0]
	ds_read_b64_tr_b16 v[62:63], v83 offset:8192
	ds_read_b64_tr_b16 v[64:65], v83 offset:8704
	ds_read_b64_tr_b16 v[86:87], v83 offset:12288
	ds_read_b64_tr_b16 v[88:89], v83 offset:12800
	s_waitcnt lgkmcnt(2)
; #define LAS __attribute__((address_space(3)))
; #define MFMA32(a, b, c) __builtin_amdgcn_mfma_f32_32x32x16_bf16(a, b, c, 0, 0, 0)
; __device__ __forceinline__ s16x4 tr16(const LAS unsigned char* p) { return __builtin_bit_cast(s16x4, __builtin_amdgcn_ds_read_tr16_b64_v4i16((LAS v4i16_t*)p)); }
; __device__ __forceinline__ bf16x8 cat8(s16x4 lo, s16x4 hi) { return (bf16x8){lo[0], lo[1], lo[2], lo[3], hi[0], hi[1], hi[2], hi[3]}; }
; __device__ __forceinline__ void pv_tile(const LAS unsigned char* vb, const f32x16& p0, const f32x16& p1, f32x16& o0, f32x16& o1, int lane, int hi) {
;     const LAS unsigned char* vp = vb + ((lane >> 4) & 1) * 32 + (lane & 3) * 8 + (4 * hi + ((lane & 15) >> 2)) * 64;
; #pragma unroll
;     for (int kk = 0; kk < 4; ++kk) {
;         const bf16x8 pf = (kk < 2) ? pack8(p0, 8 * kk) : pack8(p1, 8 * (kk - 2));
;         const bf16x8 v0 = cat8(tr16(vp + kk * 1024), tr16(vp + kk * 1024 + 512));
;         const bf16x8 v1 = cat8(tr16(vp + 4096 + kk * 1024), tr16(vp + 4096 + kk * 1024 + 512));
;         o0 = MFMA32(v0, pf, o0); o1 = MFMA32(v1, pf, o1);
;     }
; }
	v_mfma_f32_32x32x16_bf16 v[18:33], v[62:65], v[48:51], v[18:33]
	s_waitcnt lgkmcnt(0)
	v_mfma_f32_32x32x16_bf16 v[2:17], v[86:89], v[48:51], v[2:17]
	v_cvt_pk_bf16_f32 v48, v43, v54
	v_cvt_pk_bf16_f32 v49, v35, v58
	v_cvt_pk_bf16_f32 v50, v39, v60
	v_cvt_pk_bf16_f32 v51, v45, v90
	ds_read_b64_tr_b16 v[52:53], v83 offset:9216
	ds_read_b64_tr_b16 v[54:55], v83 offset:9728
	ds_read_b64_tr_b16 v[56:57], v83 offset:13312
	ds_read_b64_tr_b16 v[58:59], v83 offset:13824
	s_waitcnt lgkmcnt(2)
	v_mfma_f32_32x32x16_bf16 v[18:33], v[52:55], v[48:51], v[18:33]
	s_waitcnt lgkmcnt(0)
	v_mfma_f32_32x32x16_bf16 v[2:17], v[56:59], v[48:51], v[2:17]
	v_cvt_pk_bf16_f32 v48, v95, v0
	v_cvt_pk_bf16_f32 v49, v96, v36
	v_cvt_pk_bf16_f32 v50, v97, v40
	v_cvt_pk_bf16_f32 v51, v98, v42
	ds_read_b64_tr_b16 v[40:41], v83 offset:10240
	ds_read_b64_tr_b16 v[42:43], v83 offset:10752
	ds_read_b64_tr_b16 v[52:53], v83 offset:14336
	ds_read_b64_tr_b16 v[54:55], v83 offset:14848
	v_cvt_pk_bf16_f32 v34, v99, v34
	v_cvt_pk_bf16_f32 v35, v100, v38
	s_waitcnt lgkmcnt(2)
	v_mfma_f32_32x32x16_bf16 v[18:33], v[40:43], v[48:51], v[18:33]
	v_cvt_pk_bf16_f32 v36, v101, v44
	v_cvt_pk_bf16_f32 v37, v61, v46
	ds_read_b64_tr_b16 v[38:39], v83 offset:11264
	ds_read_b64_tr_b16 v[40:41], v83 offset:11776
	ds_read_b64_tr_b16 v[42:43], v83 offset:15360
	ds_read_b64_tr_b16 v[44:45], v83 offset:15872
	s_waitcnt lgkmcnt(4)
	v_mfma_f32_32x32x16_bf16 v[2:17], v[52:55], v[48:51], v[2:17]
	s_waitcnt lgkmcnt(2)
	v_mfma_f32_32x32x16_bf16 v[18:33], v[38:41], v[34:37], v[18:33]
	s_waitcnt lgkmcnt(0)
	v_mfma_f32_32x32x16_bf16 v[2:17], v[42:45], v[34:37], v[2:17]

; #define LAS __attribute__((address_space(3)))
; __device__ __forceinline__ unsigned cvt_pk_bf16(float lo, float hi) { unsigned r; asm volatile("v_cvt_pk_bf16_f32 %0, %1, %2" : "=v"(r) : "v"(lo), "v"(hi)); return r; }
; #define LAUNDER_GPTR(p) do { p = launder_gptr(p); } while (0)
; #define LDS_WAIT() asm volatile("s_waitcnt lgkmcnt(0)" ::: "memory")
; __device__ __forceinline__ unsigned sel_word(const unsigned (&w)[4], int j) { const int k = j >> 5; return (k == 0) ? w[0] : (k == 1) ? w[1] : (k == 2) ? w[2] : w[3]; }
; __device__ __forceinline__ void f32_k_issue(F32Tile& T, const float* kp, int lane) {
;     const float* kl = kp + (size_t)(lane >> 4) * 256 + (lane & 15) * 4;
; #pragma unroll
;     for (int i = 0; i < 16; ++i) T.x[i] = *(const f32x4*)(kl + (size_t)(4 * i) * 256);
; }
; template <int H> __device__ __forceinline__ void f32_k_commit(const F32Tile& T, LAS unsigned char* kb, int lane, float* kcopy, int skip) {
;     const int pc = lane & 15, rl = lane >> 4, c = pc >> 1;
;     float* kc = kcopy + (size_t)rl * 256 + pc * 4;
;     const unsigned keo = (unsigned)(c * 1024 + (pc & 1) * 8 + ((rl + c) & 7) * 16);
;     if (H == 0) LDS_WAIT();
; #pragma unroll
;     for (int i = 8 * H; i < 8 * H + 8; ++i) { u32x2 w; w.x = cvt_pk_bf16(T.x[i][0], T.x[i][1]); w.y = cvt_pk_bf16(T.x[i][2], T.x[i][3]);
;         *(LAS u32x2*)(kb + ((i & 1) ? (keo ^ 64u) : keo) + 128 * (i >> 1)) = w;
;         if (kcopy && 4 * i + rl >= skip) *(f32x4*)(kc + (size_t)(4 * i) * 256) = T.x[i]; }
;     if (H == 1) LDS_WAIT();
; }
; __device__ __forceinline__ void attn_decode_unit(const Params& P, const Ctx& C, int sg) {
;     ...
;       for (int j = wave - 1; j <= 32; j += 7) {
;           const bool en = ((sel_word(selw, j) >> (j & 31)) & 1u) && (64 * j <= t);
;           if (__any(en)) {
;               if (j < 32) { const size_t po = (size_t)pt[j >> 1] * (128 * 256) + (size_t)(j & 1) * 64 * 256 + g * 64;
;                   const float* in4 = P.in[4]; const float* in5 = P.in[5]; LAUNDER_GPTR(in4); LAUNDER_GPTR(in5);
;                   F32_TILE_STEP(in4 + po, in5 + po, (float*)nullptr, (float*)nullptr, 0, 64 * j, 0, t, en, m_s, l_s, os0, os1); }
.LBB0_1376:
	s_add_i32 s81, s72, 7
	s_cmp_lt_u32 s81, 32
	s_cselect_b64 vcc, -1, 0
	s_and_b32 s4, s81, 0xffffffe0
	s_cmp_eq_u32 s4, 32
	s_cselect_b64 s[4:5], -1, 0
	v_cndmask_b32_e64 v34, 0, v151, s[4:5]
	v_cndmask_b32_e32 v34, v34, v150, vcc
	v_lshrrev_b32_e32 v34, s81, v34
	v_and_b32_e32 v34, 1, v34
	s_sub_i32 s4, s51, 64
	v_cmp_eq_u32_e32 vcc, 1, v34
	v_cmp_le_i32_e64 s[4:5], s4, v232
	s_and_b64 s[70:71], vcc, s[4:5]
	v_cndmask_b32_e64 v34, 0, 1, s[70:71]
	v_cmp_ne_u32_e32 vcc, 0, v34
	s_cbranch_vccz .LBB0_1386
	s_cmp_eq_u32 s72, 25
	s_mov_b64 s[4:5], -1
	s_cbranch_scc1 .LBB0_1383
	s_ashr_i32 s4, s81, 1
	s_ashr_i32 s5, s4, 31
	s_xor_b64 s[72:73], s[70:71], -1
	s_lshl_b64 s[4:5], s[4:5], 2
	v_readlane_b32 s8, v254, 25
	s_add_u32 s4, s8, s4
	s_addc_u32 s5, s49, s5
	global_load_dword v34, v1, s[4:5]
	s_and_b32 s74, s80, 0x4000
	v_readlane_b32 s8, v254, 37
	v_readlane_b32 s9, v254, 38
	v_readlane_b32 s10, v254, 39
	v_readlane_b32 s11, v254, 40
	s_movk_i32 s47, 0x6000
	s_mov_b32 s33, 0x8000
	s_mov_b32 s45, 0xa000
	s_mov_b32 s62, 0xc000
	s_mov_b32 s48, 0xe000
	s_mov_b32 s63, 0xf000
	v_readlane_b32 s12, v254, 41
	v_readlane_b32 s13, v254, 42
	v_readlane_b32 s14, v254, 43
	v_readlane_b32 s15, v254, 44
	s_waitcnt vmcnt(0)
	v_readfirstlane_b32 s4, v34
	s_ashr_i32 s5, s4, 31
	s_lshl_b64 s[4:5], s[4:5], 15
	s_or_b32 s4, s4, s74
	s_or_b64 s[76:77], s[4:5], s[64:65]
	s_mov_b64 s[74:75], s[8:9]
	s_lshl_b64 s[76:77], s[76:77], 2
	s_add_u32 s74, s74, s76
	s_addc_u32 s75, s75, s77
	v_lshl_add_u64 v[34:35], s[74:75], 0, v[152:153]
	v_lshl_add_u64 v[34:35], v[34:35], 0, v[0:1]
	s_movk_i32 s74, 0x2000
	v_add_co_u32_e32 v36, vcc, s74, v34
	s_mov_b64 s[4:5], s[10:11]
	s_nop 0
	v_addc_co_u32_e32 v37, vcc, 0, v35, vcc
	s_movk_i32 s75, 0x4000
	global_load_dwordx4 v[138:141], v[34:35], off nt
	global_load_dwordx4 v[146:149], v[36:37], off offset:-4096 nt
	global_load_dwordx4 v[130:133], v[36:37], off nt
	v_add_co_u32_e32 v36, vcc, s75, v34
	s_add_u32 s4, s4, s76
	s_nop 0
	v_addc_co_u32_e32 v37, vcc, 0, v35, vcc
	global_load_dwordx4 v[142:145], v[36:37], off offset:-4096 nt
	global_load_dwordx4 v[122:125], v[36:37], off nt
	v_add_co_u32_e32 v36, vcc, s47, v34
	s_addc_u32 s5, s5, s77
	s_nop 0
	v_addc_co_u32_e32 v37, vcc, 0, v35, vcc
	global_load_dwordx4 v[134:137], v[36:37], off offset:-4096 nt
	global_load_dwordx4 v[118:121], v[36:37], off nt
	v_add_co_u32_e32 v36, vcc, s33, v34
	v_lshl_add_u64 v[86:87], s[4:5], 0, v[152:153]
	s_nop 0
	v_addc_co_u32_e32 v37, vcc, 0, v35, vcc
	global_load_dwordx4 v[126:129], v[36:37], off offset:-4096 nt
	global_load_dwordx4 v[62:65], v[36:37], off nt
	v_add_co_u32_e32 v36, vcc, s45, v34
	v_lshl_add_u64 v[198:199], v[86:87], 0, v[0:1]
	s_nop 0
	v_addc_co_u32_e32 v37, vcc, 0, v35, vcc
	global_load_dwordx4 v[58:61], v[36:37], off offset:-4096 nt
	global_load_dwordx4 v[54:57], v[36:37], off nt
	v_add_co_u32_e32 v36, vcc, s62, v34
	s_nop 1
	v_addc_co_u32_e32 v37, vcc, 0, v35, vcc
	global_load_dwordx4 v[50:53], v[36:37], off offset:-4096 nt
	global_load_dwordx4 v[46:49], v[36:37], off nt
	v_add_co_u32_e32 v36, vcc, s48, v34
	s_nop 1
	v_addc_co_u32_e32 v37, vcc, 0, v35, vcc
	global_load_dwordx4 v[42:45], v[36:37], off offset:-4096 nt
	global_load_dwordx4 v[38:41], v[36:37], off nt
	v_add_co_u32_e32 v34, vcc, s63, v34
	global_load_dwordx4 v[114:117], v[198:199], off nt
	s_nop 0
	v_addc_co_u32_e32 v35, vcc, 0, v35, vcc
	v_add_co_u32_e32 v86, vcc, s74, v198
	global_load_dwordx4 v[34:37], v[34:35], off nt
	s_nop 0
	v_addc_co_u32_e32 v87, vcc, 0, v199, vcc
	global_load_dwordx4 v[110:113], v[86:87], off offset:-4096 nt
	global_load_dwordx4 v[94:97], v[86:87], off nt
	v_add_co_u32_e32 v86, vcc, s75, v198
	s_nop 1
	v_addc_co_u32_e32 v87, vcc, 0, v199, vcc
	global_load_dwordx4 v[106:109], v[86:87], off offset:-4096 nt
	global_load_dwordx4 v[90:93], v[86:87], off nt
	v_add_co_u32_e32 v86, vcc, s47, v198
	s_mov_b32 s47, 0xe000
	s_nop 0
	v_addc_co_u32_e32 v87, vcc, 0, v199, vcc
	v_add_co_u32_e32 v200, vcc, s33, v198
	global_load_dwordx4 v[102:105], v[86:87], off offset:-4096 nt
	s_nop 0
	global_load_dwordx4 v[86:89], v[86:87], off nt
	v_addc_co_u32_e32 v201, vcc, 0, v199, vcc
	global_load_dwordx4 v[98:101], v[200:201], off offset:-4096 nt
	s_waitcnt lgkmcnt(0)
	s_waitcnt vmcnt(23)
	v_cvt_pk_bf16_f32 v138, v138, v139
	v_cvt_pk_bf16_f32 v139, v140, v141
	ds_write_b64 v240, v[138:139]
	s_waitcnt vmcnt(22)
	v_cvt_pk_bf16_f32 v138, v146, v147
	v_cvt_pk_bf16_f32 v139, v148, v149
	ds_write_b64 v241, v[138:139]
	s_waitcnt vmcnt(21)
	v_cvt_pk_bf16_f32 v130, v130, v131
	v_cvt_pk_bf16_f32 v131, v132, v133
	ds_write_b64 v240, v[130:131] offset:128
	s_waitcnt vmcnt(20)
	v_cvt_pk_bf16_f32 v130, v142, v143
	v_cvt_pk_bf16_f32 v131, v144, v145
	ds_write_b64 v241, v[130:131] offset:128
	s_waitcnt vmcnt(19)
	v_cvt_pk_bf16_f32 v122, v122, v123
	v_cvt_pk_bf16_f32 v123, v124, v125
	ds_write_b64 v240, v[122:123] offset:256
	s_waitcnt vmcnt(18)
	v_cvt_pk_bf16_f32 v122, v134, v135
	v_cvt_pk_bf16_f32 v123, v136, v137
	ds_write_b64 v241, v[122:123] offset:256
	s_waitcnt vmcnt(17)
	v_cvt_pk_bf16_f32 v118, v118, v119
	v_cvt_pk_bf16_f32 v119, v120, v121
	v_add_co_u32_e32 v122, vcc, s45, v198
	ds_write_b64 v240, v[118:119] offset:384
	s_waitcnt vmcnt(16)
; __device__ __forceinline__ void qk_tile_sw(const LAS unsigned char* kb, const bf16x8 (&qr)[4], f32x16& s0, f32x16& s1, int r32, int hi) {
;     f32x16 a = {0.f, 0.f, 0.f, 0.f, 0.f, 0.f, 0.f, 0.f, 0.f, 0.f, 0.f, 0.f, 0.f, 0.f, 0.f, 0.f}, b = a;
;     const LAS unsigned char* kp = kb + hi * 1024 + (r32 & ~7) * 16;
; #pragma unroll
;     for (int d0 = 0; d0 < 4; ++d0) { const int lo = (r32 + 2 * d0 + hi) & 7;
;         const bf16x8 k0 = *(const LAS bf16x8*)(kp + d0 * 2048 + lo * 16), k1 = *(const LAS bf16x8*)(kp + d0 * 2048 + lo * 16 + 512);
;         a = MFMA32(k0, qr[d0], a); b = MFMA32(k1, qr[d0], b);
;     }
;     s0 = a; s1 = b;
; }
; __device__ __forceinline__ void qk_tile(const LAS unsigned char* kb, const bf16x8 (&qr)[4], f32x16& s0, f32x16& s1, int r32, int hi) {
;     const LAS unsigned char* kp = kb + hi * 1024 + r32 * 16;
;     f32x16 a = F16Z, b = F16Z;
; #pragma unroll
;     for (int d0 = 0; d0 < 4; ++d0) {
;         const bf16x8 k0 = *(const LAS bf16x8*)(kp + d0 * 2048), k1 = *(const LAS bf16x8*)(kp + d0 * 2048 + 512);
;         a = MFMA32(k0, qr[d0], a); b = MFMA32(k1, qr[d0], b);
;     }
;     s0 = a; s1 = b;
; }
; __device__ __forceinline__ void mask_tile(f32x16& s0, f32x16& s1, int key0, int klo, int khi, bool en, int hi) {
; #pragma unroll
;     for (int r = 0; r < 16; ++r) { const int k = key0 + crow(r, hi);
;         if (!(en && k >= klo && k <= khi)) s0[r] = NEG_INF;
;         if (!(en && k + 32 >= klo && k + 32 <= khi)) s1[r] = NEG_INF; }
; }
; template <int H> __device__ __forceinline__ void f32_k_commit(const F32Tile& T, LAS unsigned char* kb, int lane, float* kcopy, int skip) {
;     ...
;     for (int i = 8 * H; i < 8 * H + 8; ++i) { u32x2 w; w.x = cvt_pk_bf16(T.x[i][0], T.x[i][1]); w.y = cvt_pk_bf16(T.x[i][2], T.x[i][3]);
;         *(LAS u32x2*)(kb + ((i & 1) ? (keo ^ 64u) : keo) + 128 * (i >> 1)) = w;
;         if (kcopy && 4 * i + rl >= skip) *(f32x4*)(kc + (size_t)(4 * i) * 256) = T.x[i]; }
;     if (H == 1) LDS_WAIT();
; }
; __device__ __forceinline__ void f32_v_issue(F32Half& T, const float* vp, int lane, int h) {
;     const float* vl = vp + (size_t)(lane >> 4) * 256 + (lane & 15) * 4;
; #pragma unroll
;     for (int i = 0; i < 8; ++i) T.x[i] = *(const f32x4*)(vl + (size_t)(4 * (8 * h + i)) * 256);
; }
; __device__ __forceinline__ void f32_v_commit(const F32Half& T, LAS unsigned char* vb, int lane, float* vcopy, int skip, int h) {
	v_cvt_pk_bf16_f32 v118, v126, v127
	v_cvt_pk_bf16_f32 v119, v128, v129
	ds_write_b64 v241, v[118:119] offset:384
	v_addc_co_u32_e32 v123, vcc, 0, v199, vcc
	global_load_dwordx4 v[118:121], v[200:201], off nt
	global_load_dwordx4 v[142:145], v[122:123], off offset:-4096 nt
	global_load_dwordx4 v[130:133], v[122:123], off nt
	v_add_co_u32_e32 v122, vcc, s62, v198
	s_mov_b32 s45, 0xc000
	s_nop 0
	v_addc_co_u32_e32 v123, vcc, 0, v199, vcc
	global_load_dwordx4 v[138:141], v[122:123], off offset:-4096 nt
	global_load_dwordx4 v[126:129], v[122:123], off nt
	v_add_co_u32_e32 v122, vcc, s48, v198
	s_mov_b32 s62, 0xf000
	s_nop 0
	v_addc_co_u32_e32 v123, vcc, 0, v199, vcc
	v_add_co_u32_e32 v146, vcc, s63, v198
	global_load_dwordx4 v[134:137], v[122:123], off offset:-4096 nt
	s_nop 0
	global_load_dwordx4 v[122:125], v[122:123], off nt
	v_addc_co_u32_e32 v147, vcc, 0, v199, vcc
	global_load_dwordx4 v[146:149], v[146:147], off nt
	s_waitcnt vmcnt(23)
	v_cvt_pk_bf16_f32 v62, v62, v63
	v_cvt_pk_bf16_f32 v63, v64, v65
	ds_write_b64 v240, v[62:63] offset:512
	s_waitcnt vmcnt(22)
	v_cvt_pk_bf16_f32 v58, v58, v59
	v_cvt_pk_bf16_f32 v59, v60, v61
	ds_write_b64 v241, v[58:59] offset:512
	s_waitcnt vmcnt(21)
	v_cvt_pk_bf16_f32 v54, v54, v55
	v_cvt_pk_bf16_f32 v55, v56, v57
	ds_write_b64 v240, v[54:55] offset:640
	s_waitcnt vmcnt(20)
	v_cvt_pk_bf16_f32 v50, v50, v51
	v_cvt_pk_bf16_f32 v51, v52, v53
	ds_write_b64 v241, v[50:51] offset:640
	s_waitcnt vmcnt(19)
	v_cvt_pk_bf16_f32 v46, v46, v47
	v_cvt_pk_bf16_f32 v47, v48, v49
	ds_write_b64 v240, v[46:47] offset:768
	s_waitcnt vmcnt(18)
	v_cvt_pk_bf16_f32 v42, v42, v43
	v_cvt_pk_bf16_f32 v43, v44, v45
	ds_write_b64 v241, v[42:43] offset:768
	s_waitcnt vmcnt(17)
	v_cvt_pk_bf16_f32 v38, v38, v39
	v_cvt_pk_bf16_f32 v39, v40, v41
	ds_write_b64 v240, v[38:39] offset:896
	s_waitcnt vmcnt(15)
	v_cvt_pk_bf16_f32 v34, v34, v35
	v_cvt_pk_bf16_f32 v35, v36, v37
	ds_write_b64 v241, v[34:35] offset:896
	s_waitcnt lgkmcnt(0)
	ds_read_b128 v[34:37], v242
	ds_read_b128 v[38:41], v242 offset:512
	s_waitcnt lgkmcnt(1)
	v_mfma_f32_32x32x16_bf16 v[50:65], v[34:37], v[74:77], 0
	ds_read_b128 v[198:201], v243 offset:2048
	ds_read_b128 v[202:205], v243 offset:2560
	s_waitcnt lgkmcnt(2)
	v_mfma_f32_32x32x16_bf16 v[34:49], v[38:41], v[74:77], 0
	s_waitcnt lgkmcnt(1)
	v_mfma_f32_32x32x16_bf16 v[50:65], v[198:201], v[66:69], v[50:65]
	s_waitcnt lgkmcnt(0)
	v_mfma_f32_32x32x16_bf16 v[34:49], v[202:205], v[66:69], v[34:49]
	ds_read_b128 v[198:201], v244 offset:4096
	ds_read_b128 v[202:205], v244 offset:4608
	s_waitcnt lgkmcnt(1)
	v_mfma_f32_32x32x16_bf16 v[50:65], v[198:201], v[70:73], v[50:65]
	s_waitcnt lgkmcnt(0)
	v_mfma_f32_32x32x16_bf16 v[34:49], v[202:205], v[70:73], v[34:49]
	ds_read_b128 v[198:201], v245 offset:6144
	ds_read_b128 v[202:205], v245 offset:6656
	s_waitcnt lgkmcnt(1)
	v_mfma_f32_32x32x16_bf16 v[50:65], v[198:201], v[78:81], v[50:65]
	v_add_u32_e32 v198, s51, v164
	v_subrev_u32_e32 v199, 64, v198
	s_waitcnt lgkmcnt(0)
	v_mfma_f32_32x32x16_bf16 v[34:49], v[202:205], v[78:81], v[34:49]
	s_and_saveexec_b64 s[76:77], s[70:71]
	v_cmp_gt_i32_e32 vcc, s46, v199
	v_cmp_gt_i32_e64 s[4:5], v199, v235
	s_or_b64 s[4:5], vcc, s[4:5]
	s_andn2_b64 s[72:73], s[72:73], exec
	s_and_b64 s[4:5], s[4:5], exec
	s_or_b64 s[72:73], s[72:73], s[4:5]
	s_or_b64 exec, exec, s[76:77]
	s_and_saveexec_b64 s[4:5], s[72:73]
	s_nop 2
	v_mov_b32_e32 v34, s50
	s_or_b64 exec, exec, s[4:5]
	v_cmp_le_u32_e32 vcc, v199, v232
	s_and_b64 vcc, s[70:71], vcc
	v_subrev_u32_e32 v200, 31, v198
	v_cndmask_b32_e32 v50, v219, v50, vcc
	v_cmp_lt_u32_e32 vcc, v199, v232
	s_and_b64 vcc, s[70:71], vcc
	s_waitcnt lgkmcnt(0)
	s_mov_b64 s[4:5], 0
	v_cndmask_b32_e32 v51, v219, v51, vcc
	v_cmp_le_u32_e32 vcc, v200, v232
	s_and_b64 vcc, s[70:71], vcc
	v_subrev_u32_e32 v200, 30, v198
	v_cndmask_b32_e32 v35, v219, v35, vcc
	v_cmp_le_u32_e32 vcc, v199, v236
	s_and_b64 vcc, s[70:71], vcc
	s_nop 0
	v_cndmask_b32_e32 v52, v219, v52, vcc
	v_cmp_le_u32_e32 vcc, v200, v232
	s_and_b64 vcc, s[70:71], vcc
	s_nop 0
	v_cndmask_b32_e32 v36, v219, v36, vcc
	v_cmp_le_u32_e32 vcc, v199, v237
	s_and_b64 vcc, s[70:71], vcc
	v_subrev_u32_e32 v199, 29, v198
	v_cndmask_b32_e32 v53, v219, v53, vcc
	v_cmp_le_u32_e32 vcc, v199, v232
	s_and_b64 vcc, s[70:71], vcc
	v_subrev_u32_e32 v199, 56, v198
	v_cndmask_b32_e32 v37, v219, v37, vcc
	v_cmp_le_u32_e32 vcc, v199, v232
	s_and_b64 vcc, s[70:71], vcc
	v_subrev_u32_e32 v199, 24, v198
	v_cndmask_b32_e32 v54, v219, v54, vcc
	v_cmp_le_u32_e32 vcc, v199, v232
	s_and_b64 vcc, s[70:71], vcc
	v_subrev_u32_e32 v199, 55, v198
	v_cndmask_b32_e32 v38, v219, v38, vcc
	v_cmp_le_u32_e32 vcc, v199, v232
	s_and_b64 vcc, s[70:71], vcc
	v_subrev_u32_e32 v199, 23, v198
	v_cndmask_b32_e32 v55, v219, v55, vcc
	v_cmp_le_u32_e32 vcc, v199, v232
	s_and_b64 vcc, s[70:71], vcc
	v_subrev_u32_e32 v199, 54, v198
	v_cndmask_b32_e32 v39, v219, v39, vcc
	v_cmp_le_u32_e32 vcc, v199, v232
	s_and_b64 vcc, s[70:71], vcc
	v_subrev_u32_e32 v199, 22, v198
	v_cndmask_b32_e32 v56, v219, v56, vcc
	v_cmp_le_u32_e32 vcc, v199, v232
	s_and_b64 vcc, s[70:71], vcc
	v_subrev_u32_e32 v199, 53, v198
	v_cndmask_b32_e32 v40, v219, v40, vcc
	v_cmp_le_u32_e32 vcc, v199, v232
	s_and_b64 vcc, s[70:71], vcc
	v_subrev_u32_e32 v199, 21, v198
	v_cndmask_b32_e32 v57, v219, v57, vcc
	v_cmp_le_u32_e32 vcc, v199, v232
	s_and_b64 vcc, s[70:71], vcc
	v_subrev_u32_e32 v199, 48, v198
	v_cndmask_b32_e32 v41, v219, v41, vcc
	v_cmp_le_u32_e32 vcc, v199, v232
	s_and_b64 vcc, s[70:71], vcc
	v_add_u32_e32 v199, -16, v198
	v_cndmask_b32_e32 v58, v219, v58, vcc
	v_cmp_le_u32_e32 vcc, v199, v232
	s_and_b64 vcc, s[70:71], vcc
; __device__ __forceinline__ void mask_tile(f32x16& s0, f32x16& s1, int key0, int klo, int khi, bool en, int hi) {
; #pragma unroll
;     for (int r = 0; r < 16; ++r) { const int k = key0 + crow(r, hi);
;         if (!(en && k >= klo && k <= khi)) s0[r] = NEG_INF;
;         if (!(en && k + 32 >= klo && k + 32 <= khi)) s1[r] = NEG_INF; }
; }
; __device__ __forceinline__ float half_swap_max(float m) { auto rr = __builtin_amdgcn_permlane32_swap(__float_as_uint(m), __float_as_uint(m), false, false); return fmaxf(__uint_as_float(rr[0]), __uint_as_float(rr[1])); }
; __device__ __forceinline__ float half_swap_sum(float m) { auto rr = __builtin_amdgcn_permlane32_swap(__float_as_uint(m), __float_as_uint(m), false, false); return __uint_as_float(rr[0]) + __uint_as_float(rr[1]); }
; __device__ __forceinline__ float tile_max(const f32x16& s0, const f32x16& s1) {
;     float m = fmaxf(s0[0], s1[0]);
; #pragma unroll
;     for (int r = 1; r < 16; ++r) m = fmaxf(m, fmaxf(s0[r], s1[r]));
;     return half_swap_max(m);
; }
; __device__ __forceinline__ void stats_step(const f32x16& s0, const f32x16& s1, float& m_run, float& l_run) {
;     const float mn = fmaxf(m_run, tile_max(s0, s1)); const float alpha = fast_exp2(m_run - mn); m_run = mn;
;     float sum = 0.f;
; #pragma unroll
;     for (int r = 0; r < 16; ++r) sum += fast_exp2(s0[r] - mn) + fast_exp2(s1[r] - mn);
;     l_run = l_run * alpha + sum;
; }
; __device__ __forceinline__ void softmax_step(f32x16& s0, f32x16& s1, float& m_run, float& l_run, f32x16& o0, f32x16& o1) {
;     const float mn = fmaxf(m_run, tile_max(s0, s1)); const float alpha = fast_exp2(m_run - mn); m_run = mn;
;     float sum = 0.f;
; #pragma unroll
;     for (int r = 0; r < 16; ++r) { s0[r] = fast_exp2(s0[r] - mn); s1[r] = fast_exp2(s1[r] - mn); sum += s0[r] + s1[r]; }
;     l_run = l_run * alpha + sum;
;     o0 = o0 * alpha; o1 = o1 * alpha;
; }
; __device__ __forceinline__ void f32_v_commit(const F32Half& T, LAS unsigned char* vb, int lane, float* vcopy, int skip, int h) {
;     const int pc = lane & 15, rl = lane >> 4;
;     LAS unsigned char* vd = vb + (pc >> 3) * 4096 + rl * 64 + (pc & 7) * 8; float* vc = vcopy + (size_t)rl * 256 + pc * 4;
; #pragma unroll
;     for (int i = 0; i < 8; ++i) { const int ri = 4 * (8 * h + i); u32x2 w; w.x = cvt_pk_bf16(T.x[i][0], T.x[i][1]); w.y = cvt_pk_bf16(T.x[i][2], T.x[i][3]);
	v_subrev_u32_e32 v199, 47, v198
	v_cndmask_b32_e32 v42, v219, v42, vcc
	v_cmp_le_u32_e32 vcc, v199, v232
	s_and_b64 vcc, s[70:71], vcc
	v_add_u32_e32 v199, -15, v198
	v_cndmask_b32_e32 v59, v219, v59, vcc
	v_cmp_le_u32_e32 vcc, v199, v232
	s_and_b64 vcc, s[70:71], vcc
	v_subrev_u32_e32 v199, 46, v198
	v_cndmask_b32_e32 v43, v219, v43, vcc
	v_cmp_le_u32_e32 vcc, v199, v232
	s_and_b64 vcc, s[70:71], vcc
	v_add_u32_e32 v199, -14, v198
	v_cndmask_b32_e32 v60, v219, v60, vcc
	v_cmp_le_u32_e32 vcc, v199, v232
	s_and_b64 vcc, s[70:71], vcc
	v_subrev_u32_e32 v199, 45, v198
	v_cndmask_b32_e32 v44, v219, v44, vcc
	v_cmp_le_u32_e32 vcc, v199, v232
	s_and_b64 vcc, s[70:71], vcc
	v_add_u32_e32 v199, -13, v198
	v_cndmask_b32_e32 v61, v219, v61, vcc
	v_cmp_le_u32_e32 vcc, v199, v232
	s_and_b64 vcc, s[70:71], vcc
	v_mov_b32_e32 v199, v1
	v_cndmask_b32_e32 v249, v219, v45, vcc
	v_subrev_u32_e32 v45, 40, v198
	v_cmp_le_u32_e32 vcc, v45, v232
	s_and_b64 vcc, s[70:71], vcc
	s_nop 0
	v_cndmask_b32_e32 v45, v219, v62, vcc
	v_add_u32_e32 v62, -8, v198
	v_cmp_le_u32_e32 vcc, v62, v232
	s_and_b64 vcc, s[70:71], vcc
	v_add_u32_e32 v62, -7, v198
	v_cndmask_b32_e32 v213, v219, v46, vcc
	v_subrev_u32_e32 v46, 39, v198
	v_cmp_le_u32_e32 vcc, v46, v232
	s_and_b64 vcc, s[70:71], vcc
	s_nop 0
	v_cndmask_b32_e32 v46, v219, v63, vcc
	v_cmp_le_u32_e32 vcc, v62, v232
	s_and_b64 vcc, s[70:71], vcc
	v_add_u32_e32 v62, -6, v198
	v_cndmask_b32_e32 v250, v219, v47, vcc
	v_subrev_u32_e32 v47, 38, v198
	v_cmp_le_u32_e32 vcc, v47, v232
	s_and_b64 vcc, s[70:71], vcc
	v_max_f32_e32 v63, v52, v52
	v_cndmask_b32_e32 v47, v219, v64, vcc
	v_cmp_le_u32_e32 vcc, v62, v232
	s_and_b64 vcc, s[70:71], vcc
	v_add_u32_e32 v62, -5, v198
	v_cndmask_b32_e32 v211, v219, v48, vcc
	v_subrev_u32_e32 v48, 37, v198
	v_cmp_le_u32_e32 vcc, v48, v232
	s_and_b64 vcc, s[70:71], vcc
	v_max_f32_e32 v64, v53, v53
	v_cndmask_b32_e32 v48, v219, v65, vcc
	v_cmp_le_u32_e32 vcc, v62, v232
	s_and_b64 vcc, s[70:71], vcc
	v_max_f32_e32 v62, v51, v51
	v_cndmask_b32_e32 v248, v219, v49, vcc
	v_max_f32_e32 v49, v35, v35
	v_max_f32_e32 v49, v62, v49
	v_max_f32_e32 v62, v36, v36
	v_max_f32_e32 v62, v63, v62
	v_max_f32_e32 v63, v37, v37
	v_max3_f32 v49, v50, v34, v49
	v_max_f32_e32 v63, v64, v63
	v_max3_f32 v49, v49, v62, v63
	v_max_f32_e32 v62, v38, v38
	v_max_f32_e32 v63, v54, v54
	v_max_f32_e32 v62, v63, v62
	v_max_f32_e32 v63, v39, v39
	v_max_f32_e32 v64, v55, v55
	v_max_f32_e32 v63, v64, v63
	v_max3_f32 v49, v49, v62, v63
	v_max_f32_e32 v62, v40, v40
	v_max_f32_e32 v63, v56, v56
	v_max_f32_e32 v62, v63, v62
	v_max_f32_e32 v63, v41, v41
	v_max_f32_e32 v64, v57, v57
	v_max_f32_e32 v63, v64, v63
	v_max3_f32 v49, v49, v62, v63
	v_max_f32_e32 v62, v42, v42
	v_max_f32_e32 v63, v58, v58
	v_max_f32_e32 v62, v63, v62
	v_max_f32_e32 v63, v43, v43
	v_max_f32_e32 v64, v59, v59
	v_max_f32_e32 v63, v64, v63
	v_max3_f32 v49, v49, v62, v63
	v_max_f32_e32 v62, v44, v44
	v_max_f32_e32 v63, v60, v60
	v_max_f32_e32 v62, v63, v62
	v_max_f32_e32 v63, v249, v249
	v_max_f32_e32 v64, v61, v61
	v_max_f32_e32 v63, v64, v63
	v_max3_f32 v49, v49, v62, v63
	v_max_f32_e32 v62, v213, v213
	v_max_f32_e32 v63, v45, v45
	v_max_f32_e32 v62, v63, v62
	v_max_f32_e32 v63, v250, v250
	v_max_f32_e32 v64, v46, v46
	v_max_f32_e32 v63, v64, v63
	v_max3_f32 v49, v49, v62, v63
	v_max_f32_e32 v62, v211, v211
	v_max_f32_e32 v63, v47, v47
	v_max_f32_e32 v62, v63, v62
	v_max_f32_e32 v63, v248, v248
	v_max_f32_e32 v64, v48, v48
	v_max_f32_e32 v63, v64, v63
	v_max3_f32 v49, v49, v62, v63
	v_mov_b32_e32 v62, v49
	s_nop 1
	v_permlane32_swap_b32_e32 v49, v62
	v_max3_f32 v247, v82, v49, v62
	v_sub_f32_e32 v34, v34, v247
	v_sub_f32_e32 v49, v50, v247
	v_exp_f32_e32 v251, v34
	v_sub_f32_e32 v34, v51, v247
	v_exp_f32_e32 v62, v49
	v_exp_f32_e32 v50, v34
	v_sub_f32_e32 v34, v35, v247
	v_exp_f32_e32 v198, v34
	v_add_f32_e32 v51, v62, v251
	v_pk_add_f32 v[34:35], v[50:51], v[198:199]
	s_nop 0
	v_pk_add_f32 v[200:201], v[34:35], v[34:35] op_sel_hi:[0,1]
	v_sub_f32_e32 v34, v52, v247
	v_exp_f32_e32 v51, v34
	v_sub_f32_e32 v34, v36, v247
	v_exp_f32_e32 v199, v34
	v_sub_f32_e32 v34, v53, v247
	v_exp_f32_e32 v52, v34
	v_sub_f32_e32 v34, v37, v247
	v_exp_f32_e32 v200, v34
	v_add_f32_e32 v53, v51, v199
	v_pk_add_f32 v[34:35], v[52:53], v[200:201]
	s_nop 0
	v_pk_add_f32 v[202:203], v[34:35], v[34:35] op_sel_hi:[0,1]
	v_sub_f32_e32 v34, v54, v247
	v_exp_f32_e32 v53, v34
	v_sub_f32_e32 v34, v38, v247
	v_exp_f32_e32 v201, v34
	v_sub_f32_e32 v34, v55, v247
	v_exp_f32_e32 v54, v34
	v_sub_f32_e32 v34, v39, v247
	v_exp_f32_e32 v202, v34
	v_add_f32_e32 v55, v53, v201
	v_pk_add_f32 v[34:35], v[54:55], v[202:203]
	s_nop 0
	v_pk_add_f32 v[206:207], v[34:35], v[34:35] op_sel_hi:[0,1]
	v_sub_f32_e32 v34, v56, v247
	v_exp_f32_e32 v55, v34
	v_sub_f32_e32 v34, v40, v247
	v_exp_f32_e32 v203, v34
	v_sub_f32_e32 v34, v57, v247
	v_exp_f32_e32 v56, v34
	v_sub_f32_e32 v34, v41, v247
	v_exp_f32_e32 v206, v34
	v_sub_f32_e32 v34, v58, v247
	v_exp_f32_e32 v215, v34
	v_sub_f32_e32 v34, v42, v247
	v_add_f32_e32 v57, v55, v203
	v_exp_f32_e32 v252, v34
	v_pk_add_f32 v[34:35], v[56:57], v[206:207]
	v_cvt_pk_bf16_f32 v58, v114, v115
	v_add_f32_e32 v217, v215, v252
	v_pk_add_f32 v[204:205], v[34:35], v[34:35] op_sel_hi:[0,1]
	v_sub_f32_e32 v34, v59, v247
	v_cvt_pk_bf16_f32 v59, v116, v117
	ds_write_b64 v246, v[58:59] offset:8192
	s_waitcnt vmcnt(14)
	v_cvt_pk_bf16_f32 v58, v110, v111
	v_cvt_pk_bf16_f32 v59, v112, v113
	ds_write_b64 v246, v[58:59] offset:8448
	s_waitcnt vmcnt(13)
	v_cvt_pk_bf16_f32 v58, v94, v95
	v_cvt_pk_bf16_f32 v59, v96, v97
	ds_write_b64 v246, v[58:59] offset:8704
	s_waitcnt vmcnt(12)
; #define LAS __attribute__((address_space(3)))
; __device__ __forceinline__ unsigned cvt_pk_bf16(float lo, float hi) { unsigned r; asm volatile("v_cvt_pk_bf16_f32 %0, %1, %2" : "=v"(r) : "v"(lo), "v"(hi)); return r; }
; __device__ __forceinline__ float fast_exp2(float x) { return __builtin_amdgcn_exp2f(x); }
; __device__ __forceinline__ void softmax_step(f32x16& s0, f32x16& s1, float& m_run, float& l_run, f32x16& o0, f32x16& o1) {
;     const float mn = fmaxf(m_run, tile_max(s0, s1)); const float alpha = fast_exp2(m_run - mn); m_run = mn;
;     float sum = 0.f;
; #pragma unroll
;     for (int r = 0; r < 16; ++r) { s0[r] = fast_exp2(s0[r] - mn); s1[r] = fast_exp2(s1[r] - mn); sum += s0[r] + s1[r]; }
;     l_run = l_run * alpha + sum;
;     o0 = o0 * alpha; o1 = o1 * alpha;
; }
; __device__ __forceinline__ bf16x8 pack8(const f32x16& p, int o) {
;     u32x4 w; w.x = cvt_pk_bf16(p[o], p[o + 1]); w.y = cvt_pk_bf16(p[o + 2], p[o + 3]); w.z = cvt_pk_bf16(p[o + 4], p[o + 5]); w.w = cvt_pk_bf16(p[o + 6], p[o + 7]);
;     return __builtin_bit_cast(bf16x8, w);
; }
; __device__ __forceinline__ void pv_tile(const LAS unsigned char* vb, const f32x16& p0, const f32x16& p1, f32x16& o0, f32x16& o1, int lane, int hi) {
;     const LAS unsigned char* vp = vb + ((lane >> 4) & 1) * 32 + (lane & 3) * 8 + (4 * hi + ((lane & 15) >> 2)) * 64;
; #pragma unroll
;     for (int kk = 0; kk < 4; ++kk) {
;         const bf16x8 pf = (kk < 2) ? pack8(p0, 8 * kk) : pack8(p1, 8 * (kk - 2));
;         const bf16x8 v0 = cat8(tr16(vp + kk * 1024), tr16(vp + kk * 1024 + 512));
;         const bf16x8 v1 = cat8(tr16(vp + 4096 + kk * 1024), tr16(vp + 4096 + kk * 1024 + 512));
;         o0 = MFMA32(v0, pf, o0); o1 = MFMA32(v1, pf, o1);
;     }
; }
; __device__ __forceinline__ void f32_v_commit(const F32Half& T, LAS unsigned char* vb, int lane, float* vcopy, int skip, int h) {
;     const int pc = lane & 15, rl = lane >> 4;
;     LAS unsigned char* vd = vb + (pc >> 3) * 4096 + rl * 64 + (pc & 7) * 8; float* vc = vcopy + (size_t)rl * 256 + pc * 4;
; #pragma unroll
;     for (int i = 0; i < 8; ++i) { const int ri = 4 * (8 * h + i); u32x2 w; w.x = cvt_pk_bf16(T.x[i][0], T.x[i][1]); w.y = cvt_pk_bf16(T.x[i][2], T.x[i][3]);
;         *(LAS u32x2*)(vd + ri * 64) = w;
;         if (vcopy && ri + rl >= skip) *(f32x4*)(vc + (size_t)ri * 256) = T.x[i]; }
; }
	v_cvt_pk_bf16_f32 v58, v106, v107
	v_cvt_pk_bf16_f32 v59, v108, v109
	ds_write_b64 v246, v[58:59] offset:8960
	s_waitcnt vmcnt(11)
	v_cvt_pk_bf16_f32 v58, v90, v91
	v_cvt_pk_bf16_f32 v59, v92, v93
	ds_write_b64 v246, v[58:59] offset:9216
	s_waitcnt vmcnt(10)
	v_cvt_pk_bf16_f32 v58, v102, v103
	v_cvt_pk_bf16_f32 v59, v104, v105
	ds_write_b64 v246, v[58:59] offset:9472
	s_waitcnt vmcnt(9)
	v_cvt_pk_bf16_f32 v58, v86, v87
	v_cvt_pk_bf16_f32 v59, v88, v89
	ds_write_b64 v246, v[58:59] offset:9728
	s_waitcnt vmcnt(8)
	v_cvt_pk_bf16_f32 v58, v98, v99
	v_cvt_pk_bf16_f32 v59, v100, v101
	ds_write_b64 v246, v[58:59] offset:9984
	s_waitcnt vmcnt(7)
	v_cvt_pk_bf16_f32 v58, v118, v119
	v_cvt_pk_bf16_f32 v59, v120, v121
	ds_write_b64 v246, v[58:59] offset:10240
	s_waitcnt vmcnt(6)
	v_cvt_pk_bf16_f32 v58, v142, v143
	v_cvt_pk_bf16_f32 v59, v144, v145
	ds_write_b64 v246, v[58:59] offset:10496
	s_waitcnt vmcnt(5)
	v_cvt_pk_bf16_f32 v58, v130, v131
	v_cvt_pk_bf16_f32 v59, v132, v133
	ds_write_b64 v246, v[58:59] offset:10752
	s_waitcnt vmcnt(4)
	v_cvt_pk_bf16_f32 v58, v138, v139
	v_cvt_pk_bf16_f32 v59, v140, v141
	v_exp_f32_e32 v216, v34
	v_sub_f32_e32 v34, v43, v247
	ds_write_b64 v246, v[58:59] offset:11008
	s_waitcnt vmcnt(3)
	v_cvt_pk_bf16_f32 v58, v126, v127
	v_cvt_pk_bf16_f32 v59, v128, v129
	v_exp_f32_e32 v204, v34
	v_sub_f32_e32 v34, v60, v247
	ds_write_b64 v246, v[58:59] offset:11264
	s_waitcnt vmcnt(2)
	v_cvt_pk_bf16_f32 v58, v134, v135
	v_cvt_pk_bf16_f32 v59, v136, v137
	v_exp_f32_e32 v207, v34
	v_sub_f32_e32 v34, v44, v247
	ds_write_b64 v246, v[58:59] offset:11520
	s_waitcnt vmcnt(1)
	v_cvt_pk_bf16_f32 v58, v122, v123
	v_cvt_pk_bf16_f32 v59, v124, v125
	v_exp_f32_e32 v253, v34
	v_sub_f32_e32 v34, v61, v247
	v_sub_f32_e32 v35, v82, v247
	ds_write_b64 v246, v[58:59] offset:11776
	s_waitcnt vmcnt(0)
	v_cvt_pk_bf16_f32 v58, v146, v147
	v_cvt_pk_bf16_f32 v59, v148, v149
	ds_write_b64 v246, v[58:59] offset:12032
	v_add_u32_e32 v106, v239, v238
	v_exp_f32_e32 v214, v34
	v_sub_f32_e32 v34, v45, v247
	v_exp_f32_e32 v208, v35
	s_waitcnt lgkmcnt(0)
	v_cvt_pk_bf16_f32 v86, v62, v50
	v_cvt_pk_bf16_f32 v87, v51, v52
	v_cvt_pk_bf16_f32 v88, v53, v54
	v_cvt_pk_bf16_f32 v89, v55, v56
	ds_read_b64_tr_b16 v[90:91], v106 offset:8192
	ds_read_b64_tr_b16 v[92:93], v106 offset:8704
	ds_read_b64_tr_b16 v[94:95], v106 offset:12288
	ds_read_b64_tr_b16 v[96:97], v106 offset:12800
	v_exp_f32_e32 v224, v34
	v_sub_f32_e32 v34, v46, v247
	v_exp_f32_e32 v212, v34
	v_sub_f32_e32 v34, v47, v247
	v_exp_f32_e32 v225, v34
	v_sub_f32_e32 v34, v48, v247
	v_exp_f32_e32 v210, v34
	v_pk_mul_f32 v[48:49], v[196:197], v[208:209] op_sel_hi:[1,0]
	v_pk_mul_f32 v[46:47], v[194:195], v[208:209] op_sel_hi:[1,0]
	v_pk_mul_f32 v[44:45], v[192:193], v[208:209] op_sel_hi:[1,0]
	v_pk_mul_f32 v[42:43], v[190:191], v[208:209] op_sel_hi:[1,0]
	v_pk_mul_f32 v[40:41], v[188:189], v[208:209] op_sel_hi:[1,0]
	v_pk_mul_f32 v[38:39], v[186:187], v[208:209] op_sel_hi:[1,0]
	v_pk_mul_f32 v[36:37], v[184:185], v[208:209] op_sel_hi:[1,0]
	v_pk_mul_f32 v[34:35], v[182:183], v[208:209] op_sel_hi:[1,0]
	v_pk_mul_f32 v[64:65], v[180:181], v[208:209] op_sel_hi:[1,0]
	v_pk_mul_f32 v[62:63], v[178:179], v[208:209] op_sel_hi:[1,0]
	v_pk_mul_f32 v[60:61], v[176:177], v[208:209] op_sel_hi:[1,0]
	v_pk_mul_f32 v[58:59], v[174:175], v[208:209] op_sel_hi:[1,0]
	v_pk_mul_f32 v[56:57], v[172:173], v[208:209] op_sel_hi:[1,0]
	v_pk_mul_f32 v[54:55], v[170:171], v[208:209] op_sel_hi:[1,0]
	v_pk_mul_f32 v[52:53], v[168:169], v[208:209] op_sel_hi:[1,0]
	v_pk_mul_f32 v[50:51], v[166:167], v[208:209] op_sel_hi:[1,0]
	s_waitcnt lgkmcnt(2)
	v_mfma_f32_32x32x16_bf16 v[34:49], v[90:93], v[86:89], v[34:49]
	v_cvt_pk_bf16_f32 v90, v215, v216
	v_cvt_pk_bf16_f32 v91, v207, v214
	v_cvt_pk_bf16_f32 v92, v224, v212
	v_cvt_pk_bf16_f32 v93, v225, v210
	ds_read_b64_tr_b16 v[98:99], v106 offset:9216
	ds_read_b64_tr_b16 v[100:101], v106 offset:9728
	v_add_f32_e32 v215, v207, v253
	s_waitcnt lgkmcnt(2)
	v_mfma_f32_32x32x16_bf16 v[50:65], v[94:97], v[86:89], v[50:65]
	v_add_f32_e64 v86, v216, v204
	v_add_f32_e64 v87, v217, v205
	v_add_f32_e64 v102, v86, v86
	v_add_f32_e64 v103, v86, v87
	v_sub_f32_e32 v86, v249, v247
	v_exp_f32_e32 v102, v86
	ds_read_b64_tr_b16 v[86:87], v106 offset:13312
	ds_read_b64_tr_b16 v[88:89], v106 offset:13824
	v_cvt_pk_bf16_f32 v94, v251, v198
	s_waitcnt lgkmcnt(2)
	v_mfma_f32_32x32x16_bf16 v[34:49], v[98:101], v[90:93], v[34:49]
	v_add_f32_e64 v104, v214, v102
	v_add_f32_e64 v105, v215, v103
	v_cvt_pk_bf16_f32 v95, v199, v200
	v_cvt_pk_bf16_f32 v96, v201, v202
	v_cvt_pk_bf16_f32 v97, v203, v206
	ds_read_b64_tr_b16 v[98:99], v106 offset:10240
	ds_read_b64_tr_b16 v[100:101], v106 offset:10752
	s_waitcnt lgkmcnt(2)
	v_mfma_f32_32x32x16_bf16 v[50:65], v[86:89], v[90:93], v[50:65]
	v_sub_f32_e32 v86, v213, v247
	v_add_f32_e64 v90, v104, v104
	v_add_f32_e64 v91, v104, v105
	v_exp_f32_e32 v103, v86
	v_sub_f32_e32 v86, v250, v247
	v_exp_f32_e32 v90, v86
	ds_read_b64_tr_b16 v[86:87], v106 offset:14336
	ds_read_b64_tr_b16 v[88:89], v106 offset:14848
	v_add_f32_e32 v213, v224, v103
	s_waitcnt lgkmcnt(2)
	v_mfma_f32_32x32x16_bf16 v[34:49], v[98:101], v[94:97], v[34:49]
	v_add_f32_e64 v92, v212, v90
	v_add_f32_e64 v93, v213, v91
	v_sub_f32_e32 v91, v211, v247
	v_add_f32_e64 v100, v92, v92
	v_add_f32_e64 v101, v92, v93
	v_exp_f32_e32 v104, v91
	v_sub_f32_e32 v91, v248, v247
	v_exp_f32_e32 v100, v91
	v_add_f32_e32 v211, v225, v104
	s_waitcnt lgkmcnt(0)
	v_mfma_f32_32x32x16_bf16 v[50:65], v[86:89], v[94:97], v[50:65]
	v_cvt_pk_bf16_f32 v88, v252, v204
	v_cvt_pk_bf16_f32 v89, v253, v102
	v_cvt_pk_bf16_f32 v90, v103, v90
	v_cvt_pk_bf16_f32 v91, v104, v100
	ds_read_b64_tr_b16 v[92:93], v106 offset:11264
	ds_read_b64_tr_b16 v[94:95], v106 offset:11776
	ds_read_b64_tr_b16 v[96:97], v106 offset:15360
	ds_read_b64_tr_b16 v[98:99], v106 offset:15872
	v_add_f32_e64 v86, v210, v100
	v_add_f32_e64 v87, v211, v101
	s_waitcnt lgkmcnt(2)
	v_mfma_f32_32x32x16_bf16 v[34:49], v[92:95], v[88:91], v[34:49]
	v_add_f32_e32 v86, v86, v87
	v_fmac_f32_e32 v86, v83, v208
	s_waitcnt lgkmcnt(0)
	v_mfma_f32_32x32x16_bf16 v[50:65], v[96:99], v[88:91], v[50:65]
; #define LAS __attribute__((address_space(3)))
; __device__ __forceinline__ int crow(int r, int hi) { return (r & 3) + 8 * (r >> 2) + 4 * hi; }
; #define LDS_WAIT() asm volatile("s_waitcnt lgkmcnt(0)" ::: "memory")
; #define MFMA32(a, b, c) __builtin_amdgcn_mfma_f32_32x32x16_bf16(a, b, c, 0, 0, 0)
; __device__ __forceinline__ void qk_tile(const LAS unsigned char* kb, const bf16x8 (&qr)[4], f32x16& s0, f32x16& s1, int r32, int hi) {
;     const LAS unsigned char* kp = kb + hi * 1024 + r32 * 16;
;     f32x16 a = F16Z, b = F16Z;
; #pragma unroll
;     for (int d0 = 0; d0 < 4; ++d0) {
;         const bf16x8 k0 = *(const LAS bf16x8*)(kp + d0 * 2048), k1 = *(const LAS bf16x8*)(kp + d0 * 2048 + 512);
;         a = MFMA32(k0, qr[d0], a); b = MFMA32(k1, qr[d0], b);
;     }
;     s0 = a; s1 = b;
; }
; __device__ __forceinline__ void mask_tile(f32x16& s0, f32x16& s1, int key0, int klo, int khi, bool en, int hi) {
; #pragma unroll
;     for (int r = 0; r < 16; ++r) { const int k = key0 + crow(r, hi);
;         if (!(en && k >= klo && k <= khi)) s0[r] = NEG_INF;
;         if (!(en && k + 32 >= klo && k + 32 <= khi)) s1[r] = NEG_INF; }
; }
; __device__ __forceinline__ void wave_tile_load(const bf16_t* kt, const bf16_t* vt, LAS unsigned char* kb, LAS unsigned char* vb, int lane) {
;     LDS_WAIT();
;     { u32x4 kr[8];
; #pragma unroll
;       for (int c = 0; c < 8; ++c) kr[c] = *(const u32x4*)((const unsigned char*)kt + lane * 128 + c * 16);
; #pragma unroll
;       for (int c = 0; c < 8; ++c) *(LAS u32x4*)(kb + c * 1024 + lane * 16) = kr[c]; }
;     __builtin_amdgcn_sched_barrier(0);
;     { u32x4 vr[8];
; #pragma unroll
;       for (int c = 0; c < 8; ++c) vr[c] = *(const u32x4*)((const unsigned char*)vt + (16 * (c & 3) + (lane >> 2)) * 128 + (c >> 2) * 64 + (lane & 3) * 16);
; #pragma unroll
;       for (int c = 0; c < 8; ++c) *(LAS u32x4*)(vb + c * 1024 + lane * 16) = vr[c]; }
;     LDS_WAIT();
; }
.LBB0_1383:
	s_and_b64 vcc, exec, s[4:5]
	s_cbranch_vccz .LBB0_1385
	s_waitcnt lgkmcnt(0)
	s_nop 5
	global_load_dwordx4 v[34:37], v[154:155], off nt
	global_load_dwordx4 v[38:41], v[154:155], off offset:16 nt
	global_load_dwordx4 v[42:45], v[154:155], off offset:32 nt
	global_load_dwordx4 v[46:49], v[154:155], off offset:48 nt
	global_load_dwordx4 v[50:53], v[154:155], off offset:64 nt
	global_load_dwordx4 v[54:57], v[154:155], off offset:80 nt
	global_load_dwordx4 v[58:61], v[154:155], off offset:96 nt
	global_load_dwordx4 v[62:65], v[154:155], off offset:112 nt
	s_waitcnt vmcnt(7)
	ds_write_b128 v230, v[34:37]
	s_waitcnt vmcnt(6)
	ds_write_b128 v230, v[38:41] offset:1024
	s_waitcnt vmcnt(5)
	ds_write_b128 v230, v[42:45] offset:2048
	s_waitcnt vmcnt(4)
	ds_write_b128 v230, v[46:49] offset:3072
	s_waitcnt vmcnt(3)
	ds_write_b128 v230, v[50:53] offset:4096
	s_waitcnt vmcnt(2)
	ds_write_b128 v230, v[54:57] offset:5120
	s_waitcnt vmcnt(1)
	ds_write_b128 v230, v[58:61] offset:6144
	s_waitcnt vmcnt(0)
	ds_write_b128 v230, v[62:65] offset:7168
	global_load_dwordx4 v[34:37], v[156:157], off nt
	global_load_dwordx4 v[38:41], v[156:157], off offset:2048 nt
	global_load_dwordx4 v[42:45], v[158:159], off nt
	global_load_dwordx4 v[46:49], v[160:161], off nt
	global_load_dwordx4 v[50:53], v[156:157], off offset:64 nt
	global_load_dwordx4 v[54:57], v[156:157], off offset:2112 nt
	global_load_dwordx4 v[58:61], v[158:159], off offset:64 nt
	global_load_dwordx4 v[62:65], v[160:161], off offset:64 nt
	v_add_u32_e32 v94, v233, v234
	v_readlane_b32 s4, v254, 29
	v_readlane_b32 s5, v254, 30
	s_and_b64 vcc, s[70:71], s[4:5]
	v_readlane_b32 s4, v254, 15
	v_readlane_b32 s5, v254, 16
	v_add_u32_e32 v128, v239, v238
	s_waitcnt vmcnt(7)
	ds_write_b128 v230, v[34:37] offset:8192
	s_waitcnt vmcnt(6)
	ds_write_b128 v230, v[38:41] offset:9216
	s_waitcnt vmcnt(5)
	ds_write_b128 v230, v[42:45] offset:10240
	s_waitcnt vmcnt(4)
	ds_write_b128 v230, v[46:49] offset:11264
	s_waitcnt vmcnt(3)
	ds_write_b128 v230, v[50:53] offset:12288
	s_waitcnt vmcnt(2)
	ds_write_b128 v230, v[54:57] offset:13312
	s_waitcnt vmcnt(1)
	ds_write_b128 v230, v[58:61] offset:14336
	s_waitcnt vmcnt(0)
	ds_write_b128 v230, v[62:65] offset:15360
	s_waitcnt lgkmcnt(0)
	ds_read_b128 v[34:37], v94
	ds_read_b128 v[38:41], v94 offset:512
	ds_read_b128 v[86:89], v94 offset:2048
	ds_read_b128 v[90:93], v94 offset:2560
	s_waitcnt lgkmcnt(3)
	v_mfma_f32_32x32x16_bf16 v[50:65], v[34:37], v[74:77], 0
	s_waitcnt lgkmcnt(2)
	v_mfma_f32_32x32x16_bf16 v[34:49], v[38:41], v[74:77], 0
	s_waitcnt lgkmcnt(1)
	v_mfma_f32_32x32x16_bf16 v[50:65], v[86:89], v[66:69], v[50:65]
	s_waitcnt lgkmcnt(0)
	v_mfma_f32_32x32x16_bf16 v[34:49], v[90:93], v[66:69], v[34:49]
	ds_read_b128 v[86:89], v94 offset:4096
	ds_read_b128 v[90:93], v94 offset:4608
	s_waitcnt lgkmcnt(1)
	v_mfma_f32_32x32x16_bf16 v[50:65], v[86:89], v[70:73], v[50:65]
	s_waitcnt lgkmcnt(0)
	v_mfma_f32_32x32x16_bf16 v[34:49], v[90:93], v[70:73], v[34:49]
	ds_read_b128 v[86:89], v94 offset:6144
	ds_read_b128 v[90:93], v94 offset:6656
	s_waitcnt lgkmcnt(1)
	v_mfma_f32_32x32x16_bf16 v[50:65], v[86:89], v[78:81], v[50:65]
	s_waitcnt lgkmcnt(0)
	v_mfma_f32_32x32x16_bf16 v[34:49], v[90:93], v[78:81], v[34:49]
	s_nop 9
	v_cndmask_b32_e32 v50, v219, v50, vcc
	s_and_b64 vcc, s[70:71], s[4:5]
	v_readlane_b32 s4, v254, 31
	v_readlane_b32 s5, v254, 32
	v_cndmask_b32_e32 v34, v219, v34, vcc
	s_and_b64 vcc, s[70:71], s[4:5]
	v_readlane_b32 s4, v254, 33
	v_readlane_b32 s5, v254, 34
	v_cndmask_b32_e32 v51, v219, v51, vcc
	s_and_b64 vcc, s[70:71], s[4:5]
	v_cndmask_b32_e32 v35, v219, v35, vcc
	s_and_b64 vcc, s[70:71], s[16:17]
	v_cndmask_b32_e32 v52, v219, v52, vcc
	s_and_b64 vcc, s[70:71], s[18:19]
	v_cndmask_b32_e32 v36, v219, v36, vcc
	s_and_b64 vcc, s[70:71], s[20:21]
	v_cndmask_b32_e32 v53, v219, v53, vcc
	s_and_b64 vcc, s[70:71], s[22:23]
	v_cndmask_b32_e32 v37, v219, v37, vcc
	s_and_b64 vcc, s[70:71], s[24:25]
	v_cndmask_b32_e32 v54, v219, v54, vcc
	s_and_b64 vcc, s[70:71], s[26:27]
	v_cndmask_b32_e32 v38, v219, v38, vcc
	s_and_b64 vcc, s[70:71], s[28:29]
	v_cndmask_b32_e32 v55, v219, v55, vcc
	s_and_b64 vcc, s[70:71], s[30:31]
	v_cndmask_b32_e32 v39, v219, v39, vcc
	s_and_b64 vcc, s[70:71], s[34:35]
	v_cndmask_b32_e32 v56, v219, v56, vcc
	s_and_b64 vcc, s[70:71], s[36:37]
	v_cndmask_b32_e32 v40, v219, v40, vcc
	s_and_b64 vcc, s[70:71], s[38:39]
	v_cndmask_b32_e32 v57, v219, v57, vcc
	s_and_b64 vcc, s[70:71], s[40:41]
	v_cndmask_b32_e32 v41, v219, v41, vcc
	s_and_b64 vcc, s[70:71], s[42:43]
	v_cndmask_b32_e32 v58, v219, v58, vcc
	s_and_b64 vcc, s[70:71], s[52:53]
	v_cndmask_b32_e32 v42, v219, v42, vcc
	s_and_b64 vcc, s[70:71], s[94:95]
	v_cndmask_b32_e32 v59, v219, v59, vcc
	s_and_b64 vcc, s[70:71], s[96:97]
	v_cndmask_b32_e32 v43, v219, v43, vcc
	s_and_b64 vcc, s[70:71], s[78:79]
	v_cndmask_b32_e32 v60, v219, v60, vcc
	s_and_b64 vcc, s[70:71], s[92:93]
	v_cndmask_b32_e32 v44, v219, v44, vcc
	s_and_b64 vcc, s[70:71], s[56:57]
	v_cndmask_b32_e32 v61, v219, v61, vcc
	s_and_b64 vcc, s[70:71], s[2:3]
	v_cndmask_b32_e32 v117, v219, v45, vcc
	s_and_b64 vcc, s[70:71], s[88:89]
	v_cndmask_b32_e32 v45, v219, v62, vcc
	s_and_b64 vcc, s[70:71], s[90:91]
	v_cndmask_b32_e32 v119, v219, v46, vcc
	s_and_b64 vcc, s[70:71], s[58:59]
	v_cndmask_b32_e32 v46, v219, v63, vcc
	s_and_b64 vcc, s[70:71], s[54:55]
	v_cndmask_b32_e32 v120, v219, v47, vcc
	s_and_b64 vcc, s[70:71], s[82:83]
	v_cndmask_b32_e32 v47, v219, v64, vcc
	s_and_b64 vcc, s[70:71], s[84:85]
	v_cndmask_b32_e32 v121, v219, v48, vcc
	s_and_b64 vcc, s[70:71], s[6:7]
	v_cndmask_b32_e32 v48, v219, v65, vcc
	s_and_b64 vcc, s[70:71], s[60:61]
; __device__ __forceinline__ float fast_exp2(float x) { return __builtin_amdgcn_exp2f(x); }
; __device__ __forceinline__ float half_swap_max(float m) { auto rr = __builtin_amdgcn_permlane32_swap(__float_as_uint(m), __float_as_uint(m), false, false); return fmaxf(__uint_as_float(rr[0]), __uint_as_float(rr[1])); }
; __device__ __forceinline__ float tile_max(const f32x16& s0, const f32x16& s1) {
;     float m = fmaxf(s0[0], s1[0]);
; #pragma unroll
;     for (int r = 1; r < 16; ++r) m = fmaxf(m, fmaxf(s0[r], s1[r]));
;     return half_swap_max(m);
; }
; __device__ __forceinline__ void stats_step(const f32x16& s0, const f32x16& s1, float& m_run, float& l_run) {
;     const float mn = fmaxf(m_run, tile_max(s0, s1)); const float alpha = fast_exp2(m_run - mn); m_run = mn;
;     float sum = 0.f;
; #pragma unroll
;     for (int r = 0; r < 16; ++r) sum += fast_exp2(s0[r] - mn) + fast_exp2(s1[r] - mn);
;     l_run = l_run * alpha + sum;
; }
; __device__ __forceinline__ void softmax_step(f32x16& s0, f32x16& s1, float& m_run, float& l_run, f32x16& o0, f32x16& o1) {
;     const float mn = fmaxf(m_run, tile_max(s0, s1)); const float alpha = fast_exp2(m_run - mn); m_run = mn;
;     float sum = 0.f;
; #pragma unroll
;     for (int r = 0; r < 16; ++r) { s0[r] = fast_exp2(s0[r] - mn); s1[r] = fast_exp2(s1[r] - mn); sum += s0[r] + s1[r]; }
;     l_run = l_run * alpha + sum;
;     o0 = o0 * alpha; o1 = o1 * alpha;
; }
	v_cndmask_b32_e32 v122, v219, v49, vcc
	v_max_f32_e32 v49, v35, v35
	v_max_f32_e32 v62, v51, v51
	v_max_f32_e32 v63, v36, v36
	v_max_f32_e32 v64, v52, v52
	v_max_f32_e32 v65, v37, v37
	v_max_f32_e32 v86, v53, v53
	v_max_f32_e32 v49, v62, v49
	v_max_f32_e32 v87, v38, v38
	v_max_f32_e32 v88, v54, v54
	v_max_f32_e32 v89, v39, v39
	v_max_f32_e32 v90, v55, v55
	v_max_f32_e32 v62, v64, v63
	v_max_f32_e32 v63, v86, v65
	v_max3_f32 v49, v50, v34, v49
	v_max_f32_e32 v91, v40, v40
	v_max_f32_e32 v92, v56, v56
	v_max_f32_e32 v93, v41, v41
	v_max_f32_e32 v94, v57, v57
	v_max_f32_e32 v64, v88, v87
	v_max_f32_e32 v65, v90, v89
	v_max3_f32 v49, v49, v62, v63
	v_max_f32_e32 v95, v42, v42
	v_max_f32_e32 v96, v58, v58
	v_max_f32_e32 v97, v43, v43
	v_max_f32_e32 v98, v59, v59
	v_max_f32_e32 v86, v92, v91
	v_max_f32_e32 v87, v94, v93
	v_max3_f32 v49, v49, v64, v65
	v_max_f32_e32 v99, v44, v44
	v_max_f32_e32 v88, v96, v95
	v_max_f32_e32 v89, v98, v97
	v_max3_f32 v49, v49, v86, v87
	v_max_f32_e32 v62, v60, v60
	v_max_f32_e32 v63, v117, v117
	v_max_f32_e32 v64, v61, v61
	v_max3_f32 v49, v49, v88, v89
	v_max_f32_e32 v62, v62, v99
	v_max_f32_e32 v63, v64, v63
	v_max3_f32 v49, v49, v62, v63
	v_max_f32_e32 v62, v119, v119
	v_max_f32_e32 v63, v45, v45
	v_max_f32_e32 v62, v63, v62
	v_max_f32_e32 v63, v120, v120
	v_max_f32_e32 v64, v46, v46
	v_max_f32_e32 v63, v64, v63
	v_max3_f32 v49, v49, v62, v63
	v_max_f32_e32 v62, v121, v121
	v_max_f32_e32 v63, v47, v47
	v_max_f32_e32 v62, v63, v62
	v_max_f32_e32 v63, v122, v122
	v_max_f32_e32 v64, v48, v48
	v_max_f32_e32 v63, v64, v63
	v_max3_f32 v49, v49, v62, v63
	v_mov_b32_e32 v62, v49
	s_nop 1
	v_permlane32_swap_b32_e32 v49, v62
	v_max3_f32 v247, v82, v49, v62
	v_sub_f32_e32 v34, v34, v247
	v_sub_f32_e32 v49, v50, v247
	v_exp_f32_e32 v123, v34
	v_sub_f32_e32 v34, v51, v247
	v_exp_f32_e32 v62, v49
	v_exp_f32_e32 v50, v34
	v_sub_f32_e32 v34, v35, v247
	v_exp_f32_e32 v86, v34
	v_add_f32_e32 v51, v62, v123
	v_mov_b32_e32 v87, v1
	v_cvt_pk_bf16_f32 v90, v62, v50
	v_pk_add_f32 v[34:35], v[50:51], v[86:87]
	s_nop 0
	v_pk_add_f32 v[88:89], v[34:35], v[34:35] op_sel_hi:[0,1]
	v_sub_f32_e32 v34, v52, v247
	v_exp_f32_e32 v51, v34
	v_sub_f32_e32 v34, v36, v247
	v_exp_f32_e32 v87, v34
	v_sub_f32_e32 v34, v53, v247
	v_exp_f32_e32 v52, v34
	v_sub_f32_e32 v34, v37, v247
	v_exp_f32_e32 v88, v34
	v_add_f32_e32 v53, v51, v87
	v_cvt_pk_bf16_f32 v91, v51, v52
	v_pk_add_f32 v[34:35], v[52:53], v[88:89]
	s_nop 0
	v_pk_add_f32 v[106:107], v[34:35], v[34:35] op_sel_hi:[0,1]
	v_sub_f32_e32 v34, v54, v247
	v_exp_f32_e32 v53, v34
	v_sub_f32_e32 v34, v38, v247
	v_exp_f32_e32 v89, v34
	v_sub_f32_e32 v34, v55, v247
	v_exp_f32_e32 v54, v34
	v_sub_f32_e32 v34, v39, v247
	v_exp_f32_e32 v106, v34
	v_add_f32_e32 v55, v53, v89
	v_cvt_pk_bf16_f32 v92, v53, v54
	v_pk_add_f32 v[34:35], v[54:55], v[106:107]
	s_nop 0
	v_pk_add_f32 v[108:109], v[34:35], v[34:35] op_sel_hi:[0,1]
	v_sub_f32_e32 v34, v56, v247
	v_exp_f32_e32 v55, v34
	v_sub_f32_e32 v34, v40, v247
	v_exp_f32_e32 v107, v34
	v_sub_f32_e32 v34, v57, v247
	v_exp_f32_e32 v56, v34
	v_sub_f32_e32 v34, v41, v247
	v_exp_f32_e32 v108, v34
	v_sub_f32_e32 v34, v58, v247
	v_exp_f32_e32 v102, v34
	v_sub_f32_e32 v34, v42, v247
	v_add_f32_e32 v57, v55, v107
	v_exp_f32_e32 v124, v34
	v_pk_add_f32 v[34:35], v[56:57], v[108:109]
	v_cvt_pk_bf16_f32 v93, v55, v56
	ds_read_b64_tr_b16 v[94:95], v128 offset:8192
	ds_read_b64_tr_b16 v[96:97], v128 offset:8704
	v_pk_add_f32 v[110:111], v[34:35], v[34:35] op_sel_hi:[0,1]
	v_sub_f32_e32 v34, v59, v247
	v_exp_f32_e32 v112, v34
	v_sub_f32_e32 v34, v43, v247
	v_exp_f32_e32 v110, v34
	v_sub_f32_e32 v34, v60, v247
	v_exp_f32_e32 v109, v34
	v_sub_f32_e32 v34, v44, v247
	v_exp_f32_e32 v125, v34
	v_sub_f32_e32 v34, v61, v247
	v_sub_f32_e32 v35, v82, v247
	v_exp_f32_e32 v114, v34
	v_sub_f32_e32 v34, v45, v247
	v_exp_f32_e32 v82, v35
	ds_read_b64_tr_b16 v[98:99], v128 offset:12288
	ds_read_b64_tr_b16 v[100:101], v128 offset:12800
	v_exp_f32_e32 v126, v34
	v_sub_f32_e32 v34, v46, v247
	v_exp_f32_e32 v116, v34
	v_sub_f32_e32 v34, v47, v247
	v_exp_f32_e32 v127, v34
	v_sub_f32_e32 v34, v48, v247
	v_exp_f32_e32 v118, v34
	v_pk_mul_f32 v[48:49], v[196:197], v[82:83] op_sel_hi:[1,0]
	v_pk_mul_f32 v[46:47], v[194:195], v[82:83] op_sel_hi:[1,0]
	v_pk_mul_f32 v[44:45], v[192:193], v[82:83] op_sel_hi:[1,0]
	v_pk_mul_f32 v[42:43], v[190:191], v[82:83] op_sel_hi:[1,0]
	v_pk_mul_f32 v[40:41], v[188:189], v[82:83] op_sel_hi:[1,0]
	v_pk_mul_f32 v[38:39], v[186:187], v[82:83] op_sel_hi:[1,0]
	v_pk_mul_f32 v[36:37], v[184:185], v[82:83] op_sel_hi:[1,0]
	v_pk_mul_f32 v[34:35], v[182:183], v[82:83] op_sel_hi:[1,0]
	v_pk_mul_f32 v[64:65], v[180:181], v[82:83] op_sel_hi:[1,0]
	v_pk_mul_f32 v[62:63], v[178:179], v[82:83] op_sel_hi:[1,0]
	v_pk_mul_f32 v[60:61], v[176:177], v[82:83] op_sel_hi:[1,0]
	v_pk_mul_f32 v[58:59], v[174:175], v[82:83] op_sel_hi:[1,0]
	v_pk_mul_f32 v[56:57], v[172:173], v[82:83] op_sel_hi:[1,0]
	v_pk_mul_f32 v[54:55], v[170:171], v[82:83] op_sel_hi:[1,0]
	v_pk_mul_f32 v[52:53], v[168:169], v[82:83] op_sel_hi:[1,0]
	v_pk_mul_f32 v[50:51], v[166:167], v[82:83] op_sel_hi:[1,0]
	v_add_f32_e32 v113, v102, v124
	s_waitcnt lgkmcnt(2)
; #define LAS __attribute__((address_space(3)))
; #define MFMA32(a, b, c) __builtin_amdgcn_mfma_f32_32x32x16_bf16(a, b, c, 0, 0, 0)
; __device__ __forceinline__ s16x4 tr16(const LAS unsigned char* p) { return __builtin_bit_cast(s16x4, __builtin_amdgcn_ds_read_tr16_b64_v4i16((LAS v4i16_t*)p)); }
; __device__ __forceinline__ bf16x8 cat8(s16x4 lo, s16x4 hi) { return (bf16x8){lo[0], lo[1], lo[2], lo[3], hi[0], hi[1], hi[2], hi[3]}; }
; __device__ __forceinline__ void pv_tile(const LAS unsigned char* vb, const f32x16& p0, const f32x16& p1, f32x16& o0, f32x16& o1, int lane, int hi) {
;     const LAS unsigned char* vp = vb + ((lane >> 4) & 1) * 32 + (lane & 3) * 8 + (4 * hi + ((lane & 15) >> 2)) * 64;
; #pragma unroll
;     for (int kk = 0; kk < 4; ++kk) {
;         const bf16x8 pf = (kk < 2) ? pack8(p0, 8 * kk) : pack8(p1, 8 * (kk - 2));
;         const bf16x8 v0 = cat8(tr16(vp + kk * 1024), tr16(vp + kk * 1024 + 512));
;         const bf16x8 v1 = cat8(tr16(vp + 4096 + kk * 1024), tr16(vp + 4096 + kk * 1024 + 512));
;         o0 = MFMA32(v0, pf, o0); o1 = MFMA32(v1, pf, o1);
;     }
; }
	v_mfma_f32_32x32x16_bf16 v[34:49], v[94:97], v[90:93], v[34:49]
	v_cvt_pk_bf16_f32 v94, v102, v112
	v_cvt_pk_bf16_f32 v95, v109, v114
	v_cvt_pk_bf16_f32 v96, v126, v116
	v_cvt_pk_bf16_f32 v97, v127, v118
	ds_read_b64_tr_b16 v[102:103], v128 offset:9216
	ds_read_b64_tr_b16 v[104:105], v128 offset:9728
	v_add_f32_e32 v115, v109, v125
	s_waitcnt lgkmcnt(2)
	v_mfma_f32_32x32x16_bf16 v[50:65], v[98:101], v[90:93], v[50:65]
	v_add_f32_e64 v90, v112, v110
	v_add_f32_e64 v91, v113, v111
	v_add_f32_e64 v112, v90, v90
	v_add_f32_e64 v113, v90, v91
	v_sub_f32_e32 v90, v117, v247
	v_exp_f32_e32 v112, v90
	ds_read_b64_tr_b16 v[90:91], v128 offset:13312
	ds_read_b64_tr_b16 v[92:93], v128 offset:13824
	v_cvt_pk_bf16_f32 v86, v123, v86
	s_waitcnt lgkmcnt(2)
	v_mfma_f32_32x32x16_bf16 v[34:49], v[102:105], v[94:97], v[34:49]
	v_add_f32_e64 v102, v114, v112
	v_add_f32_e64 v103, v115, v113
	v_cvt_pk_bf16_f32 v87, v87, v88
	v_cvt_pk_bf16_f32 v88, v89, v106
	v_cvt_pk_bf16_f32 v89, v107, v108
	ds_read_b64_tr_b16 v[98:99], v128 offset:10240
	ds_read_b64_tr_b16 v[100:101], v128 offset:10752
	s_waitcnt lgkmcnt(2)
	v_mfma_f32_32x32x16_bf16 v[50:65], v[90:93], v[94:97], v[50:65]
	v_sub_f32_e32 v90, v119, v247
	v_add_f32_e64 v94, v102, v102
	v_add_f32_e64 v95, v102, v103
	v_exp_f32_e32 v102, v90
	v_sub_f32_e32 v90, v120, v247
	v_exp_f32_e32 v94, v90
	ds_read_b64_tr_b16 v[90:91], v128 offset:14336
	ds_read_b64_tr_b16 v[92:93], v128 offset:14848
	v_add_f32_e32 v117, v126, v102
	s_waitcnt lgkmcnt(2)
	v_mfma_f32_32x32x16_bf16 v[34:49], v[98:101], v[86:89], v[34:49]
	v_add_f32_e64 v96, v116, v94
	v_add_f32_e64 v97, v117, v95
	v_sub_f32_e32 v95, v121, v247
	v_add_f32_e64 v100, v96, v96
	v_add_f32_e64 v101, v96, v97
	v_exp_f32_e32 v103, v95
	v_sub_f32_e32 v95, v122, v247
	v_exp_f32_e32 v100, v95
	v_add_f32_e32 v119, v127, v103
	s_waitcnt lgkmcnt(0)
	v_mfma_f32_32x32x16_bf16 v[50:65], v[90:93], v[86:89], v[50:65]
	v_cvt_pk_bf16_f32 v88, v124, v110
	v_cvt_pk_bf16_f32 v89, v125, v112
	v_cvt_pk_bf16_f32 v90, v102, v94
	v_cvt_pk_bf16_f32 v91, v103, v100
	ds_read_b64_tr_b16 v[92:93], v128 offset:11264
	ds_read_b64_tr_b16 v[94:95], v128 offset:11776
	ds_read_b64_tr_b16 v[96:97], v128 offset:15360
	ds_read_b64_tr_b16 v[98:99], v128 offset:15872
	v_add_f32_e64 v86, v118, v100
	v_add_f32_e64 v87, v119, v101
	s_waitcnt lgkmcnt(2)
	v_mfma_f32_32x32x16_bf16 v[34:49], v[92:95], v[88:91], v[34:49]
	v_add_f32_e32 v86, v86, v87
	v_fmac_f32_e32 v86, v83, v82
	s_waitcnt lgkmcnt(0)
	v_mfma_f32_32x32x16_bf16 v[50:65], v[96:99], v[88:91], v[50:65]
